# previous + s_barrier issued before s_setprio 0 at the end of each MFMA block
# speedup vs baseline: 1.0021x; 1.0021x over previous
.LBB0_197:
	s_ashr_i32 s47, s46, 31
	ds_read_b128 v[18:21], v190
	ds_read_b128 v[22:25], v190 offset:1024
	ds_read_b128 v[26:29], v190 offset:2048
	ds_read_b128 v[30:33], v190 offset:3072
	ds_read_b128 v[2:5], v190 offset:16384
	ds_read_b128 v[6:9], v190 offset:17408
	ds_read_b128 v[10:13], v190 offset:18432
	ds_read_b128 v[14:17], v190 offset:19456
	s_lshl_b64 s[8:9], s[46:47], 20
	s_add_u32 s48, s22, s8
	s_addc_u32 s49, s23, s9
	s_and_b64 s[8:9], s[2:3], exec
	s_cselect_b32 s47, s49, s73
	s_cselect_b32 s70, s48, s72
	s_ashr_i32 s45, s44, 31
	s_lshl_b64 s[8:9], s[44:45], 20
	s_add_u32 s50, s27, s8
	s_addc_u32 s51, s68, s9
	s_and_b64 s[8:9], s[2:3], exec
	s_cselect_b32 s45, s51, s55
	s_cselect_b32 s71, s50, s54
	s_add_u32 s8, s72, 0x80080
	s_addc_u32 s9, s73, 0
	s_mov_b32 m0, s92
	v_lshl_add_u64 v[216:217], s[8:9], 0, v[164:165]
	ds_read_b128 v[180:183], v191
	ds_read_b128 v[184:187], v191 offset:1024
	ds_read_b128 v[192:195], v191 offset:2048
	ds_read_b128 v[196:199], v191 offset:3072
	ds_read_b128 v[200:203], v191 offset:4096
	ds_read_b128 v[204:207], v191 offset:5120
	ds_read_b128 v[208:211], v191 offset:6144
	ds_read_b128 v[212:215], v191 offset:7168
	global_load_lds_dwordx4 v[216:217], off
	v_lshl_add_u64 v[216:217], s[8:9], 0, v[168:169]
	s_mov_b32 m0, s93
	s_nop 0
	global_load_lds_dwordx4 v[216:217], off
	s_waitcnt vmcnt(8)
	s_waitcnt lgkmcnt(0)
	s_setprio 1
	s_barrier
	v_mfma_f32_16x16x128_f8f6f4 v[158:161], v[18:25], v[180:187], 0
	v_mfma_f32_16x16x128_f8f6f4 v[154:157], v[26:33], v[180:187], 0
	v_mfma_f32_16x16x128_f8f6f4 v[146:149], v[26:33], v[192:199], 0
	v_mfma_f32_16x16x128_f8f6f4 v[150:153], v[18:25], v[192:199], 0
	v_mfma_f32_16x16x128_f8f6f4 v[142:145], v[18:25], v[200:207], 0
	v_mfma_f32_16x16x128_f8f6f4 v[138:141], v[26:33], v[200:207], 0
	v_mfma_f32_16x16x128_f8f6f4 v[130:133], v[26:33], v[208:215], 0
	v_mfma_f32_16x16x128_f8f6f4 v[134:137], v[18:25], v[208:215], 0
	s_setprio 0
	s_setprio 1
	v_mfma_f32_16x16x128_f8f6f4 v[102:105], v[2:9], v[208:215], 0
	v_mfma_f32_16x16x128_f8f6f4 v[98:101], v[10:17], v[208:215], 0
	v_mfma_f32_16x16x128_f8f6f4 v[106:109], v[10:17], v[200:207], 0
	v_mfma_f32_16x16x128_f8f6f4 v[110:113], v[2:9], v[200:207], 0
	v_mfma_f32_16x16x128_f8f6f4 v[118:121], v[2:9], v[192:199], 0
	v_mfma_f32_16x16x128_f8f6f4 v[114:117], v[10:17], v[192:199], 0
	v_mfma_f32_16x16x128_f8f6f4 v[122:125], v[10:17], v[180:187], 0
	v_mfma_f32_16x16x128_f8f6f4 v[126:129], v[2:9], v[180:187], 0
	s_barrier
	s_setprio 0
	v_lshl_add_u64 v[180:181], s[54:55], 0, v[166:167]
	s_mov_b32 m0, s77
	v_lshl_add_u64 v[182:183], v[180:181], 0, s[16:17]
	ds_read_b128 v[192:195], v191 offset:16384
	ds_read_b128 v[196:199], v191 offset:17408
	ds_read_b128 v[200:203], v191 offset:18432
	ds_read_b128 v[204:207], v191 offset:19456
	ds_read_b128 v[208:211], v191 offset:20480
	ds_read_b128 v[212:215], v191 offset:21504
	ds_read_b128 v[216:219], v191 offset:22528
	ds_read_b128 v[220:223], v191 offset:23552
	global_load_lds_dwordx4 v[182:183], off
	v_lshl_add_u64 v[182:183], s[54:55], 0, v[170:171]
	s_add_u32 s8, s54, 0x80100
	v_lshl_add_u64 v[184:185], v[182:183], 0, s[16:17]
	s_mov_b32 m0, s78
	s_addc_u32 s9, s55, 0
	global_load_lds_dwordx4 v[184:185], off
	v_lshl_add_u64 v[184:185], s[8:9], 0, v[166:167]
	s_mov_b32 m0, s79
	s_nop 0
	global_load_lds_dwordx4 v[184:185], off
	v_lshl_add_u64 v[184:185], s[8:9], 0, v[170:171]
	s_mov_b32 m0, s80
	s_nop 0
	global_load_lds_dwordx4 v[184:185], off
	v_lshl_add_u64 v[184:185], s[72:73], 0, v[164:165]
	v_lshl_add_u64 v[186:187], v[184:185], 0, s[16:17]
	s_mov_b32 m0, s53
	s_nop 0
	global_load_lds_dwordx4 v[186:187], off
	v_lshl_add_u64 v[186:187], s[72:73], 0, v[168:169]
	v_lshl_add_u64 v[224:225], v[186:187], 0, s[16:17]
	s_mov_b32 m0, s81
	s_nop 0
	global_load_lds_dwordx4 v[224:225], off
	s_waitcnt vmcnt(8)
	s_waitcnt lgkmcnt(0)
	s_setprio 1
	s_barrier
	v_mfma_f32_16x16x128_f8f6f4 v[94:97], v[18:25], v[192:199], 0
	v_mfma_f32_16x16x128_f8f6f4 v[90:93], v[26:33], v[192:199], 0
	v_mfma_f32_16x16x128_f8f6f4 v[82:85], v[26:33], v[200:207], 0
	v_mfma_f32_16x16x128_f8f6f4 v[86:89], v[18:25], v[200:207], 0
	v_mfma_f32_16x16x128_f8f6f4 v[78:81], v[18:25], v[208:215], 0
	v_mfma_f32_16x16x128_f8f6f4 v[74:77], v[26:33], v[208:215], 0
	v_mfma_f32_16x16x128_f8f6f4 v[66:69], v[26:33], v[216:223], 0
	v_mfma_f32_16x16x128_f8f6f4 v[70:73], v[18:25], v[216:223], 0
	s_setprio 0
	s_setprio 1
	v_mfma_f32_16x16x128_f8f6f4 v[38:41], v[2:9], v[216:223], 0
	v_mfma_f32_16x16x128_f8f6f4 v[34:37], v[10:17], v[216:223], 0
	v_mfma_f32_16x16x128_f8f6f4 v[42:45], v[10:17], v[208:215], 0
	v_mfma_f32_16x16x128_f8f6f4 v[46:49], v[2:9], v[208:215], 0
	v_mfma_f32_16x16x128_f8f6f4 v[54:57], v[2:9], v[200:207], 0
	v_mfma_f32_16x16x128_f8f6f4 v[50:53], v[10:17], v[200:207], 0
	v_mfma_f32_16x16x128_f8f6f4 v[58:61], v[10:17], v[192:199], 0
	v_mfma_f32_16x16x128_f8f6f4 v[62:65], v[2:9], v[192:199], 0
	s_barrier
	s_setprio 0
	ds_read_b128 v[18:21], v190 offset:32768
	ds_read_b128 v[22:25], v190 offset:33792
	ds_read_b128 v[26:29], v190 offset:34816
	ds_read_b128 v[30:33], v190 offset:35840
	ds_read_b128 v[2:5], v190 offset:49152
	ds_read_b128 v[6:9], v190 offset:50176
	ds_read_b128 v[10:13], v190 offset:51200
	ds_read_b128 v[14:17], v190 offset:52224
	s_add_u32 s8, s72, 0x80100
	s_addc_u32 s9, s73, 0
	s_mov_b32 m0, s82
	v_lshl_add_u64 v[224:225], s[8:9], 0, v[164:165]
	ds_read_b128 v[192:195], v191 offset:32768
	ds_read_b128 v[196:199], v191 offset:33792
	ds_read_b128 v[200:203], v191 offset:34816
	ds_read_b128 v[204:207], v191 offset:35840
	ds_read_b128 v[208:211], v191 offset:36864
	ds_read_b128 v[212:215], v191 offset:37888
	ds_read_b128 v[216:219], v191 offset:38912
	ds_read_b128 v[220:223], v191 offset:39936
	global_load_lds_dwordx4 v[224:225], off
	v_lshl_add_u64 v[224:225], s[8:9], 0, v[168:169]
	s_mov_b32 m0, s83
	s_nop 0
	global_load_lds_dwordx4 v[224:225], off
	s_waitcnt vmcnt(8)
	s_waitcnt lgkmcnt(0)
	s_setprio 1
	s_barrier
	v_mfma_f32_16x16x128_f8f6f4 v[158:161], v[18:25], v[192:199], v[158:161]
	v_mfma_f32_16x16x128_f8f6f4 v[154:157], v[26:33], v[192:199], v[154:157]
	v_mfma_f32_16x16x128_f8f6f4 v[146:149], v[26:33], v[200:207], v[146:149]
	v_mfma_f32_16x16x128_f8f6f4 v[150:153], v[18:25], v[200:207], v[150:153]
	v_mfma_f32_16x16x128_f8f6f4 v[142:145], v[18:25], v[208:215], v[142:145]
	v_mfma_f32_16x16x128_f8f6f4 v[138:141], v[26:33], v[208:215], v[138:141]
	v_mfma_f32_16x16x128_f8f6f4 v[130:133], v[26:33], v[216:223], v[130:133]
	v_mfma_f32_16x16x128_f8f6f4 v[134:137], v[18:25], v[216:223], v[134:137]
	s_setprio 0
	s_setprio 1
	v_mfma_f32_16x16x128_f8f6f4 v[102:105], v[2:9], v[216:223], v[102:105]
	v_mfma_f32_16x16x128_f8f6f4 v[98:101], v[10:17], v[216:223], v[98:101]
	v_mfma_f32_16x16x128_f8f6f4 v[106:109], v[10:17], v[208:215], v[106:109]
	v_mfma_f32_16x16x128_f8f6f4 v[110:113], v[2:9], v[208:215], v[110:113]
	v_mfma_f32_16x16x128_f8f6f4 v[118:121], v[2:9], v[200:207], v[118:121]
	v_mfma_f32_16x16x128_f8f6f4 v[114:117], v[10:17], v[200:207], v[114:117]
	v_mfma_f32_16x16x128_f8f6f4 v[122:125], v[10:17], v[192:199], v[122:125]
	v_mfma_f32_16x16x128_f8f6f4 v[126:129], v[2:9], v[192:199], v[126:129]
	s_barrier
	s_setprio 0
	s_mov_b32 m0, s86
	v_lshl_add_u64 v[180:181], v[180:181], 0, s[20:21]
	s_add_u32 s8, s54, 0x80180
	ds_read_b128 v[192:195], v191 offset:49152
	ds_read_b128 v[196:199], v191 offset:50176
	ds_read_b128 v[200:203], v191 offset:51200
	ds_read_b128 v[204:207], v191 offset:52224
	ds_read_b128 v[208:211], v191 offset:53248
	ds_read_b128 v[212:215], v191 offset:54272
	ds_read_b128 v[216:219], v191 offset:55296
	ds_read_b128 v[220:223], v191 offset:56320
	global_load_lds_dwordx4 v[180:181], off
	v_lshl_add_u64 v[180:181], v[182:183], 0, s[20:21]
	s_mov_b32 m0, s87
	s_addc_u32 s9, s55, 0
	global_load_lds_dwordx4 v[180:181], off
	v_lshl_add_u64 v[180:181], s[8:9], 0, v[166:167]
	s_mov_b32 m0, s90
	s_nop 0
	global_load_lds_dwordx4 v[180:181], off
	v_lshl_add_u64 v[180:181], s[8:9], 0, v[170:171]
	s_mov_b32 m0, s91
	s_nop 0
	global_load_lds_dwordx4 v[180:181], off
	v_lshl_add_u64 v[180:181], v[184:185], 0, s[20:21]
	s_mov_b32 m0, s88
	s_nop 0
	global_load_lds_dwordx4 v[180:181], off
	v_lshl_add_u64 v[180:181], v[186:187], 0, s[20:21]
	s_mov_b32 m0, s89
	s_nop 0
	global_load_lds_dwordx4 v[180:181], off
	s_waitcnt vmcnt(8)
	s_waitcnt lgkmcnt(0)
	s_setprio 1
	s_barrier
	v_mfma_f32_16x16x128_f8f6f4 v[94:97], v[18:25], v[192:199], v[94:97]
	v_mfma_f32_16x16x128_f8f6f4 v[90:93], v[26:33], v[192:199], v[90:93]
	v_mfma_f32_16x16x128_f8f6f4 v[82:85], v[26:33], v[200:207], v[82:85]
	v_mfma_f32_16x16x128_f8f6f4 v[86:89], v[18:25], v[200:207], v[86:89]
	v_mfma_f32_16x16x128_f8f6f4 v[78:81], v[18:25], v[208:215], v[78:81]
	v_mfma_f32_16x16x128_f8f6f4 v[74:77], v[26:33], v[208:215], v[74:77]
	v_mfma_f32_16x16x128_f8f6f4 v[66:69], v[26:33], v[216:223], v[66:69]
	v_mfma_f32_16x16x128_f8f6f4 v[70:73], v[18:25], v[216:223], v[70:73]
	s_setprio 0
	s_setprio 1
	v_mfma_f32_16x16x128_f8f6f4 v[38:41], v[2:9], v[216:223], v[38:41]
	v_mfma_f32_16x16x128_f8f6f4 v[34:37], v[10:17], v[216:223], v[34:37]
	v_mfma_f32_16x16x128_f8f6f4 v[42:45], v[10:17], v[208:215], v[42:45]
	v_mfma_f32_16x16x128_f8f6f4 v[46:49], v[2:9], v[208:215], v[46:49]
	v_mfma_f32_16x16x128_f8f6f4 v[54:57], v[2:9], v[200:207], v[54:57]
	v_mfma_f32_16x16x128_f8f6f4 v[50:53], v[10:17], v[200:207], v[50:53]
	v_mfma_f32_16x16x128_f8f6f4 v[58:61], v[10:17], v[192:199], v[58:61]
	v_mfma_f32_16x16x128_f8f6f4 v[62:65], v[2:9], v[192:199], v[62:65]
	s_barrier
	s_setprio 0
	s_add_u32 s72, s72, 0x80180
	s_addc_u32 s73, s73, 0
	s_add_u32 s8, s54, 0x200
	s_addc_u32 s9, s55, 0
	s_mov_b32 s62, 0
.LBB0_198:
	ds_read_b128 v[2:5], v190
	ds_read_b128 v[6:9], v190 offset:1024
	ds_read_b128 v[18:21], v190 offset:2048
	ds_read_b128 v[22:25], v190 offset:3072
	ds_read_b128 v[26:29], v190 offset:16384
	ds_read_b128 v[30:33], v190 offset:17408
	ds_read_b128 v[180:183], v190 offset:18432
	ds_read_b128 v[184:187], v190 offset:19456
	s_add_u32 s54, s72, 0xfff80080
	s_addc_u32 s55, s73, -1
	s_cmp_eq_u32 s62, 28
	s_cselect_b32 s75, s47, s55
	s_cselect_b32 s74, s70, s54
	s_cselect_b32 s55, s45, s9
	s_cselect_b32 s54, s71, s8
	s_mov_b32 m0, s92
	v_lshl_add_u64 v[216:217], s[72:73], 0, v[172:173]
	ds_read_b128 v[10:13], v191
	ds_read_b128 v[14:17], v191 offset:1024
	ds_read_b128 v[192:195], v191 offset:2048
	ds_read_b128 v[196:199], v191 offset:3072
	ds_read_b128 v[200:203], v191 offset:4096
	ds_read_b128 v[204:207], v191 offset:5120
	ds_read_b128 v[208:211], v191 offset:6144
	ds_read_b128 v[212:215], v191 offset:7168
	global_load_lds_dwordx4 v[216:217], off
	v_lshl_add_u64 v[216:217], s[72:73], 0, v[174:175]
	s_mov_b32 m0, s93
	s_nop 0
	global_load_lds_dwordx4 v[216:217], off
	s_waitcnt vmcnt(8)
	s_waitcnt lgkmcnt(0)
	s_setprio 1
	s_barrier
	v_mfma_f32_16x16x128_f8f6f4 v[158:161], v[2:9], v[10:17], v[158:161]
	v_mfma_f32_16x16x128_f8f6f4 v[154:157], v[18:25], v[10:17], v[154:157]
	v_mfma_f32_16x16x128_f8f6f4 v[146:149], v[18:25], v[192:199], v[146:149]
	v_mfma_f32_16x16x128_f8f6f4 v[150:153], v[2:9], v[192:199], v[150:153]
	v_mfma_f32_16x16x128_f8f6f4 v[142:145], v[2:9], v[200:207], v[142:145]
	v_mfma_f32_16x16x128_f8f6f4 v[138:141], v[18:25], v[200:207], v[138:141]
	v_mfma_f32_16x16x128_f8f6f4 v[130:133], v[18:25], v[208:215], v[130:133]
	v_mfma_f32_16x16x128_f8f6f4 v[134:137], v[2:9], v[208:215], v[134:137]
	s_setprio 0
	s_setprio 1
	v_mfma_f32_16x16x128_f8f6f4 v[102:105], v[26:33], v[208:215], v[102:105]
	v_mfma_f32_16x16x128_f8f6f4 v[98:101], v[180:187], v[208:215], v[98:101]
	v_mfma_f32_16x16x128_f8f6f4 v[106:109], v[180:187], v[200:207], v[106:109]
	v_mfma_f32_16x16x128_f8f6f4 v[110:113], v[26:33], v[200:207], v[110:113]
	v_mfma_f32_16x16x128_f8f6f4 v[118:121], v[26:33], v[192:199], v[118:121]
	v_mfma_f32_16x16x128_f8f6f4 v[114:117], v[180:187], v[192:199], v[114:117]
	v_mfma_f32_16x16x128_f8f6f4 v[122:125], v[180:187], v[10:17], v[122:125]
	v_mfma_f32_16x16x128_f8f6f4 v[126:129], v[26:33], v[10:17], v[126:129]
	s_barrier
	s_setprio 0
	s_mov_b32 m0, s77
	v_lshl_add_u64 v[10:11], s[54:55], 0, v[166:167]
	s_add_u32 vcc_lo, s54, 0x80000
	ds_read_b128 v[192:195], v191 offset:16384
	ds_read_b128 v[196:199], v191 offset:17408
	ds_read_b128 v[200:203], v191 offset:18432
	ds_read_b128 v[204:207], v191 offset:19456
	ds_read_b128 v[208:211], v191 offset:20480
	ds_read_b128 v[212:215], v191 offset:21504
	ds_read_b128 v[216:219], v191 offset:22528
	ds_read_b128 v[220:223], v191 offset:23552
	global_load_lds_dwordx4 v[10:11], off
	v_lshl_add_u64 v[12:13], s[54:55], 0, v[170:171]
	s_mov_b32 m0, s78
	s_addc_u32 vcc_hi, s55, 0
	global_load_lds_dwordx4 v[12:13], off
	v_lshl_add_u64 v[14:15], vcc, 0, v[166:167]
	s_mov_b32 m0, s79
	v_lshl_add_u64 v[16:17], s[74:75], 0, v[168:169]
	global_load_lds_dwordx4 v[14:15], off
	v_lshl_add_u64 v[14:15], vcc, 0, v[170:171]
	s_mov_b32 m0, s80
	s_nop 0
	global_load_lds_dwordx4 v[14:15], off
	v_lshl_add_u64 v[14:15], s[74:75], 0, v[164:165]
	s_mov_b32 m0, s53
	s_nop 0
	global_load_lds_dwordx4 v[14:15], off
	s_mov_b32 m0, s81
	s_nop 0
	global_load_lds_dwordx4 v[16:17], off
	s_waitcnt vmcnt(8)
	s_waitcnt lgkmcnt(0)
	s_setprio 1
	s_barrier
	v_mfma_f32_16x16x128_f8f6f4 v[94:97], v[2:9], v[192:199], v[94:97]
	v_mfma_f32_16x16x128_f8f6f4 v[90:93], v[18:25], v[192:199], v[90:93]
	v_mfma_f32_16x16x128_f8f6f4 v[82:85], v[18:25], v[200:207], v[82:85]
	v_mfma_f32_16x16x128_f8f6f4 v[86:89], v[2:9], v[200:207], v[86:89]
	v_mfma_f32_16x16x128_f8f6f4 v[78:81], v[2:9], v[208:215], v[78:81]
	v_mfma_f32_16x16x128_f8f6f4 v[74:77], v[18:25], v[208:215], v[74:77]
	v_mfma_f32_16x16x128_f8f6f4 v[66:69], v[18:25], v[216:223], v[66:69]
	v_mfma_f32_16x16x128_f8f6f4 v[70:73], v[2:9], v[216:223], v[70:73]
	s_setprio 0
	s_setprio 1
	v_mfma_f32_16x16x128_f8f6f4 v[38:41], v[26:33], v[216:223], v[38:41]
	v_mfma_f32_16x16x128_f8f6f4 v[34:37], v[180:187], v[216:223], v[34:37]
	v_mfma_f32_16x16x128_f8f6f4 v[42:45], v[180:187], v[208:215], v[42:45]
	v_mfma_f32_16x16x128_f8f6f4 v[46:49], v[26:33], v[208:215], v[46:49]
	v_mfma_f32_16x16x128_f8f6f4 v[54:57], v[26:33], v[200:207], v[54:57]
	v_mfma_f32_16x16x128_f8f6f4 v[50:53], v[180:187], v[200:207], v[50:53]
	v_mfma_f32_16x16x128_f8f6f4 v[58:61], v[180:187], v[192:199], v[58:61]
	v_mfma_f32_16x16x128_f8f6f4 v[62:65], v[26:33], v[192:199], v[62:65]
	s_barrier
	s_setprio 0
	ds_read_b128 v[18:21], v190 offset:32768
	ds_read_b128 v[22:25], v190 offset:33792
	ds_read_b128 v[26:29], v190 offset:34816
	ds_read_b128 v[30:33], v190 offset:35840
	ds_read_b128 v[2:5], v190 offset:49152
	ds_read_b128 v[6:9], v190 offset:50176
	ds_read_b128 v[180:183], v190 offset:51200
	ds_read_b128 v[184:187], v190 offset:52224
	s_add_u32 s74, s74, 0x80000
	s_addc_u32 s75, s75, 0
	s_mov_b32 m0, s82
	v_lshl_add_u64 v[224:225], s[74:75], 0, v[164:165]
	ds_read_b128 v[192:195], v191 offset:32768
	ds_read_b128 v[196:199], v191 offset:33792
	ds_read_b128 v[200:203], v191 offset:34816
	ds_read_b128 v[204:207], v191 offset:35840
	ds_read_b128 v[208:211], v191 offset:36864
	ds_read_b128 v[212:215], v191 offset:37888
	ds_read_b128 v[216:219], v191 offset:38912
	ds_read_b128 v[220:223], v191 offset:39936
	global_load_lds_dwordx4 v[224:225], off
	v_lshl_add_u64 v[224:225], s[74:75], 0, v[168:169]
	s_mov_b32 m0, s83
	s_nop 0
	global_load_lds_dwordx4 v[224:225], off
	s_waitcnt vmcnt(8)
	s_waitcnt lgkmcnt(0)
	s_setprio 1
	s_barrier
	v_mfma_f32_16x16x128_f8f6f4 v[158:161], v[18:25], v[192:199], v[158:161]
	v_mfma_f32_16x16x128_f8f6f4 v[154:157], v[26:33], v[192:199], v[154:157]
	v_mfma_f32_16x16x128_f8f6f4 v[146:149], v[26:33], v[200:207], v[146:149]
	v_mfma_f32_16x16x128_f8f6f4 v[150:153], v[18:25], v[200:207], v[150:153]
	v_mfma_f32_16x16x128_f8f6f4 v[142:145], v[18:25], v[208:215], v[142:145]
	v_mfma_f32_16x16x128_f8f6f4 v[138:141], v[26:33], v[208:215], v[138:141]
	v_mfma_f32_16x16x128_f8f6f4 v[130:133], v[26:33], v[216:223], v[130:133]
	v_mfma_f32_16x16x128_f8f6f4 v[134:137], v[18:25], v[216:223], v[134:137]
	s_setprio 0
	s_setprio 1
	v_mfma_f32_16x16x128_f8f6f4 v[102:105], v[2:9], v[216:223], v[102:105]
	v_mfma_f32_16x16x128_f8f6f4 v[98:101], v[180:187], v[216:223], v[98:101]
	v_mfma_f32_16x16x128_f8f6f4 v[106:109], v[180:187], v[208:215], v[106:109]
	v_mfma_f32_16x16x128_f8f6f4 v[110:113], v[2:9], v[208:215], v[110:113]
	v_mfma_f32_16x16x128_f8f6f4 v[118:121], v[2:9], v[200:207], v[118:121]
	v_mfma_f32_16x16x128_f8f6f4 v[114:117], v[180:187], v[200:207], v[114:117]
	v_mfma_f32_16x16x128_f8f6f4 v[122:125], v[180:187], v[192:199], v[122:125]
	v_mfma_f32_16x16x128_f8f6f4 v[126:129], v[2:9], v[192:199], v[126:129]
	s_barrier
	s_setprio 0
	s_mov_b32 m0, s86
	v_lshl_add_u64 v[10:11], v[10:11], 0, s[4:5]
	s_add_u32 s54, s54, 0x80080
	ds_read_b128 v[192:195], v191 offset:49152
	ds_read_b128 v[196:199], v191 offset:50176
	ds_read_b128 v[200:203], v191 offset:51200
	ds_read_b128 v[204:207], v191 offset:52224
	ds_read_b128 v[208:211], v191 offset:53248
	ds_read_b128 v[212:215], v191 offset:54272
	ds_read_b128 v[216:219], v191 offset:55296
	ds_read_b128 v[220:223], v191 offset:56320
	global_load_lds_dwordx4 v[10:11], off
	v_lshl_add_u64 v[10:11], v[12:13], 0, s[4:5]
	s_mov_b32 m0, s87
	s_addc_u32 s55, s55, 0
	global_load_lds_dwordx4 v[10:11], off
	v_lshl_add_u64 v[10:11], s[54:55], 0, v[166:167]
	s_mov_b32 m0, s90
	s_nop 0
	global_load_lds_dwordx4 v[10:11], off
	v_lshl_add_u64 v[10:11], s[54:55], 0, v[170:171]
	s_mov_b32 m0, s91
	s_nop 0
	global_load_lds_dwordx4 v[10:11], off
	v_lshl_add_u64 v[10:11], v[14:15], 0, s[4:5]
	s_mov_b32 m0, s88
	s_nop 0
	global_load_lds_dwordx4 v[10:11], off
	v_lshl_add_u64 v[10:11], v[16:17], 0, s[4:5]
	s_mov_b32 m0, s89
	s_nop 0
	global_load_lds_dwordx4 v[10:11], off
	s_waitcnt vmcnt(8)
	s_waitcnt lgkmcnt(0)
	s_setprio 1
	s_barrier
	v_mfma_f32_16x16x128_f8f6f4 v[94:97], v[18:25], v[192:199], v[94:97]
	v_mfma_f32_16x16x128_f8f6f4 v[90:93], v[26:33], v[192:199], v[90:93]
	v_mfma_f32_16x16x128_f8f6f4 v[82:85], v[26:33], v[200:207], v[82:85]
	v_mfma_f32_16x16x128_f8f6f4 v[86:89], v[18:25], v[200:207], v[86:89]
	v_mfma_f32_16x16x128_f8f6f4 v[78:81], v[18:25], v[208:215], v[78:81]
	v_mfma_f32_16x16x128_f8f6f4 v[74:77], v[26:33], v[208:215], v[74:77]
	v_mfma_f32_16x16x128_f8f6f4 v[66:69], v[26:33], v[216:223], v[66:69]
	v_mfma_f32_16x16x128_f8f6f4 v[70:73], v[18:25], v[216:223], v[70:73]
	s_setprio 0
	s_setprio 1
	v_mfma_f32_16x16x128_f8f6f4 v[38:41], v[2:9], v[216:223], v[38:41]
	v_mfma_f32_16x16x128_f8f6f4 v[34:37], v[180:187], v[216:223], v[34:37]
	v_mfma_f32_16x16x128_f8f6f4 v[42:45], v[180:187], v[208:215], v[42:45]
	v_mfma_f32_16x16x128_f8f6f4 v[46:49], v[2:9], v[208:215], v[46:49]
	v_mfma_f32_16x16x128_f8f6f4 v[54:57], v[2:9], v[200:207], v[54:57]
	v_mfma_f32_16x16x128_f8f6f4 v[50:53], v[180:187], v[200:207], v[50:53]
	v_mfma_f32_16x16x128_f8f6f4 v[58:61], v[180:187], v[192:199], v[58:61]
	v_mfma_f32_16x16x128_f8f6f4 v[62:65], v[2:9], v[192:199], v[62:65]
	s_barrier
	s_setprio 0
	s_add_i32 s62, s62, 2
	s_add_u32 s72, s72, 0x100
	s_addc_u32 s73, s73, 0
	s_add_u32 s8, s8, 0x100
	s_addc_u32 s9, s9, 0
	s_cmp_gt_u32 s62, 29
	s_cbranch_scc0 .LBB0_198
	s_and_b64 vcc, exec, s[6:7]
	s_cbranch_vccz .LBB0_201
	s_barrier

.LBB0_282:
	ds_read_b128 v[2:5], v187
	ds_read_b128 v[6:9], v187 offset:1024
	ds_read_b128 v[174:177], v187 offset:2048
	ds_read_b128 v[178:181], v187 offset:3072
	ds_read_b128 v[190:193], v187 offset:16384
	ds_read_b128 v[194:197], v187 offset:17408
	ds_read_b128 v[198:201], v187 offset:18432
	ds_read_b128 v[202:205], v187 offset:19456
	s_add_u32 s49, s52, 0x100
	s_addc_u32 s71, s53, 0
	s_and_b64 s[62:63], s[54:55], exec
	s_cselect_b32 s73, s1, s71
	s_cselect_b32 s72, s0, s49
	s_add_u32 s49, s50, 0x100
	s_addc_u32 s62, s51, 0
	s_and_b64 s[54:55], s[54:55], exec
	s_cselect_b32 s55, s5, s62
	s_cselect_b32 s54, s4, s49
	s_add_u32 s62, s52, 0x158080
	s_addc_u32 s63, s53, 0
	s_add_i32 s49, s33, 0xc000
	v_lshl_add_u64 v[182:183], s[62:63], 0, v[154:155]
	s_mov_b32 m0, s49
	s_add_i32 s71, s33, 0xe000
	ds_read_b128 v[206:209], v188
	ds_read_b128 v[210:213], v188 offset:1024
	ds_read_b128 v[214:217], v188 offset:2048
	ds_read_b128 v[218:221], v188 offset:3072
	ds_read_b128 v[222:225], v188 offset:4096
	ds_read_b128 v[226:229], v188 offset:5120
	ds_read_b128 v[230:233], v188 offset:6144
	ds_read_b128 v[234:237], v188 offset:7168
	global_load_lds_dwordx4 v[182:183], off
	v_lshl_add_u64 v[182:183], s[62:63], 0, v[158:159]
	s_mov_b32 m0, s71
	s_nop 0
	global_load_lds_dwordx4 v[182:183], off
	s_waitcnt vmcnt(8)
	s_waitcnt lgkmcnt(0)
	s_setprio 1
	s_barrier
	v_mfma_f32_16x16x128_f8f6f4 v[134:137], v[2:9], v[206:213], 0
	v_mfma_f32_16x16x128_f8f6f4 v[130:133], v[174:181], v[206:213], 0
	v_mfma_f32_16x16x128_f8f6f4 v[122:125], v[174:181], v[214:221], 0
	v_mfma_f32_16x16x128_f8f6f4 v[126:129], v[2:9], v[214:221], 0
	v_mfma_f32_16x16x128_f8f6f4 v[118:121], v[2:9], v[222:229], 0
	v_mfma_f32_16x16x128_f8f6f4 v[114:117], v[174:181], v[222:229], 0
	v_mfma_f32_16x16x128_f8f6f4 v[106:109], v[174:181], v[230:237], 0
	v_mfma_f32_16x16x128_f8f6f4 v[110:113], v[2:9], v[230:237], 0
	s_setprio 0
	s_setprio 1
	v_mfma_f32_16x16x128_f8f6f4 v[78:81], v[190:197], v[230:237], 0
	v_mfma_f32_16x16x128_f8f6f4 v[74:77], v[198:205], v[230:237], 0
	v_mfma_f32_16x16x128_f8f6f4 v[82:85], v[198:205], v[222:229], 0
	v_mfma_f32_16x16x128_f8f6f4 v[86:89], v[190:197], v[222:229], 0
	v_mfma_f32_16x16x128_f8f6f4 v[94:97], v[190:197], v[214:221], 0
	v_mfma_f32_16x16x128_f8f6f4 v[90:93], v[198:205], v[214:221], 0
	v_mfma_f32_16x16x128_f8f6f4 v[98:101], v[198:205], v[206:213], 0
	v_mfma_f32_16x16x128_f8f6f4 v[102:105], v[190:197], v[206:213], 0
	s_barrier
	s_setprio 0
	s_mov_b32 m0, s47
	v_lshl_add_u64 v[182:183], s[54:55], 0, v[156:157]
	s_add_u32 s62, s54, 0x158000
	ds_read_b128 v[206:209], v188 offset:16384
	ds_read_b128 v[210:213], v188 offset:17408
	ds_read_b128 v[214:217], v188 offset:18432
	ds_read_b128 v[218:221], v188 offset:19456
	ds_read_b128 v[222:225], v188 offset:20480
	ds_read_b128 v[226:229], v188 offset:21504
	ds_read_b128 v[230:233], v188 offset:22528
	ds_read_b128 v[234:237], v188 offset:23552
	global_load_lds_dwordx4 v[182:183], off
	v_lshl_add_u64 v[238:239], s[54:55], 0, v[160:161]
	s_mov_b32 m0, s68
	s_addc_u32 s63, s55, 0
	global_load_lds_dwordx4 v[238:239], off
	v_lshl_add_u64 v[242:243], s[62:63], 0, v[156:157]
	s_mov_b32 m0, s69
	v_lshl_add_u64 v[244:245], s[72:73], 0, v[158:159]
	global_load_lds_dwordx4 v[242:243], off
	v_lshl_add_u64 v[242:243], s[62:63], 0, v[160:161]
	s_mov_b32 m0, s74
	s_nop 0
	global_load_lds_dwordx4 v[242:243], off
	v_lshl_add_u64 v[242:243], s[72:73], 0, v[154:155]
	s_mov_b32 m0, s33
	s_nop 0
	global_load_lds_dwordx4 v[242:243], off
	s_mov_b32 m0, s75
	s_nop 0
	global_load_lds_dwordx4 v[244:245], off
	s_waitcnt vmcnt(8)
	s_waitcnt lgkmcnt(0)
	s_setprio 1
	s_barrier
	v_mfma_f32_16x16x128_f8f6f4 v[70:73], v[2:9], v[206:213], 0
	v_mfma_f32_16x16x128_f8f6f4 v[66:69], v[174:181], v[206:213], 0
	v_mfma_f32_16x16x128_f8f6f4 v[58:61], v[174:181], v[214:221], 0
	v_mfma_f32_16x16x128_f8f6f4 v[62:65], v[2:9], v[214:221], 0
	v_mfma_f32_16x16x128_f8f6f4 v[54:57], v[2:9], v[222:229], 0
	v_mfma_f32_16x16x128_f8f6f4 v[50:53], v[174:181], v[222:229], 0
	v_mfma_f32_16x16x128_f8f6f4 v[42:45], v[174:181], v[230:237], 0
	v_mfma_f32_16x16x128_f8f6f4 v[46:49], v[2:9], v[230:237], 0
	s_setprio 0
	s_setprio 1
	v_mfma_f32_16x16x128_f8f6f4 v[14:17], v[190:197], v[230:237], 0
	v_mfma_f32_16x16x128_f8f6f4 v[10:13], v[198:205], v[230:237], 0
	v_mfma_f32_16x16x128_f8f6f4 v[18:21], v[198:205], v[222:229], 0
	v_mfma_f32_16x16x128_f8f6f4 v[22:25], v[190:197], v[222:229], 0
	v_mfma_f32_16x16x128_f8f6f4 v[30:33], v[190:197], v[214:221], 0
	v_mfma_f32_16x16x128_f8f6f4 v[26:29], v[198:205], v[214:221], 0
	v_mfma_f32_16x16x128_f8f6f4 v[34:37], v[198:205], v[206:213], 0
	v_mfma_f32_16x16x128_f8f6f4 v[38:41], v[190:197], v[206:213], 0
	s_barrier
	s_setprio 0
	ds_read_b128 v[2:5], v187 offset:32768
	ds_read_b128 v[6:9], v187 offset:33792
	ds_read_b128 v[174:177], v187 offset:34816
	ds_read_b128 v[178:181], v187 offset:35840
	ds_read_b128 v[190:193], v187 offset:49152
	ds_read_b128 v[194:197], v187 offset:50176
	ds_read_b128 v[198:201], v187 offset:51200
	ds_read_b128 v[202:205], v187 offset:52224
	s_add_u32 s62, s72, 0x158000
	s_addc_u32 s63, s73, 0
	s_mov_b32 m0, s76
	v_lshl_add_u64 v[246:247], s[62:63], 0, v[154:155]
	ds_read_b128 v[206:209], v188 offset:32768
	ds_read_b128 v[210:213], v188 offset:33792
	ds_read_b128 v[214:217], v188 offset:34816
	ds_read_b128 v[218:221], v188 offset:35840
	ds_read_b128 v[222:225], v188 offset:36864
	ds_read_b128 v[226:229], v188 offset:37888
	ds_read_b128 v[230:233], v188 offset:38912
	ds_read_b128 v[234:237], v188 offset:39936
	global_load_lds_dwordx4 v[246:247], off
	v_lshl_add_u64 v[246:247], s[62:63], 0, v[158:159]
	s_mov_b32 m0, s77
	s_nop 0
	global_load_lds_dwordx4 v[246:247], off
	s_waitcnt vmcnt(8)
	s_waitcnt lgkmcnt(0)
	s_setprio 1
	s_barrier
	v_mfma_f32_16x16x128_f8f6f4 v[134:137], v[2:9], v[206:213], v[134:137]
	v_mfma_f32_16x16x128_f8f6f4 v[130:133], v[174:181], v[206:213], v[130:133]
	v_mfma_f32_16x16x128_f8f6f4 v[122:125], v[174:181], v[214:221], v[122:125]
	v_mfma_f32_16x16x128_f8f6f4 v[126:129], v[2:9], v[214:221], v[126:129]
	v_mfma_f32_16x16x128_f8f6f4 v[118:121], v[2:9], v[222:229], v[118:121]
	v_mfma_f32_16x16x128_f8f6f4 v[114:117], v[174:181], v[222:229], v[114:117]
	v_mfma_f32_16x16x128_f8f6f4 v[106:109], v[174:181], v[230:237], v[106:109]
	v_mfma_f32_16x16x128_f8f6f4 v[110:113], v[2:9], v[230:237], v[110:113]
	s_setprio 0
	s_setprio 1
	v_mfma_f32_16x16x128_f8f6f4 v[78:81], v[190:197], v[230:237], v[78:81]
	v_mfma_f32_16x16x128_f8f6f4 v[74:77], v[198:205], v[230:237], v[74:77]
	v_mfma_f32_16x16x128_f8f6f4 v[82:85], v[198:205], v[222:229], v[82:85]
	v_mfma_f32_16x16x128_f8f6f4 v[86:89], v[190:197], v[222:229], v[86:89]
	v_mfma_f32_16x16x128_f8f6f4 v[94:97], v[190:197], v[214:221], v[94:97]
	v_mfma_f32_16x16x128_f8f6f4 v[90:93], v[198:205], v[214:221], v[90:93]
	v_mfma_f32_16x16x128_f8f6f4 v[98:101], v[198:205], v[206:213], v[98:101]
	v_mfma_f32_16x16x128_f8f6f4 v[102:105], v[190:197], v[206:213], v[102:105]
	s_barrier
	s_setprio 0
	s_mov_b32 m0, s83
	v_lshl_add_u64 v[182:183], v[182:183], 0, s[26:27]
	s_add_u32 s54, s54, 0x158080
	ds_read_b128 v[206:209], v188 offset:49152
	ds_read_b128 v[210:213], v188 offset:50176
	ds_read_b128 v[214:217], v188 offset:51200
	ds_read_b128 v[218:221], v188 offset:52224
	ds_read_b128 v[222:225], v188 offset:53248
	ds_read_b128 v[226:229], v188 offset:54272
	ds_read_b128 v[230:233], v188 offset:55296
	ds_read_b128 v[234:237], v188 offset:56320
	global_load_lds_dwordx4 v[182:183], off
	v_lshl_add_u64 v[182:183], v[238:239], 0, s[26:27]
	s_mov_b32 m0, s84
	s_addc_u32 s55, s55, 0
	global_load_lds_dwordx4 v[182:183], off
	v_lshl_add_u64 v[182:183], s[54:55], 0, v[156:157]
	s_mov_b32 m0, s87
	s_nop 0
	global_load_lds_dwordx4 v[182:183], off
	v_lshl_add_u64 v[182:183], s[54:55], 0, v[160:161]
	s_mov_b32 m0, s88
	s_nop 0
	global_load_lds_dwordx4 v[182:183], off
	v_lshl_add_u64 v[182:183], v[242:243], 0, s[26:27]
	s_mov_b32 m0, s85
	s_nop 0
	global_load_lds_dwordx4 v[182:183], off
	v_lshl_add_u64 v[182:183], v[244:245], 0, s[26:27]
	s_mov_b32 m0, s86
	s_nop 0
	global_load_lds_dwordx4 v[182:183], off
	s_waitcnt vmcnt(8)
	s_waitcnt lgkmcnt(0)
	s_setprio 1
	s_barrier
	v_mfma_f32_16x16x128_f8f6f4 v[70:73], v[2:9], v[206:213], v[70:73]
	v_mfma_f32_16x16x128_f8f6f4 v[66:69], v[174:181], v[206:213], v[66:69]
	v_mfma_f32_16x16x128_f8f6f4 v[58:61], v[174:181], v[214:221], v[58:61]
	v_mfma_f32_16x16x128_f8f6f4 v[62:65], v[2:9], v[214:221], v[62:65]
	v_mfma_f32_16x16x128_f8f6f4 v[54:57], v[2:9], v[222:229], v[54:57]
	v_mfma_f32_16x16x128_f8f6f4 v[50:53], v[174:181], v[222:229], v[50:53]
	v_mfma_f32_16x16x128_f8f6f4 v[42:45], v[174:181], v[230:237], v[42:45]
	v_mfma_f32_16x16x128_f8f6f4 v[46:49], v[2:9], v[230:237], v[46:49]
	s_setprio 0
	s_setprio 1
	v_mfma_f32_16x16x128_f8f6f4 v[14:17], v[190:197], v[230:237], v[14:17]
	v_mfma_f32_16x16x128_f8f6f4 v[10:13], v[198:205], v[230:237], v[10:13]
	v_mfma_f32_16x16x128_f8f6f4 v[18:21], v[198:205], v[222:229], v[18:21]
	v_mfma_f32_16x16x128_f8f6f4 v[22:25], v[190:197], v[222:229], v[22:25]
	v_mfma_f32_16x16x128_f8f6f4 v[30:33], v[190:197], v[214:221], v[30:33]
	v_mfma_f32_16x16x128_f8f6f4 v[26:29], v[198:205], v[214:221], v[26:29]
	v_mfma_f32_16x16x128_f8f6f4 v[34:37], v[198:205], v[206:213], v[34:37]
	v_mfma_f32_16x16x128_f8f6f4 v[38:41], v[190:197], v[206:213], v[38:41]
	s_barrier
	s_setprio 0
	s_cmp_lt_u32 s95, 3
	s_cbranch_scc1 .LBB0_287
	s_add_u32 s54, s79, s9
	s_addc_u32 s55, s80, s8
	s_add_u32 s52, s52, 0x158180
	s_addc_u32 s53, s53, 0
	s_add_u32 s8, s50, 0x200
	v_lshl_add_u64 v[174:175], v[172:173], 2, s[54:55]
	s_addc_u32 s9, s51, 0
	s_mov_b32 s72, 4
	s_cmp_eq_u32 s95, s72
	s_cselect_b64 s[50:51], -1, 0
	s_cmp_lg_u32 s95, s72
	s_cbranch_scc1 .LBB0_285

.LBB0_285:
	ds_read_b128 v[2:5], v187
	ds_read_b128 v[6:9], v187 offset:1024
	ds_read_b128 v[190:193], v187 offset:2048
	ds_read_b128 v[194:197], v187 offset:3072
	ds_read_b128 v[198:201], v187 offset:16384
	ds_read_b128 v[202:205], v187 offset:17408
	ds_read_b128 v[206:209], v187 offset:18432
	ds_read_b128 v[210:213], v187 offset:19456
	s_add_u32 s54, s52, 0xffea8080
	s_addc_u32 s55, s53, -1
	s_and_b64 s[50:51], s[50:51], exec
	s_cselect_b32 s50, s4, s8
	s_cselect_b32 s55, s1, s55
	s_cselect_b32 s54, s0, s54
	s_cselect_b32 s51, s5, s9
	s_mov_b32 m0, s49
	v_lshl_add_u64 v[238:239], s[52:53], 0, v[162:163]
	ds_read_b128 v[176:179], v188
	ds_read_b128 v[180:183], v188 offset:1024
	ds_read_b128 v[214:217], v188 offset:2048
	ds_read_b128 v[218:221], v188 offset:3072
	ds_read_b128 v[222:225], v188 offset:4096
	ds_read_b128 v[226:229], v188 offset:5120
	ds_read_b128 v[230:233], v188 offset:6144
	ds_read_b128 v[234:237], v188 offset:7168
	global_load_lds_dwordx4 v[238:239], off
	v_lshl_add_u64 v[238:239], s[52:53], 0, v[164:165]
	s_mov_b32 m0, s71
	s_nop 0
	global_load_lds_dwordx4 v[238:239], off
	s_waitcnt vmcnt(8)
	s_waitcnt lgkmcnt(0)
	s_setprio 1
	s_barrier
	v_mfma_f32_16x16x128_f8f6f4 v[134:137], v[2:9], v[176:183], v[134:137]
	v_mfma_f32_16x16x128_f8f6f4 v[130:133], v[190:197], v[176:183], v[130:133]
	v_mfma_f32_16x16x128_f8f6f4 v[122:125], v[190:197], v[214:221], v[122:125]
	v_mfma_f32_16x16x128_f8f6f4 v[126:129], v[2:9], v[214:221], v[126:129]
	v_mfma_f32_16x16x128_f8f6f4 v[118:121], v[2:9], v[222:229], v[118:121]
	v_mfma_f32_16x16x128_f8f6f4 v[114:117], v[190:197], v[222:229], v[114:117]
	v_mfma_f32_16x16x128_f8f6f4 v[106:109], v[190:197], v[230:237], v[106:109]
	v_mfma_f32_16x16x128_f8f6f4 v[110:113], v[2:9], v[230:237], v[110:113]
	s_setprio 0
	s_setprio 1
	v_mfma_f32_16x16x128_f8f6f4 v[78:81], v[198:205], v[230:237], v[78:81]
	v_mfma_f32_16x16x128_f8f6f4 v[74:77], v[206:213], v[230:237], v[74:77]
	v_mfma_f32_16x16x128_f8f6f4 v[82:85], v[206:213], v[222:229], v[82:85]
	v_mfma_f32_16x16x128_f8f6f4 v[86:89], v[198:205], v[222:229], v[86:89]
	v_mfma_f32_16x16x128_f8f6f4 v[94:97], v[198:205], v[214:221], v[94:97]
	v_mfma_f32_16x16x128_f8f6f4 v[90:93], v[206:213], v[214:221], v[90:93]
	v_mfma_f32_16x16x128_f8f6f4 v[98:101], v[206:213], v[176:183], v[98:101]
	v_mfma_f32_16x16x128_f8f6f4 v[102:105], v[198:205], v[176:183], v[102:105]
	s_barrier
	s_setprio 0
	s_mov_b32 m0, s47
	v_lshl_add_u64 v[176:177], s[50:51], 0, v[156:157]
	s_add_u32 s62, s50, 0x158000
	ds_read_b128 v[214:217], v188 offset:16384
	ds_read_b128 v[218:221], v188 offset:17408
	ds_read_b128 v[222:225], v188 offset:18432
	ds_read_b128 v[226:229], v188 offset:19456
	ds_read_b128 v[230:233], v188 offset:20480
	ds_read_b128 v[234:237], v188 offset:21504
	ds_read_b128 v[242:245], v188 offset:22528
	ds_read_b128 v[246:249], v188 offset:23552
	global_load_lds_dwordx4 v[176:177], off
	v_lshl_add_u64 v[178:179], s[50:51], 0, v[160:161]
	s_mov_b32 m0, s68
	s_addc_u32 s63, s51, 0
	global_load_lds_dwordx4 v[178:179], off
	v_lshl_add_u64 v[180:181], s[62:63], 0, v[156:157]
	s_mov_b32 m0, s69
	v_lshl_add_u64 v[182:183], s[54:55], 0, v[158:159]
	global_load_lds_dwordx4 v[180:181], off
	v_lshl_add_u64 v[180:181], s[62:63], 0, v[160:161]
	s_mov_b32 m0, s74
	s_nop 0
	global_load_lds_dwordx4 v[180:181], off
	v_lshl_add_u64 v[180:181], s[54:55], 0, v[154:155]
	s_mov_b32 m0, s33
	s_nop 0
	global_load_lds_dwordx4 v[180:181], off
	s_mov_b32 m0, s75
	s_nop 0
	global_load_lds_dwordx4 v[182:183], off
	s_waitcnt vmcnt(8)
	s_waitcnt lgkmcnt(0)
	s_setprio 1
	s_barrier
	v_mfma_f32_16x16x128_f8f6f4 v[70:73], v[2:9], v[214:221], v[70:73]
	v_mfma_f32_16x16x128_f8f6f4 v[66:69], v[190:197], v[214:221], v[66:69]
	v_mfma_f32_16x16x128_f8f6f4 v[58:61], v[190:197], v[222:229], v[58:61]
	v_mfma_f32_16x16x128_f8f6f4 v[62:65], v[2:9], v[222:229], v[62:65]
	v_mfma_f32_16x16x128_f8f6f4 v[54:57], v[2:9], v[230:237], v[54:57]
	v_mfma_f32_16x16x128_f8f6f4 v[50:53], v[190:197], v[230:237], v[50:53]
	v_mfma_f32_16x16x128_f8f6f4 v[42:45], v[190:197], v[242:249], v[42:45]
	v_mfma_f32_16x16x128_f8f6f4 v[46:49], v[2:9], v[242:249], v[46:49]
	s_setprio 0
	s_setprio 1
	v_mfma_f32_16x16x128_f8f6f4 v[14:17], v[198:205], v[242:249], v[14:17]
	v_mfma_f32_16x16x128_f8f6f4 v[10:13], v[206:213], v[242:249], v[10:13]
	v_mfma_f32_16x16x128_f8f6f4 v[18:21], v[206:213], v[230:237], v[18:21]
	v_mfma_f32_16x16x128_f8f6f4 v[22:25], v[198:205], v[230:237], v[22:25]
	v_mfma_f32_16x16x128_f8f6f4 v[30:33], v[198:205], v[222:229], v[30:33]
	v_mfma_f32_16x16x128_f8f6f4 v[26:29], v[206:213], v[222:229], v[26:29]
	v_mfma_f32_16x16x128_f8f6f4 v[34:37], v[206:213], v[214:221], v[34:37]
	v_mfma_f32_16x16x128_f8f6f4 v[38:41], v[198:205], v[214:221], v[38:41]
	s_barrier
	s_setprio 0
	ds_read_b128 v[190:193], v187 offset:32768
	ds_read_b128 v[194:197], v187 offset:33792
	ds_read_b128 v[198:201], v187 offset:34816
	ds_read_b128 v[202:205], v187 offset:35840
	ds_read_b128 v[2:5], v187 offset:49152
	ds_read_b128 v[6:9], v187 offset:50176
	ds_read_b128 v[206:209], v187 offset:51200
	ds_read_b128 v[210:213], v187 offset:52224
	s_add_u32 s54, s54, 0x158000
	s_addc_u32 s55, s55, 0
	s_mov_b32 m0, s76
	v_lshl_add_u64 v[238:239], s[54:55], 0, v[154:155]
	ds_read_b128 v[214:217], v188 offset:32768
	ds_read_b128 v[218:221], v188 offset:33792
	ds_read_b128 v[222:225], v188 offset:34816
	ds_read_b128 v[226:229], v188 offset:35840
	ds_read_b128 v[230:233], v188 offset:36864
	ds_read_b128 v[234:237], v188 offset:37888
	ds_read_b128 v[242:245], v188 offset:38912
	ds_read_b128 v[246:249], v188 offset:39936
	global_load_lds_dwordx4 v[238:239], off
	v_lshl_add_u64 v[238:239], s[54:55], 0, v[158:159]
	s_mov_b32 m0, s77
	s_nop 0
	global_load_lds_dwordx4 v[238:239], off
	s_waitcnt vmcnt(8)
	s_waitcnt lgkmcnt(0)
	s_setprio 1
	s_barrier
	v_mfma_f32_16x16x128_f8f6f4 v[134:137], v[190:197], v[214:221], v[134:137]
	v_mfma_f32_16x16x128_f8f6f4 v[130:133], v[198:205], v[214:221], v[130:133]
	v_mfma_f32_16x16x128_f8f6f4 v[122:125], v[198:205], v[222:229], v[122:125]
	v_mfma_f32_16x16x128_f8f6f4 v[126:129], v[190:197], v[222:229], v[126:129]
	v_mfma_f32_16x16x128_f8f6f4 v[118:121], v[190:197], v[230:237], v[118:121]
	v_mfma_f32_16x16x128_f8f6f4 v[114:117], v[198:205], v[230:237], v[114:117]
	v_mfma_f32_16x16x128_f8f6f4 v[106:109], v[198:205], v[242:249], v[106:109]
	v_mfma_f32_16x16x128_f8f6f4 v[110:113], v[190:197], v[242:249], v[110:113]
	s_setprio 0
	s_setprio 1
	v_mfma_f32_16x16x128_f8f6f4 v[78:81], v[2:9], v[242:249], v[78:81]
	v_mfma_f32_16x16x128_f8f6f4 v[74:77], v[206:213], v[242:249], v[74:77]
	v_mfma_f32_16x16x128_f8f6f4 v[82:85], v[206:213], v[230:237], v[82:85]
	v_mfma_f32_16x16x128_f8f6f4 v[86:89], v[2:9], v[230:237], v[86:89]
	v_mfma_f32_16x16x128_f8f6f4 v[94:97], v[2:9], v[222:229], v[94:97]
	v_mfma_f32_16x16x128_f8f6f4 v[90:93], v[206:213], v[222:229], v[90:93]
	v_mfma_f32_16x16x128_f8f6f4 v[98:101], v[206:213], v[214:221], v[98:101]
	v_mfma_f32_16x16x128_f8f6f4 v[102:105], v[2:9], v[214:221], v[102:105]
	s_barrier
	s_setprio 0
	s_mov_b32 m0, s83
	v_lshl_add_u64 v[176:177], v[176:177], 0, s[26:27]
	s_add_u32 s50, s50, 0x158080
	ds_read_b128 v[214:217], v188 offset:49152
	ds_read_b128 v[218:221], v188 offset:50176
	ds_read_b128 v[222:225], v188 offset:51200
	ds_read_b128 v[226:229], v188 offset:52224
	ds_read_b128 v[230:233], v188 offset:53248
	ds_read_b128 v[234:237], v188 offset:54272
	ds_read_b128 v[242:245], v188 offset:55296
	ds_read_b128 v[246:249], v188 offset:56320
	global_load_lds_dwordx4 v[176:177], off
	v_lshl_add_u64 v[176:177], v[178:179], 0, s[26:27]
	s_mov_b32 m0, s84
	s_addc_u32 s51, s51, 0
	global_load_lds_dwordx4 v[176:177], off
	v_lshl_add_u64 v[176:177], s[50:51], 0, v[156:157]
	s_mov_b32 m0, s87
	s_nop 0
	global_load_lds_dwordx4 v[176:177], off
	v_lshl_add_u64 v[176:177], s[50:51], 0, v[160:161]
	s_mov_b32 m0, s88
	s_nop 0
	global_load_lds_dwordx4 v[176:177], off
	v_lshl_add_u64 v[176:177], v[180:181], 0, s[26:27]
	s_mov_b32 m0, s85
	s_nop 0
	global_load_lds_dwordx4 v[176:177], off
	v_lshl_add_u64 v[176:177], v[182:183], 0, s[26:27]
	s_mov_b32 m0, s86
	s_nop 0
	global_load_lds_dwordx4 v[176:177], off
	s_waitcnt vmcnt(8)
	s_waitcnt lgkmcnt(0)
	s_setprio 1
	s_barrier
	v_mfma_f32_16x16x128_f8f6f4 v[70:73], v[190:197], v[214:221], v[70:73]
	v_mfma_f32_16x16x128_f8f6f4 v[66:69], v[198:205], v[214:221], v[66:69]
	v_mfma_f32_16x16x128_f8f6f4 v[58:61], v[198:205], v[222:229], v[58:61]
	v_mfma_f32_16x16x128_f8f6f4 v[62:65], v[190:197], v[222:229], v[62:65]
	v_mfma_f32_16x16x128_f8f6f4 v[54:57], v[190:197], v[230:237], v[54:57]
	v_mfma_f32_16x16x128_f8f6f4 v[50:53], v[198:205], v[230:237], v[50:53]
	v_mfma_f32_16x16x128_f8f6f4 v[42:45], v[198:205], v[242:249], v[42:45]
	v_mfma_f32_16x16x128_f8f6f4 v[46:49], v[190:197], v[242:249], v[46:49]
	s_setprio 0
	s_setprio 1
	v_mfma_f32_16x16x128_f8f6f4 v[14:17], v[2:9], v[242:249], v[14:17]
	v_mfma_f32_16x16x128_f8f6f4 v[10:13], v[206:213], v[242:249], v[10:13]
	v_mfma_f32_16x16x128_f8f6f4 v[18:21], v[206:213], v[230:237], v[18:21]
	v_mfma_f32_16x16x128_f8f6f4 v[22:25], v[2:9], v[230:237], v[22:25]
	v_mfma_f32_16x16x128_f8f6f4 v[30:33], v[2:9], v[222:229], v[30:33]
	v_mfma_f32_16x16x128_f8f6f4 v[26:29], v[206:213], v[222:229], v[26:29]
	v_mfma_f32_16x16x128_f8f6f4 v[34:37], v[206:213], v[214:221], v[34:37]
	v_mfma_f32_16x16x128_f8f6f4 v[38:41], v[2:9], v[214:221], v[38:41]
	s_barrier
	s_setprio 0
	s_add_i32 s50, s72, 2
	s_add_u32 s52, s52, 0x100
	s_addc_u32 s53, s53, 0
	s_add_u32 s8, s8, 0x100
	s_addc_u32 s9, s9, 0
	s_cmp_ge_i32 s72, s95
	s_cbranch_scc1 .LBB0_287
	s_mov_b32 s72, s50
	s_cmp_eq_u32 s95, s72
	s_cselect_b64 s[50:51], -1, 0
	s_cmp_lg_u32 s95, s72
	s_cbranch_scc0 .LBB0_284
	s_branch .LBB0_285

.LBB0_437:
	s_ashr_i32 s47, s46, 31
	ds_read_b128 v[18:21], v200
	ds_read_b128 v[22:25], v200 offset:1024
	ds_read_b128 v[26:29], v200 offset:2048
	ds_read_b128 v[30:33], v200 offset:3072
	ds_read_b128 v[2:5], v200 offset:16384
	ds_read_b128 v[6:9], v200 offset:17408
	ds_read_b128 v[10:13], v200 offset:18432
	ds_read_b128 v[14:17], v200 offset:19456
	s_lshl_b64 s[8:9], s[46:47], 20
	s_add_u32 s48, s12, s8
	s_addc_u32 s49, s13, s9
	s_and_b64 s[8:9], s[2:3], exec
	s_cselect_b32 s47, s49, s73
	s_cselect_b32 s71, s48, s72
	s_ashr_i32 s45, s44, 31
	s_lshl_b64 s[8:9], s[44:45], 20
	s_add_u32 s50, s39, s8
	s_addc_u32 s51, s76, s9
	s_and_b64 s[8:9], s[2:3], exec
	s_cselect_b32 s45, s51, s55
	s_cselect_b32 s94, s50, s54
	s_add_u32 s8, s72, 0x80080
	s_addc_u32 s9, s73, 0
	s_mov_b32 m0, s33
	v_lshl_add_u64 v[226:227], s[8:9], 0, v[162:163]
	ds_read_b128 v[180:183], v201
	ds_read_b128 v[184:187], v201 offset:1024
	ds_read_b128 v[202:205], v201 offset:2048
	ds_read_b128 v[206:209], v201 offset:3072
	ds_read_b128 v[210:213], v201 offset:4096
	ds_read_b128 v[214:217], v201 offset:5120
	ds_read_b128 v[218:221], v201 offset:6144
	ds_read_b128 v[222:225], v201 offset:7168
	global_load_lds_dwordx4 v[226:227], off
	v_lshl_add_u64 v[226:227], s[8:9], 0, v[166:167]
	s_mov_b32 m0, s93
	s_nop 0
	global_load_lds_dwordx4 v[226:227], off
	s_waitcnt vmcnt(8)
	s_waitcnt lgkmcnt(0)
	s_setprio 1
	s_barrier
	v_mfma_f32_16x16x128_f8f6f4 v[158:161], v[18:25], v[180:187], 0
	v_mfma_f32_16x16x128_f8f6f4 v[154:157], v[26:33], v[180:187], 0
	v_mfma_f32_16x16x128_f8f6f4 v[146:149], v[26:33], v[202:209], 0
	v_mfma_f32_16x16x128_f8f6f4 v[150:153], v[18:25], v[202:209], 0
	v_mfma_f32_16x16x128_f8f6f4 v[142:145], v[18:25], v[210:217], 0
	v_mfma_f32_16x16x128_f8f6f4 v[138:141], v[26:33], v[210:217], 0
	v_mfma_f32_16x16x128_f8f6f4 v[130:133], v[26:33], v[218:225], 0
	v_mfma_f32_16x16x128_f8f6f4 v[134:137], v[18:25], v[218:225], 0
	s_setprio 0
	s_setprio 1
	v_mfma_f32_16x16x128_f8f6f4 v[102:105], v[2:9], v[218:225], 0
	v_mfma_f32_16x16x128_f8f6f4 v[98:101], v[10:17], v[218:225], 0
	v_mfma_f32_16x16x128_f8f6f4 v[106:109], v[10:17], v[210:217], 0
	v_mfma_f32_16x16x128_f8f6f4 v[110:113], v[2:9], v[210:217], 0
	v_mfma_f32_16x16x128_f8f6f4 v[118:121], v[2:9], v[202:209], 0
	v_mfma_f32_16x16x128_f8f6f4 v[114:117], v[10:17], v[202:209], 0
	v_mfma_f32_16x16x128_f8f6f4 v[122:125], v[10:17], v[180:187], 0
	v_mfma_f32_16x16x128_f8f6f4 v[126:129], v[2:9], v[180:187], 0
	s_barrier
	s_setprio 0
	v_lshl_add_u64 v[180:181], s[54:55], 0, v[164:165]
	s_mov_b32 m0, s78
	v_lshl_add_u64 v[182:183], v[180:181], 0, s[26:27]
	ds_read_b128 v[202:205], v201 offset:16384
	ds_read_b128 v[206:209], v201 offset:17408
	ds_read_b128 v[210:213], v201 offset:18432
	ds_read_b128 v[214:217], v201 offset:19456
	ds_read_b128 v[218:221], v201 offset:20480
	ds_read_b128 v[222:225], v201 offset:21504
	ds_read_b128 v[226:229], v201 offset:22528
	ds_read_b128 v[230:233], v201 offset:23552
	global_load_lds_dwordx4 v[182:183], off
	v_lshl_add_u64 v[182:183], s[54:55], 0, v[168:169]
	s_add_u32 s8, s54, 0x80100
	v_lshl_add_u64 v[184:185], v[182:183], 0, s[26:27]
	s_mov_b32 m0, s79
	s_addc_u32 s9, s55, 0
	global_load_lds_dwordx4 v[184:185], off
	v_lshl_add_u64 v[184:185], s[8:9], 0, v[164:165]
	s_mov_b32 m0, s80
	s_nop 0
	global_load_lds_dwordx4 v[184:185], off
	v_lshl_add_u64 v[184:185], s[8:9], 0, v[168:169]
	s_mov_b32 m0, s81
	s_nop 0
	global_load_lds_dwordx4 v[184:185], off
	v_lshl_add_u64 v[184:185], s[72:73], 0, v[162:163]
	v_lshl_add_u64 v[186:187], v[184:185], 0, s[26:27]
	s_mov_b32 m0, s53
	s_nop 0
	global_load_lds_dwordx4 v[186:187], off
	v_lshl_add_u64 v[186:187], s[72:73], 0, v[166:167]
	v_lshl_add_u64 v[234:235], v[186:187], 0, s[26:27]
	s_mov_b32 m0, s82
	s_nop 0
	global_load_lds_dwordx4 v[234:235], off
	s_waitcnt vmcnt(8)
	s_waitcnt lgkmcnt(0)
	s_setprio 1
	s_barrier
	v_mfma_f32_16x16x128_f8f6f4 v[94:97], v[18:25], v[202:209], 0
	v_mfma_f32_16x16x128_f8f6f4 v[90:93], v[26:33], v[202:209], 0
	v_mfma_f32_16x16x128_f8f6f4 v[82:85], v[26:33], v[210:217], 0
	v_mfma_f32_16x16x128_f8f6f4 v[86:89], v[18:25], v[210:217], 0
	v_mfma_f32_16x16x128_f8f6f4 v[78:81], v[18:25], v[218:225], 0
	v_mfma_f32_16x16x128_f8f6f4 v[74:77], v[26:33], v[218:225], 0
	v_mfma_f32_16x16x128_f8f6f4 v[66:69], v[26:33], v[226:233], 0
	v_mfma_f32_16x16x128_f8f6f4 v[70:73], v[18:25], v[226:233], 0
	s_setprio 0
	s_setprio 1
	v_mfma_f32_16x16x128_f8f6f4 v[38:41], v[2:9], v[226:233], 0
	v_mfma_f32_16x16x128_f8f6f4 v[34:37], v[10:17], v[226:233], 0
	v_mfma_f32_16x16x128_f8f6f4 v[42:45], v[10:17], v[218:225], 0
	v_mfma_f32_16x16x128_f8f6f4 v[46:49], v[2:9], v[218:225], 0
	v_mfma_f32_16x16x128_f8f6f4 v[54:57], v[2:9], v[210:217], 0
	v_mfma_f32_16x16x128_f8f6f4 v[50:53], v[10:17], v[210:217], 0
	v_mfma_f32_16x16x128_f8f6f4 v[58:61], v[10:17], v[202:209], 0
	v_mfma_f32_16x16x128_f8f6f4 v[62:65], v[2:9], v[202:209], 0
	s_barrier
	s_setprio 0
	ds_read_b128 v[18:21], v200 offset:32768
	ds_read_b128 v[22:25], v200 offset:33792
	ds_read_b128 v[26:29], v200 offset:34816
	ds_read_b128 v[30:33], v200 offset:35840
	ds_read_b128 v[2:5], v200 offset:49152
	ds_read_b128 v[6:9], v200 offset:50176
	ds_read_b128 v[10:13], v200 offset:51200
	ds_read_b128 v[14:17], v200 offset:52224
	s_add_u32 s8, s72, 0x80100
	s_addc_u32 s9, s73, 0
	s_mov_b32 m0, s83
	v_lshl_add_u64 v[234:235], s[8:9], 0, v[162:163]
	ds_read_b128 v[202:205], v201 offset:32768
	ds_read_b128 v[206:209], v201 offset:33792
	ds_read_b128 v[210:213], v201 offset:34816
	ds_read_b128 v[214:217], v201 offset:35840
	ds_read_b128 v[218:221], v201 offset:36864
	ds_read_b128 v[222:225], v201 offset:37888
	ds_read_b128 v[226:229], v201 offset:38912
	ds_read_b128 v[230:233], v201 offset:39936
	global_load_lds_dwordx4 v[234:235], off
	v_lshl_add_u64 v[234:235], s[8:9], 0, v[166:167]
	s_mov_b32 m0, s84
	s_nop 0
	global_load_lds_dwordx4 v[234:235], off
	s_waitcnt vmcnt(8)
	s_waitcnt lgkmcnt(0)
	s_setprio 1
	s_barrier
	v_mfma_f32_16x16x128_f8f6f4 v[158:161], v[18:25], v[202:209], v[158:161]
	v_mfma_f32_16x16x128_f8f6f4 v[154:157], v[26:33], v[202:209], v[154:157]
	v_mfma_f32_16x16x128_f8f6f4 v[146:149], v[26:33], v[210:217], v[146:149]
	v_mfma_f32_16x16x128_f8f6f4 v[150:153], v[18:25], v[210:217], v[150:153]
	v_mfma_f32_16x16x128_f8f6f4 v[142:145], v[18:25], v[218:225], v[142:145]
	v_mfma_f32_16x16x128_f8f6f4 v[138:141], v[26:33], v[218:225], v[138:141]
	v_mfma_f32_16x16x128_f8f6f4 v[130:133], v[26:33], v[226:233], v[130:133]
	v_mfma_f32_16x16x128_f8f6f4 v[134:137], v[18:25], v[226:233], v[134:137]
	s_setprio 0
	s_setprio 1
	v_mfma_f32_16x16x128_f8f6f4 v[102:105], v[2:9], v[226:233], v[102:105]
	v_mfma_f32_16x16x128_f8f6f4 v[98:101], v[10:17], v[226:233], v[98:101]
	v_mfma_f32_16x16x128_f8f6f4 v[106:109], v[10:17], v[218:225], v[106:109]
	v_mfma_f32_16x16x128_f8f6f4 v[110:113], v[2:9], v[218:225], v[110:113]
	v_mfma_f32_16x16x128_f8f6f4 v[118:121], v[2:9], v[210:217], v[118:121]
	v_mfma_f32_16x16x128_f8f6f4 v[114:117], v[10:17], v[210:217], v[114:117]
	v_mfma_f32_16x16x128_f8f6f4 v[122:125], v[10:17], v[202:209], v[122:125]
	v_mfma_f32_16x16x128_f8f6f4 v[126:129], v[2:9], v[202:209], v[126:129]
	s_barrier
	s_setprio 0
	s_mov_b32 m0, s87
	v_lshl_add_u64 v[180:181], v[180:181], 0, s[36:37]
	s_add_u32 s8, s54, 0x80180
	ds_read_b128 v[202:205], v201 offset:49152
	ds_read_b128 v[206:209], v201 offset:50176
	ds_read_b128 v[210:213], v201 offset:51200
	ds_read_b128 v[214:217], v201 offset:52224
	ds_read_b128 v[218:221], v201 offset:53248
	ds_read_b128 v[222:225], v201 offset:54272
	ds_read_b128 v[226:229], v201 offset:55296
	ds_read_b128 v[230:233], v201 offset:56320
	global_load_lds_dwordx4 v[180:181], off
	v_lshl_add_u64 v[180:181], v[182:183], 0, s[36:37]
	s_mov_b32 m0, s88
	s_addc_u32 s9, s55, 0
	global_load_lds_dwordx4 v[180:181], off
	v_lshl_add_u64 v[180:181], s[8:9], 0, v[164:165]
	s_mov_b32 m0, s91
	s_nop 0
	global_load_lds_dwordx4 v[180:181], off
	v_lshl_add_u64 v[180:181], s[8:9], 0, v[168:169]
	s_mov_b32 m0, s92
	s_nop 0
	global_load_lds_dwordx4 v[180:181], off
	v_lshl_add_u64 v[180:181], v[184:185], 0, s[36:37]
	s_mov_b32 m0, s89
	s_nop 0
	global_load_lds_dwordx4 v[180:181], off
	v_lshl_add_u64 v[180:181], v[186:187], 0, s[36:37]
	s_mov_b32 m0, s90
	s_nop 0
	global_load_lds_dwordx4 v[180:181], off
	s_waitcnt vmcnt(8)
	s_waitcnt lgkmcnt(0)
	s_setprio 1
	s_barrier
	v_mfma_f32_16x16x128_f8f6f4 v[94:97], v[18:25], v[202:209], v[94:97]
	v_mfma_f32_16x16x128_f8f6f4 v[90:93], v[26:33], v[202:209], v[90:93]
	v_mfma_f32_16x16x128_f8f6f4 v[82:85], v[26:33], v[210:217], v[82:85]
	v_mfma_f32_16x16x128_f8f6f4 v[86:89], v[18:25], v[210:217], v[86:89]
	v_mfma_f32_16x16x128_f8f6f4 v[78:81], v[18:25], v[218:225], v[78:81]
	v_mfma_f32_16x16x128_f8f6f4 v[74:77], v[26:33], v[218:225], v[74:77]
	v_mfma_f32_16x16x128_f8f6f4 v[66:69], v[26:33], v[226:233], v[66:69]
	v_mfma_f32_16x16x128_f8f6f4 v[70:73], v[18:25], v[226:233], v[70:73]
	s_setprio 0
	s_setprio 1
	v_mfma_f32_16x16x128_f8f6f4 v[38:41], v[2:9], v[226:233], v[38:41]
	v_mfma_f32_16x16x128_f8f6f4 v[34:37], v[10:17], v[226:233], v[34:37]
	v_mfma_f32_16x16x128_f8f6f4 v[42:45], v[10:17], v[218:225], v[42:45]
	v_mfma_f32_16x16x128_f8f6f4 v[46:49], v[2:9], v[218:225], v[46:49]
	v_mfma_f32_16x16x128_f8f6f4 v[54:57], v[2:9], v[210:217], v[54:57]
	v_mfma_f32_16x16x128_f8f6f4 v[50:53], v[10:17], v[210:217], v[50:53]
	v_mfma_f32_16x16x128_f8f6f4 v[58:61], v[10:17], v[202:209], v[58:61]
	v_mfma_f32_16x16x128_f8f6f4 v[62:65], v[2:9], v[202:209], v[62:65]
	s_barrier
	s_setprio 0
	s_add_u32 s72, s72, 0x80180
	s_addc_u32 s73, s73, 0
	s_add_u32 s8, s54, 0x200
	s_addc_u32 s9, s55, 0
	s_mov_b32 s62, 0
.LBB0_438:
	ds_read_b128 v[2:5], v200
	ds_read_b128 v[6:9], v200 offset:1024
	ds_read_b128 v[18:21], v200 offset:2048
	ds_read_b128 v[22:25], v200 offset:3072
	ds_read_b128 v[26:29], v200 offset:16384
	ds_read_b128 v[30:33], v200 offset:17408
	ds_read_b128 v[180:183], v200 offset:18432
	ds_read_b128 v[184:187], v200 offset:19456
	s_add_u32 s54, s72, 0xfff80080
	s_addc_u32 s55, s73, -1
	s_cmp_eq_u32 s62, 28
	s_cselect_b32 s75, s47, s55
	s_cselect_b32 s74, s71, s54
	s_cselect_b32 s55, s45, s9
	s_cselect_b32 s54, s94, s8
	s_mov_b32 m0, s33
	v_lshl_add_u64 v[226:227], s[72:73], 0, v[170:171]
	ds_read_b128 v[10:13], v201
	ds_read_b128 v[14:17], v201 offset:1024
	ds_read_b128 v[202:205], v201 offset:2048
	ds_read_b128 v[206:209], v201 offset:3072
	ds_read_b128 v[210:213], v201 offset:4096
	ds_read_b128 v[214:217], v201 offset:5120
	ds_read_b128 v[218:221], v201 offset:6144
	ds_read_b128 v[222:225], v201 offset:7168
	global_load_lds_dwordx4 v[226:227], off
	v_lshl_add_u64 v[226:227], s[72:73], 0, v[172:173]
	s_mov_b32 m0, s93
	s_nop 0
	global_load_lds_dwordx4 v[226:227], off
	s_waitcnt vmcnt(8)
	s_waitcnt lgkmcnt(0)
	s_setprio 1
	s_barrier
	v_mfma_f32_16x16x128_f8f6f4 v[158:161], v[2:9], v[10:17], v[158:161]
	v_mfma_f32_16x16x128_f8f6f4 v[154:157], v[18:25], v[10:17], v[154:157]
	v_mfma_f32_16x16x128_f8f6f4 v[146:149], v[18:25], v[202:209], v[146:149]
	v_mfma_f32_16x16x128_f8f6f4 v[150:153], v[2:9], v[202:209], v[150:153]
	v_mfma_f32_16x16x128_f8f6f4 v[142:145], v[2:9], v[210:217], v[142:145]
	v_mfma_f32_16x16x128_f8f6f4 v[138:141], v[18:25], v[210:217], v[138:141]
	v_mfma_f32_16x16x128_f8f6f4 v[130:133], v[18:25], v[218:225], v[130:133]
	v_mfma_f32_16x16x128_f8f6f4 v[134:137], v[2:9], v[218:225], v[134:137]
	s_setprio 0
	s_setprio 1
	v_mfma_f32_16x16x128_f8f6f4 v[102:105], v[26:33], v[218:225], v[102:105]
	v_mfma_f32_16x16x128_f8f6f4 v[98:101], v[180:187], v[218:225], v[98:101]
	v_mfma_f32_16x16x128_f8f6f4 v[106:109], v[180:187], v[210:217], v[106:109]
	v_mfma_f32_16x16x128_f8f6f4 v[110:113], v[26:33], v[210:217], v[110:113]
	v_mfma_f32_16x16x128_f8f6f4 v[118:121], v[26:33], v[202:209], v[118:121]
	v_mfma_f32_16x16x128_f8f6f4 v[114:117], v[180:187], v[202:209], v[114:117]
	v_mfma_f32_16x16x128_f8f6f4 v[122:125], v[180:187], v[10:17], v[122:125]
	v_mfma_f32_16x16x128_f8f6f4 v[126:129], v[26:33], v[10:17], v[126:129]
	s_barrier
	s_setprio 0
	s_mov_b32 m0, s78
	v_lshl_add_u64 v[10:11], s[54:55], 0, v[164:165]
	s_add_u32 s96, s54, 0x80000
	ds_read_b128 v[202:205], v201 offset:16384
	ds_read_b128 v[206:209], v201 offset:17408
	ds_read_b128 v[210:213], v201 offset:18432
	ds_read_b128 v[214:217], v201 offset:19456
	ds_read_b128 v[218:221], v201 offset:20480
	ds_read_b128 v[222:225], v201 offset:21504
	ds_read_b128 v[226:229], v201 offset:22528
	ds_read_b128 v[230:233], v201 offset:23552
	global_load_lds_dwordx4 v[10:11], off
	v_lshl_add_u64 v[12:13], s[54:55], 0, v[168:169]
	s_mov_b32 m0, s79
	s_addc_u32 s97, s55, 0
	global_load_lds_dwordx4 v[12:13], off
	v_lshl_add_u64 v[14:15], s[96:97], 0, v[164:165]
	s_mov_b32 m0, s80
	v_lshl_add_u64 v[16:17], s[74:75], 0, v[166:167]
	global_load_lds_dwordx4 v[14:15], off
	v_lshl_add_u64 v[14:15], s[96:97], 0, v[168:169]
	s_mov_b32 m0, s81
	s_nop 0
	global_load_lds_dwordx4 v[14:15], off
	v_lshl_add_u64 v[14:15], s[74:75], 0, v[162:163]
	s_mov_b32 m0, s53
	s_nop 0
	global_load_lds_dwordx4 v[14:15], off
	s_mov_b32 m0, s82
	s_nop 0
	global_load_lds_dwordx4 v[16:17], off
	s_waitcnt vmcnt(8)
	s_waitcnt lgkmcnt(0)
	s_setprio 1
	s_barrier
	v_mfma_f32_16x16x128_f8f6f4 v[94:97], v[2:9], v[202:209], v[94:97]
	v_mfma_f32_16x16x128_f8f6f4 v[90:93], v[18:25], v[202:209], v[90:93]
	v_mfma_f32_16x16x128_f8f6f4 v[82:85], v[18:25], v[210:217], v[82:85]
	v_mfma_f32_16x16x128_f8f6f4 v[86:89], v[2:9], v[210:217], v[86:89]
	v_mfma_f32_16x16x128_f8f6f4 v[78:81], v[2:9], v[218:225], v[78:81]
	v_mfma_f32_16x16x128_f8f6f4 v[74:77], v[18:25], v[218:225], v[74:77]
	v_mfma_f32_16x16x128_f8f6f4 v[66:69], v[18:25], v[226:233], v[66:69]
	v_mfma_f32_16x16x128_f8f6f4 v[70:73], v[2:9], v[226:233], v[70:73]
	s_setprio 0
	s_setprio 1
	v_mfma_f32_16x16x128_f8f6f4 v[38:41], v[26:33], v[226:233], v[38:41]
	v_mfma_f32_16x16x128_f8f6f4 v[34:37], v[180:187], v[226:233], v[34:37]
	v_mfma_f32_16x16x128_f8f6f4 v[42:45], v[180:187], v[218:225], v[42:45]
	v_mfma_f32_16x16x128_f8f6f4 v[46:49], v[26:33], v[218:225], v[46:49]
	v_mfma_f32_16x16x128_f8f6f4 v[54:57], v[26:33], v[210:217], v[54:57]
	v_mfma_f32_16x16x128_f8f6f4 v[50:53], v[180:187], v[210:217], v[50:53]
	v_mfma_f32_16x16x128_f8f6f4 v[58:61], v[180:187], v[202:209], v[58:61]
	v_mfma_f32_16x16x128_f8f6f4 v[62:65], v[26:33], v[202:209], v[62:65]
	s_barrier
	s_setprio 0
	ds_read_b128 v[18:21], v200 offset:32768
	ds_read_b128 v[22:25], v200 offset:33792
	ds_read_b128 v[26:29], v200 offset:34816
	ds_read_b128 v[30:33], v200 offset:35840
	ds_read_b128 v[2:5], v200 offset:49152
	ds_read_b128 v[6:9], v200 offset:50176
	ds_read_b128 v[180:183], v200 offset:51200
	ds_read_b128 v[184:187], v200 offset:52224
	s_add_u32 s74, s74, 0x80000
	s_addc_u32 s75, s75, 0
	s_mov_b32 m0, s83
	v_lshl_add_u64 v[234:235], s[74:75], 0, v[162:163]
	ds_read_b128 v[202:205], v201 offset:32768
	ds_read_b128 v[206:209], v201 offset:33792
	ds_read_b128 v[210:213], v201 offset:34816
	ds_read_b128 v[214:217], v201 offset:35840
	ds_read_b128 v[218:221], v201 offset:36864
	ds_read_b128 v[222:225], v201 offset:37888
	ds_read_b128 v[226:229], v201 offset:38912
	ds_read_b128 v[230:233], v201 offset:39936
	global_load_lds_dwordx4 v[234:235], off
	v_lshl_add_u64 v[234:235], s[74:75], 0, v[166:167]
	s_mov_b32 m0, s84
	s_nop 0
	global_load_lds_dwordx4 v[234:235], off
	s_waitcnt vmcnt(8)
	s_waitcnt lgkmcnt(0)
	s_setprio 1
	s_barrier
	v_mfma_f32_16x16x128_f8f6f4 v[158:161], v[18:25], v[202:209], v[158:161]
	v_mfma_f32_16x16x128_f8f6f4 v[154:157], v[26:33], v[202:209], v[154:157]
	v_mfma_f32_16x16x128_f8f6f4 v[146:149], v[26:33], v[210:217], v[146:149]
	v_mfma_f32_16x16x128_f8f6f4 v[150:153], v[18:25], v[210:217], v[150:153]
	v_mfma_f32_16x16x128_f8f6f4 v[142:145], v[18:25], v[218:225], v[142:145]
	v_mfma_f32_16x16x128_f8f6f4 v[138:141], v[26:33], v[218:225], v[138:141]
	v_mfma_f32_16x16x128_f8f6f4 v[130:133], v[26:33], v[226:233], v[130:133]
	v_mfma_f32_16x16x128_f8f6f4 v[134:137], v[18:25], v[226:233], v[134:137]
	s_setprio 0
	s_setprio 1
	v_mfma_f32_16x16x128_f8f6f4 v[102:105], v[2:9], v[226:233], v[102:105]
	v_mfma_f32_16x16x128_f8f6f4 v[98:101], v[180:187], v[226:233], v[98:101]
	v_mfma_f32_16x16x128_f8f6f4 v[106:109], v[180:187], v[218:225], v[106:109]
	v_mfma_f32_16x16x128_f8f6f4 v[110:113], v[2:9], v[218:225], v[110:113]
	v_mfma_f32_16x16x128_f8f6f4 v[118:121], v[2:9], v[210:217], v[118:121]
	v_mfma_f32_16x16x128_f8f6f4 v[114:117], v[180:187], v[210:217], v[114:117]
	v_mfma_f32_16x16x128_f8f6f4 v[122:125], v[180:187], v[202:209], v[122:125]
	v_mfma_f32_16x16x128_f8f6f4 v[126:129], v[2:9], v[202:209], v[126:129]
	s_barrier
	s_setprio 0
	s_mov_b32 m0, s87
	v_lshl_add_u64 v[10:11], v[10:11], 0, s[4:5]
	s_add_u32 s54, s54, 0x80080
	ds_read_b128 v[202:205], v201 offset:49152
	ds_read_b128 v[206:209], v201 offset:50176
	ds_read_b128 v[210:213], v201 offset:51200
	ds_read_b128 v[214:217], v201 offset:52224
	ds_read_b128 v[218:221], v201 offset:53248
	ds_read_b128 v[222:225], v201 offset:54272
	ds_read_b128 v[226:229], v201 offset:55296
	ds_read_b128 v[230:233], v201 offset:56320
	global_load_lds_dwordx4 v[10:11], off
	v_lshl_add_u64 v[10:11], v[12:13], 0, s[4:5]
	s_mov_b32 m0, s88
	s_addc_u32 s55, s55, 0
	global_load_lds_dwordx4 v[10:11], off
	v_lshl_add_u64 v[10:11], s[54:55], 0, v[164:165]
	s_mov_b32 m0, s91
	s_nop 0
	global_load_lds_dwordx4 v[10:11], off
	v_lshl_add_u64 v[10:11], s[54:55], 0, v[168:169]
	s_mov_b32 m0, s92
	s_nop 0
	global_load_lds_dwordx4 v[10:11], off
	v_lshl_add_u64 v[10:11], v[14:15], 0, s[4:5]
	s_mov_b32 m0, s89
	s_nop 0
	global_load_lds_dwordx4 v[10:11], off
	v_lshl_add_u64 v[10:11], v[16:17], 0, s[4:5]
	s_mov_b32 m0, s90
	s_nop 0
	global_load_lds_dwordx4 v[10:11], off
	s_waitcnt vmcnt(8)
	s_waitcnt lgkmcnt(0)
	s_setprio 1
	s_barrier
	v_mfma_f32_16x16x128_f8f6f4 v[94:97], v[18:25], v[202:209], v[94:97]
	v_mfma_f32_16x16x128_f8f6f4 v[90:93], v[26:33], v[202:209], v[90:93]
	v_mfma_f32_16x16x128_f8f6f4 v[82:85], v[26:33], v[210:217], v[82:85]
	v_mfma_f32_16x16x128_f8f6f4 v[86:89], v[18:25], v[210:217], v[86:89]
	v_mfma_f32_16x16x128_f8f6f4 v[78:81], v[18:25], v[218:225], v[78:81]
	v_mfma_f32_16x16x128_f8f6f4 v[74:77], v[26:33], v[218:225], v[74:77]
	v_mfma_f32_16x16x128_f8f6f4 v[66:69], v[26:33], v[226:233], v[66:69]
	v_mfma_f32_16x16x128_f8f6f4 v[70:73], v[18:25], v[226:233], v[70:73]
	s_setprio 0
	s_setprio 1
	v_mfma_f32_16x16x128_f8f6f4 v[38:41], v[2:9], v[226:233], v[38:41]
	v_mfma_f32_16x16x128_f8f6f4 v[34:37], v[180:187], v[226:233], v[34:37]
	v_mfma_f32_16x16x128_f8f6f4 v[42:45], v[180:187], v[218:225], v[42:45]
	v_mfma_f32_16x16x128_f8f6f4 v[46:49], v[2:9], v[218:225], v[46:49]
	v_mfma_f32_16x16x128_f8f6f4 v[54:57], v[2:9], v[210:217], v[54:57]
	v_mfma_f32_16x16x128_f8f6f4 v[50:53], v[180:187], v[210:217], v[50:53]
	v_mfma_f32_16x16x128_f8f6f4 v[58:61], v[180:187], v[202:209], v[58:61]
	v_mfma_f32_16x16x128_f8f6f4 v[62:65], v[2:9], v[202:209], v[62:65]
	s_barrier
	s_setprio 0
	s_add_i32 s62, s62, 2
	s_add_u32 s72, s72, 0x100
	s_addc_u32 s73, s73, 0
	s_add_u32 s8, s8, 0x100
	s_addc_u32 s9, s9, 0
	s_cmp_gt_u32 s62, 29
	s_cbranch_scc0 .LBB0_438
	s_and_b64 vcc, exec, s[6:7]
	s_cbranch_vccz .LBB0_441
	s_barrier

.LBB0_452:
	ds_read_b128 v[146:149], v143
	ds_read_b128 v[150:153], v143 offset:1024
	ds_read_b128 v[154:157], v143 offset:2048
	ds_read_b128 v[158:161], v143 offset:3072
	ds_read_b128 v[162:165], v143 offset:16384
	ds_read_b128 v[166:169], v143 offset:17408
	ds_read_b128 v[170:173], v143 offset:18432
	ds_read_b128 v[174:177], v143 offset:19456
	s_add_u32 s8, s52, 0xfff00080
	s_addc_u32 s9, s53, -1
	s_cmp_eq_u32 s91, 28
	s_cselect_b32 s73, s27, s9
	s_cselect_b32 s72, s37, s8
	s_cselect_b32 s55, s39, s90
	s_cselect_b32 s54, s45, s89
	v_lshl_add_u64 v[140:141], s[52:53], 0, v[136:137]
	s_add_i32 m0, s47, 0xc000
	ds_read_b128 v[180:183], v144
	ds_read_b128 v[184:187], v144 offset:1024
	ds_read_b128 v[188:191], v144 offset:2048
	ds_read_b128 v[192:195], v144 offset:3072
	ds_read_b128 v[196:199], v144 offset:4096
	ds_read_b128 v[200:203], v144 offset:5120
	ds_read_b128 v[204:207], v144 offset:6144
	ds_read_b128 v[208:211], v144 offset:7168
	global_load_lds_dwordx4 v[140:141], off
	v_lshl_add_u64 v[140:141], s[52:53], 0, v[138:139]
	s_add_i32 m0, s47, 0xe000
	s_nop 0
	global_load_lds_dwordx4 v[140:141], off
	s_waitcnt vmcnt(8)
	s_waitcnt lgkmcnt(0)
	s_setprio 1
	s_barrier
	v_mfma_f32_16x16x32_bf16 v[126:129], v[146:149], v[180:183], v[126:129]
	v_mfma_f32_16x16x32_bf16 v[122:125], v[154:157], v[180:183], v[122:125]
	v_mfma_f32_16x16x32_bf16 v[118:121], v[146:149], v[188:191], v[118:121]
	v_mfma_f32_16x16x32_bf16 v[114:117], v[154:157], v[188:191], v[114:117]
	v_mfma_f32_16x16x32_bf16 v[110:113], v[146:149], v[196:199], v[110:113]
	v_mfma_f32_16x16x32_bf16 v[106:109], v[154:157], v[196:199], v[106:109]
	v_mfma_f32_16x16x32_bf16 v[102:105], v[146:149], v[204:207], v[102:105]
	v_mfma_f32_16x16x32_bf16 v[98:101], v[154:157], v[204:207], v[98:101]
	v_mfma_f32_16x16x32_bf16 v[126:129], v[150:153], v[184:187], v[126:129]
	v_mfma_f32_16x16x32_bf16 v[122:125], v[158:161], v[184:187], v[122:125]
	v_mfma_f32_16x16x32_bf16 v[118:121], v[150:153], v[192:195], v[118:121]
	v_mfma_f32_16x16x32_bf16 v[114:117], v[158:161], v[192:195], v[114:117]
	v_mfma_f32_16x16x32_bf16 v[110:113], v[150:153], v[200:203], v[110:113]
	v_mfma_f32_16x16x32_bf16 v[106:109], v[158:161], v[200:203], v[106:109]
	v_mfma_f32_16x16x32_bf16 v[102:105], v[150:153], v[208:211], v[102:105]
	v_mfma_f32_16x16x32_bf16 v[98:101], v[158:161], v[208:211], v[98:101]
	s_setprio 0
	s_setprio 1
	v_mfma_f32_16x16x32_bf16 v[90:93], v[162:165], v[180:183], v[90:93]
	v_mfma_f32_16x16x32_bf16 v[82:85], v[170:173], v[180:183], v[82:85]
	v_mfma_f32_16x16x32_bf16 v[74:77], v[162:165], v[188:191], v[74:77]
	v_mfma_f32_16x16x32_bf16 v[66:69], v[170:173], v[188:191], v[66:69]
	v_mfma_f32_16x16x32_bf16 v[58:61], v[162:165], v[196:199], v[58:61]
	v_mfma_f32_16x16x32_bf16 v[50:53], v[170:173], v[196:199], v[50:53]
	v_mfma_f32_16x16x32_bf16 v[42:45], v[162:165], v[204:207], v[42:45]
	v_mfma_f32_16x16x32_bf16 v[34:37], v[170:173], v[204:207], v[34:37]
	v_mfma_f32_16x16x32_bf16 v[90:93], v[166:169], v[184:187], v[90:93]
	v_mfma_f32_16x16x32_bf16 v[82:85], v[174:177], v[184:187], v[82:85]
	v_mfma_f32_16x16x32_bf16 v[74:77], v[166:169], v[192:195], v[74:77]
	v_mfma_f32_16x16x32_bf16 v[66:69], v[174:177], v[192:195], v[66:69]
	v_mfma_f32_16x16x32_bf16 v[58:61], v[166:169], v[200:203], v[58:61]
	v_mfma_f32_16x16x32_bf16 v[50:53], v[174:177], v[200:203], v[50:53]
	v_mfma_f32_16x16x32_bf16 v[42:45], v[166:169], v[208:211], v[42:45]
	v_mfma_f32_16x16x32_bf16 v[34:37], v[174:177], v[208:211], v[34:37]
	s_barrier
	s_setprio 0
	s_mov_b32 m0, s74
	v_lshl_add_u64 v[140:141], s[54:55], 0, v[132:133]
	s_add_u32 s8, s54, 0x100000
	ds_read_b128 v[180:183], v144 offset:16384
	ds_read_b128 v[184:187], v144 offset:17408
	ds_read_b128 v[188:191], v144 offset:18432
	ds_read_b128 v[192:195], v144 offset:19456
	ds_read_b128 v[196:199], v144 offset:20480
	ds_read_b128 v[200:203], v144 offset:21504
	ds_read_b128 v[204:207], v144 offset:22528
	ds_read_b128 v[208:211], v144 offset:23552
	global_load_lds_dwordx4 v[140:141], off
	v_lshl_add_u64 v[212:213], s[54:55], 0, v[130:131]
	s_mov_b32 m0, s75
	s_addc_u32 s9, s55, 0
	global_load_lds_dwordx4 v[212:213], off
	v_lshl_add_u64 v[214:215], s[8:9], 0, v[132:133]
	s_mov_b32 m0, s76
	v_lshl_add_u64 v[216:217], s[72:73], 0, v[130:131]
	global_load_lds_dwordx4 v[214:215], off
	v_lshl_add_u64 v[214:215], s[8:9], 0, v[130:131]
	s_mov_b32 m0, s77
	s_nop 0
	global_load_lds_dwordx4 v[214:215], off
	v_lshl_add_u64 v[214:215], s[72:73], 0, v[132:133]
	s_mov_b32 m0, s47
	s_nop 0
	global_load_lds_dwordx4 v[214:215], off
	s_mov_b32 m0, s78
	s_nop 0
	global_load_lds_dwordx4 v[216:217], off
	s_waitcnt vmcnt(8)
	s_waitcnt lgkmcnt(0)
	s_setprio 1
	s_barrier
	v_mfma_f32_16x16x32_bf16 v[94:97], v[146:149], v[180:183], v[94:97]
	v_mfma_f32_16x16x32_bf16 v[86:89], v[154:157], v[180:183], v[86:89]
	v_mfma_f32_16x16x32_bf16 v[78:81], v[146:149], v[188:191], v[78:81]
	v_mfma_f32_16x16x32_bf16 v[70:73], v[154:157], v[188:191], v[70:73]
	v_mfma_f32_16x16x32_bf16 v[62:65], v[146:149], v[196:199], v[62:65]
	v_mfma_f32_16x16x32_bf16 v[54:57], v[154:157], v[196:199], v[54:57]
	v_mfma_f32_16x16x32_bf16 v[46:49], v[146:149], v[204:207], v[46:49]
	v_mfma_f32_16x16x32_bf16 v[38:41], v[154:157], v[204:207], v[38:41]
	v_mfma_f32_16x16x32_bf16 v[94:97], v[150:153], v[184:187], v[94:97]
	v_mfma_f32_16x16x32_bf16 v[86:89], v[158:161], v[184:187], v[86:89]
	v_mfma_f32_16x16x32_bf16 v[78:81], v[150:153], v[192:195], v[78:81]
	v_mfma_f32_16x16x32_bf16 v[70:73], v[158:161], v[192:195], v[70:73]
	v_mfma_f32_16x16x32_bf16 v[62:65], v[150:153], v[200:203], v[62:65]
	v_mfma_f32_16x16x32_bf16 v[54:57], v[158:161], v[200:203], v[54:57]
	v_mfma_f32_16x16x32_bf16 v[46:49], v[150:153], v[208:211], v[46:49]
	v_mfma_f32_16x16x32_bf16 v[38:41], v[158:161], v[208:211], v[38:41]
	s_setprio 0
	s_setprio 1
	v_mfma_f32_16x16x32_bf16 v[30:33], v[162:165], v[180:183], v[30:33]
	v_mfma_f32_16x16x32_bf16 v[26:29], v[170:173], v[180:183], v[26:29]
	v_mfma_f32_16x16x32_bf16 v[22:25], v[162:165], v[188:191], v[22:25]
	v_mfma_f32_16x16x32_bf16 v[18:21], v[170:173], v[188:191], v[18:21]
	v_mfma_f32_16x16x32_bf16 v[14:17], v[162:165], v[196:199], v[14:17]
	v_mfma_f32_16x16x32_bf16 v[10:13], v[170:173], v[196:199], v[10:13]
	v_mfma_f32_16x16x32_bf16 v[6:9], v[162:165], v[204:207], v[6:9]
	v_mfma_f32_16x16x32_bf16 v[2:5], v[170:173], v[204:207], v[2:5]
	v_mfma_f32_16x16x32_bf16 v[30:33], v[166:169], v[184:187], v[30:33]
	v_mfma_f32_16x16x32_bf16 v[26:29], v[174:177], v[184:187], v[26:29]
	v_mfma_f32_16x16x32_bf16 v[22:25], v[166:169], v[192:195], v[22:25]
	v_mfma_f32_16x16x32_bf16 v[18:21], v[174:177], v[192:195], v[18:21]
	v_mfma_f32_16x16x32_bf16 v[14:17], v[166:169], v[200:203], v[14:17]
	v_mfma_f32_16x16x32_bf16 v[10:13], v[174:177], v[200:203], v[10:13]
	v_mfma_f32_16x16x32_bf16 v[6:9], v[166:169], v[208:211], v[6:9]
	v_mfma_f32_16x16x32_bf16 v[2:5], v[174:177], v[208:211], v[2:5]
	s_barrier
	s_setprio 0
	ds_read_b128 v[146:149], v143 offset:32768
	ds_read_b128 v[150:153], v143 offset:33792
	ds_read_b128 v[154:157], v143 offset:34816
	ds_read_b128 v[158:161], v143 offset:35840
	ds_read_b128 v[162:165], v143 offset:49152
	ds_read_b128 v[166:169], v143 offset:50176
	ds_read_b128 v[170:173], v143 offset:51200
	ds_read_b128 v[174:177], v143 offset:52224
	s_add_u32 s8, s72, 0x100000
	s_addc_u32 s9, s73, 0
	s_mov_b32 m0, s79
	v_lshl_add_u64 v[218:219], s[8:9], 0, v[132:133]
	ds_read_b128 v[180:183], v144 offset:32768
	ds_read_b128 v[184:187], v144 offset:33792
	ds_read_b128 v[188:191], v144 offset:34816
	ds_read_b128 v[192:195], v144 offset:35840
	ds_read_b128 v[196:199], v144 offset:36864
	ds_read_b128 v[200:203], v144 offset:37888
	ds_read_b128 v[204:207], v144 offset:38912
	ds_read_b128 v[208:211], v144 offset:39936
	global_load_lds_dwordx4 v[218:219], off
	v_lshl_add_u64 v[218:219], s[8:9], 0, v[130:131]
	s_mov_b32 m0, s80
	s_nop 0
	global_load_lds_dwordx4 v[218:219], off
	s_waitcnt vmcnt(8)
	s_waitcnt lgkmcnt(0)
	s_setprio 1
	s_barrier
	v_mfma_f32_16x16x32_bf16 v[126:129], v[146:149], v[180:183], v[126:129]
	v_mfma_f32_16x16x32_bf16 v[122:125], v[154:157], v[180:183], v[122:125]
	v_mfma_f32_16x16x32_bf16 v[118:121], v[146:149], v[188:191], v[118:121]
	v_mfma_f32_16x16x32_bf16 v[114:117], v[154:157], v[188:191], v[114:117]
	v_mfma_f32_16x16x32_bf16 v[110:113], v[146:149], v[196:199], v[110:113]
	v_mfma_f32_16x16x32_bf16 v[106:109], v[154:157], v[196:199], v[106:109]
	v_mfma_f32_16x16x32_bf16 v[102:105], v[146:149], v[204:207], v[102:105]
	v_mfma_f32_16x16x32_bf16 v[98:101], v[154:157], v[204:207], v[98:101]
	v_mfma_f32_16x16x32_bf16 v[126:129], v[150:153], v[184:187], v[126:129]
	v_mfma_f32_16x16x32_bf16 v[122:125], v[158:161], v[184:187], v[122:125]
	v_mfma_f32_16x16x32_bf16 v[118:121], v[150:153], v[192:195], v[118:121]
	v_mfma_f32_16x16x32_bf16 v[114:117], v[158:161], v[192:195], v[114:117]
	v_mfma_f32_16x16x32_bf16 v[110:113], v[150:153], v[200:203], v[110:113]
	v_mfma_f32_16x16x32_bf16 v[106:109], v[158:161], v[200:203], v[106:109]
	v_mfma_f32_16x16x32_bf16 v[102:105], v[150:153], v[208:211], v[102:105]
	v_mfma_f32_16x16x32_bf16 v[98:101], v[158:161], v[208:211], v[98:101]
	s_setprio 0
	s_setprio 1
	v_mfma_f32_16x16x32_bf16 v[90:93], v[162:165], v[180:183], v[90:93]
	v_mfma_f32_16x16x32_bf16 v[82:85], v[170:173], v[180:183], v[82:85]
	v_mfma_f32_16x16x32_bf16 v[74:77], v[162:165], v[188:191], v[74:77]
	v_mfma_f32_16x16x32_bf16 v[66:69], v[170:173], v[188:191], v[66:69]
	v_mfma_f32_16x16x32_bf16 v[58:61], v[162:165], v[196:199], v[58:61]
	v_mfma_f32_16x16x32_bf16 v[50:53], v[170:173], v[196:199], v[50:53]
	v_mfma_f32_16x16x32_bf16 v[42:45], v[162:165], v[204:207], v[42:45]
	v_mfma_f32_16x16x32_bf16 v[34:37], v[170:173], v[204:207], v[34:37]
	v_mfma_f32_16x16x32_bf16 v[90:93], v[166:169], v[184:187], v[90:93]
	v_mfma_f32_16x16x32_bf16 v[82:85], v[174:177], v[184:187], v[82:85]
	v_mfma_f32_16x16x32_bf16 v[74:77], v[166:169], v[192:195], v[74:77]
	v_mfma_f32_16x16x32_bf16 v[66:69], v[174:177], v[192:195], v[66:69]
	v_mfma_f32_16x16x32_bf16 v[58:61], v[166:169], v[200:203], v[58:61]
	v_mfma_f32_16x16x32_bf16 v[50:53], v[174:177], v[200:203], v[50:53]
	v_mfma_f32_16x16x32_bf16 v[42:45], v[166:169], v[208:211], v[42:45]
	v_mfma_f32_16x16x32_bf16 v[34:37], v[174:177], v[208:211], v[34:37]
	s_barrier
	s_setprio 0
	s_mov_b32 m0, s81
	v_lshl_add_u64 v[140:141], v[140:141], 0, s[4:5]
	s_add_u32 s8, s54, 0x100080
	ds_read_b128 v[180:183], v144 offset:49152
	ds_read_b128 v[184:187], v144 offset:50176
	ds_read_b128 v[188:191], v144 offset:51200
	ds_read_b128 v[192:195], v144 offset:52224
	ds_read_b128 v[196:199], v144 offset:53248
	ds_read_b128 v[200:203], v144 offset:54272
	ds_read_b128 v[204:207], v144 offset:55296
	ds_read_b128 v[208:211], v144 offset:56320
	global_load_lds_dwordx4 v[140:141], off
	v_lshl_add_u64 v[140:141], v[212:213], 0, s[4:5]
	s_mov_b32 m0, s82
	s_addc_u32 s9, s55, 0
	global_load_lds_dwordx4 v[140:141], off
	v_lshl_add_u64 v[140:141], s[8:9], 0, v[132:133]
	s_mov_b32 m0, s85
	s_nop 0
	global_load_lds_dwordx4 v[140:141], off
	v_lshl_add_u64 v[140:141], s[8:9], 0, v[130:131]
	s_mov_b32 m0, s86
	s_nop 0
	global_load_lds_dwordx4 v[140:141], off
	v_lshl_add_u64 v[140:141], v[214:215], 0, s[4:5]
	s_mov_b32 m0, s83
	s_nop 0
	global_load_lds_dwordx4 v[140:141], off
	v_lshl_add_u64 v[140:141], v[216:217], 0, s[4:5]
	s_mov_b32 m0, s84
	s_nop 0
	global_load_lds_dwordx4 v[140:141], off
	s_waitcnt vmcnt(8)
	s_waitcnt lgkmcnt(0)
	s_setprio 1
	s_barrier
	v_mfma_f32_16x16x32_bf16 v[94:97], v[146:149], v[180:183], v[94:97]
	v_mfma_f32_16x16x32_bf16 v[86:89], v[154:157], v[180:183], v[86:89]
	v_mfma_f32_16x16x32_bf16 v[78:81], v[146:149], v[188:191], v[78:81]
	v_mfma_f32_16x16x32_bf16 v[70:73], v[154:157], v[188:191], v[70:73]
	v_mfma_f32_16x16x32_bf16 v[62:65], v[146:149], v[196:199], v[62:65]
	v_mfma_f32_16x16x32_bf16 v[54:57], v[154:157], v[196:199], v[54:57]
	v_mfma_f32_16x16x32_bf16 v[46:49], v[146:149], v[204:207], v[46:49]
	v_mfma_f32_16x16x32_bf16 v[38:41], v[154:157], v[204:207], v[38:41]
	v_mfma_f32_16x16x32_bf16 v[94:97], v[150:153], v[184:187], v[94:97]
	v_mfma_f32_16x16x32_bf16 v[86:89], v[158:161], v[184:187], v[86:89]
	v_mfma_f32_16x16x32_bf16 v[78:81], v[150:153], v[192:195], v[78:81]
	v_mfma_f32_16x16x32_bf16 v[70:73], v[158:161], v[192:195], v[70:73]
	v_mfma_f32_16x16x32_bf16 v[62:65], v[150:153], v[200:203], v[62:65]
	v_mfma_f32_16x16x32_bf16 v[54:57], v[158:161], v[200:203], v[54:57]
	v_mfma_f32_16x16x32_bf16 v[46:49], v[150:153], v[208:211], v[46:49]
	v_mfma_f32_16x16x32_bf16 v[38:41], v[158:161], v[208:211], v[38:41]
	s_setprio 0
	s_setprio 1
	v_mfma_f32_16x16x32_bf16 v[30:33], v[162:165], v[180:183], v[30:33]
	v_mfma_f32_16x16x32_bf16 v[26:29], v[170:173], v[180:183], v[26:29]
	v_mfma_f32_16x16x32_bf16 v[22:25], v[162:165], v[188:191], v[22:25]
	v_mfma_f32_16x16x32_bf16 v[18:21], v[170:173], v[188:191], v[18:21]
	v_mfma_f32_16x16x32_bf16 v[14:17], v[162:165], v[196:199], v[14:17]
	v_mfma_f32_16x16x32_bf16 v[10:13], v[170:173], v[196:199], v[10:13]
	v_mfma_f32_16x16x32_bf16 v[6:9], v[162:165], v[204:207], v[6:9]
	v_mfma_f32_16x16x32_bf16 v[2:5], v[170:173], v[204:207], v[2:5]
	v_mfma_f32_16x16x32_bf16 v[30:33], v[166:169], v[184:187], v[30:33]
	v_mfma_f32_16x16x32_bf16 v[26:29], v[174:177], v[184:187], v[26:29]
	v_mfma_f32_16x16x32_bf16 v[22:25], v[166:169], v[192:195], v[22:25]
	v_mfma_f32_16x16x32_bf16 v[18:21], v[174:177], v[192:195], v[18:21]
	v_mfma_f32_16x16x32_bf16 v[14:17], v[166:169], v[200:203], v[14:17]
	v_mfma_f32_16x16x32_bf16 v[10:13], v[174:177], v[200:203], v[10:13]
	v_mfma_f32_16x16x32_bf16 v[6:9], v[166:169], v[208:211], v[6:9]
	v_mfma_f32_16x16x32_bf16 v[2:5], v[174:177], v[208:211], v[2:5]
	s_barrier
	s_setprio 0
	s_add_i32 s91, s91, 2
	s_add_u32 s52, s52, 0x100
	s_addc_u32 s53, s53, 0
	s_add_u32 s89, s89, 0x100
	s_addc_u32 s90, s90, 0
	s_cmp_gt_u32 s91, 29
	s_cbranch_scc0 .LBB0_452
	s_and_b64 vcc, exec, s[6:7]
	s_cbranch_vccz .LBB0_455
	s_barrier

.LBB0_600:
	s_ashr_i32 s55, s54, 31
	ds_read_b128 v[18:21], v200
	ds_read_b128 v[22:25], v200 offset:1024
	ds_read_b128 v[26:29], v200 offset:2048
	ds_read_b128 v[30:33], v200 offset:3072
	ds_read_b128 v[2:5], v200 offset:16384
	ds_read_b128 v[6:9], v200 offset:17408
	ds_read_b128 v[10:13], v200 offset:18432
	ds_read_b128 v[14:17], v200 offset:19456
	s_lshl_b64 s[4:5], s[54:55], 18
	s_add_u32 s72, s38, s4
	s_addc_u32 s73, s39, s5
	s_and_b64 s[4:5], s[2:3], exec
	s_cselect_b32 s4, s73, s81
	s_cselect_b32 s5, s72, s80
	s_ashr_i32 s53, s52, 31
	s_lshl_b64 s[8:9], s[52:53], 18
	s_add_u32 s74, s94, s8
	v_readlane_b32 s8, v254, 6
	s_addc_u32 s75, s8, s9
	s_and_b64 s[8:9], s[2:3], exec
	s_cselect_b32 s53, s75, s79
	s_cselect_b32 s55, s74, s78
	s_add_u32 s8, s80, 0x20080
	s_addc_u32 s9, s81, 0
	s_mov_b32 m0, s96
	v_lshl_add_u64 v[226:227], s[8:9], 0, v[162:163]
	ds_read_b128 v[182:185], v201
	ds_read_b128 v[186:189], v201 offset:1024
	ds_read_b128 v[202:205], v201 offset:2048
	ds_read_b128 v[206:209], v201 offset:3072
	ds_read_b128 v[210:213], v201 offset:4096
	ds_read_b128 v[214:217], v201 offset:5120
	ds_read_b128 v[218:221], v201 offset:6144
	ds_read_b128 v[222:225], v201 offset:7168
	global_load_lds_dwordx4 v[226:227], off
	v_lshl_add_u64 v[226:227], s[8:9], 0, v[166:167]
	s_mov_b32 m0, s61
	s_nop 0
	global_load_lds_dwordx4 v[226:227], off
	s_waitcnt vmcnt(8)
	s_waitcnt lgkmcnt(0)
	s_setprio 1
	s_barrier
	v_mfma_f32_16x16x128_f8f6f4 v[158:161], v[18:25], v[182:189], 0
	v_mfma_f32_16x16x128_f8f6f4 v[154:157], v[26:33], v[182:189], 0
	v_mfma_f32_16x16x128_f8f6f4 v[146:149], v[26:33], v[202:209], 0
	v_mfma_f32_16x16x128_f8f6f4 v[150:153], v[18:25], v[202:209], 0
	v_mfma_f32_16x16x128_f8f6f4 v[142:145], v[18:25], v[210:217], 0
	v_mfma_f32_16x16x128_f8f6f4 v[138:141], v[26:33], v[210:217], 0
	v_mfma_f32_16x16x128_f8f6f4 v[130:133], v[26:33], v[218:225], 0
	v_mfma_f32_16x16x128_f8f6f4 v[134:137], v[18:25], v[218:225], 0
	s_setprio 0
	s_setprio 1
	v_mfma_f32_16x16x128_f8f6f4 v[102:105], v[2:9], v[218:225], 0
	v_mfma_f32_16x16x128_f8f6f4 v[98:101], v[10:17], v[218:225], 0
	v_mfma_f32_16x16x128_f8f6f4 v[106:109], v[10:17], v[210:217], 0
	v_mfma_f32_16x16x128_f8f6f4 v[110:113], v[2:9], v[210:217], 0
	v_mfma_f32_16x16x128_f8f6f4 v[118:121], v[2:9], v[202:209], 0
	v_mfma_f32_16x16x128_f8f6f4 v[114:117], v[10:17], v[202:209], 0
	v_mfma_f32_16x16x128_f8f6f4 v[122:125], v[10:17], v[182:189], 0
	v_mfma_f32_16x16x128_f8f6f4 v[126:129], v[2:9], v[182:189], 0
	s_barrier
	s_setprio 0
	v_lshl_add_u64 v[182:183], s[78:79], 0, v[164:165]
	s_mov_b32 m0, s68
	v_lshl_add_u64 v[184:185], v[182:183], 0, s[46:47]
	ds_read_b128 v[202:205], v201 offset:16384
	ds_read_b128 v[206:209], v201 offset:17408
	ds_read_b128 v[210:213], v201 offset:18432
	ds_read_b128 v[214:217], v201 offset:19456
	ds_read_b128 v[218:221], v201 offset:20480
	ds_read_b128 v[222:225], v201 offset:21504
	ds_read_b128 v[226:229], v201 offset:22528
	ds_read_b128 v[230:233], v201 offset:23552
	global_load_lds_dwordx4 v[184:185], off
	v_lshl_add_u64 v[184:185], s[78:79], 0, v[168:169]
	s_add_u32 s8, s78, 0x20100
	v_lshl_add_u64 v[186:187], v[184:185], 0, s[46:47]
	s_mov_b32 m0, s69
	s_addc_u32 s9, s79, 0
	global_load_lds_dwordx4 v[186:187], off
	v_lshl_add_u64 v[186:187], s[8:9], 0, v[164:165]
	s_mov_b32 m0, s77
	s_nop 0
	global_load_lds_dwordx4 v[186:187], off
	v_lshl_add_u64 v[186:187], s[8:9], 0, v[168:169]
	s_mov_b32 m0, s84
	s_nop 0
	global_load_lds_dwordx4 v[186:187], off
	v_lshl_add_u64 v[186:187], s[80:81], 0, v[162:163]
	v_lshl_add_u64 v[188:189], v[186:187], 0, s[46:47]
	s_mov_b32 m0, s33
	s_nop 0
	global_load_lds_dwordx4 v[188:189], off
	v_lshl_add_u64 v[188:189], s[80:81], 0, v[166:167]
	v_lshl_add_u64 v[234:235], v[188:189], 0, s[46:47]
	s_mov_b32 m0, s85
	s_nop 0
	global_load_lds_dwordx4 v[234:235], off
	s_waitcnt vmcnt(8)
	s_waitcnt lgkmcnt(0)
	s_setprio 1
	s_barrier
	v_mfma_f32_16x16x128_f8f6f4 v[94:97], v[18:25], v[202:209], 0
	v_mfma_f32_16x16x128_f8f6f4 v[90:93], v[26:33], v[202:209], 0
	v_mfma_f32_16x16x128_f8f6f4 v[82:85], v[26:33], v[210:217], 0
	v_mfma_f32_16x16x128_f8f6f4 v[86:89], v[18:25], v[210:217], 0
	v_mfma_f32_16x16x128_f8f6f4 v[78:81], v[18:25], v[218:225], 0
	v_mfma_f32_16x16x128_f8f6f4 v[74:77], v[26:33], v[218:225], 0
	v_mfma_f32_16x16x128_f8f6f4 v[66:69], v[26:33], v[226:233], 0
	v_mfma_f32_16x16x128_f8f6f4 v[70:73], v[18:25], v[226:233], 0
	s_setprio 0
	s_setprio 1
	v_mfma_f32_16x16x128_f8f6f4 v[38:41], v[2:9], v[226:233], 0
	v_mfma_f32_16x16x128_f8f6f4 v[34:37], v[10:17], v[226:233], 0
	v_mfma_f32_16x16x128_f8f6f4 v[42:45], v[10:17], v[218:225], 0
	v_mfma_f32_16x16x128_f8f6f4 v[46:49], v[2:9], v[218:225], 0
	v_mfma_f32_16x16x128_f8f6f4 v[54:57], v[2:9], v[210:217], 0
	v_mfma_f32_16x16x128_f8f6f4 v[50:53], v[10:17], v[210:217], 0
	v_mfma_f32_16x16x128_f8f6f4 v[58:61], v[10:17], v[202:209], 0
	v_mfma_f32_16x16x128_f8f6f4 v[62:65], v[2:9], v[202:209], 0
	s_barrier
	s_setprio 0
	ds_read_b128 v[18:21], v200 offset:32768
	ds_read_b128 v[22:25], v200 offset:33792
	ds_read_b128 v[26:29], v200 offset:34816
	ds_read_b128 v[30:33], v200 offset:35840
	ds_read_b128 v[2:5], v200 offset:49152
	ds_read_b128 v[6:9], v200 offset:50176
	ds_read_b128 v[10:13], v200 offset:51200
	ds_read_b128 v[14:17], v200 offset:52224
	s_add_u32 s8, s80, 0x20100
	s_addc_u32 s9, s81, 0
	s_mov_b32 m0, s86
	v_lshl_add_u64 v[234:235], s[8:9], 0, v[162:163]
	ds_read_b128 v[202:205], v201 offset:32768
	ds_read_b128 v[206:209], v201 offset:33792
	ds_read_b128 v[210:213], v201 offset:34816
	ds_read_b128 v[214:217], v201 offset:35840
	ds_read_b128 v[218:221], v201 offset:36864
	ds_read_b128 v[222:225], v201 offset:37888
	ds_read_b128 v[226:229], v201 offset:38912
	ds_read_b128 v[230:233], v201 offset:39936
	global_load_lds_dwordx4 v[234:235], off
	v_lshl_add_u64 v[234:235], s[8:9], 0, v[166:167]
	s_mov_b32 m0, s87
	s_nop 0
	global_load_lds_dwordx4 v[234:235], off
	s_waitcnt vmcnt(8)
	s_waitcnt lgkmcnt(0)
	s_setprio 1
	s_barrier
	v_mfma_f32_16x16x128_f8f6f4 v[158:161], v[18:25], v[202:209], v[158:161]
	v_mfma_f32_16x16x128_f8f6f4 v[154:157], v[26:33], v[202:209], v[154:157]
	v_mfma_f32_16x16x128_f8f6f4 v[146:149], v[26:33], v[210:217], v[146:149]
	v_mfma_f32_16x16x128_f8f6f4 v[150:153], v[18:25], v[210:217], v[150:153]
	v_mfma_f32_16x16x128_f8f6f4 v[142:145], v[18:25], v[218:225], v[142:145]
	v_mfma_f32_16x16x128_f8f6f4 v[138:141], v[26:33], v[218:225], v[138:141]
	v_mfma_f32_16x16x128_f8f6f4 v[130:133], v[26:33], v[226:233], v[130:133]
	v_mfma_f32_16x16x128_f8f6f4 v[134:137], v[18:25], v[226:233], v[134:137]
	s_setprio 0
	s_setprio 1
	v_mfma_f32_16x16x128_f8f6f4 v[102:105], v[2:9], v[226:233], v[102:105]
	v_mfma_f32_16x16x128_f8f6f4 v[98:101], v[10:17], v[226:233], v[98:101]
	v_mfma_f32_16x16x128_f8f6f4 v[106:109], v[10:17], v[218:225], v[106:109]
	v_mfma_f32_16x16x128_f8f6f4 v[110:113], v[2:9], v[218:225], v[110:113]
	v_mfma_f32_16x16x128_f8f6f4 v[118:121], v[2:9], v[210:217], v[118:121]
	v_mfma_f32_16x16x128_f8f6f4 v[114:117], v[10:17], v[210:217], v[114:117]
	v_mfma_f32_16x16x128_f8f6f4 v[122:125], v[10:17], v[202:209], v[122:125]
	v_mfma_f32_16x16x128_f8f6f4 v[126:129], v[2:9], v[202:209], v[126:129]
	s_barrier
	s_setprio 0
	s_mov_b32 m0, s89
	v_lshl_add_u64 v[182:183], v[182:183], 0, s[48:49]
	s_add_u32 s8, s78, 0x20180
	ds_read_b128 v[202:205], v201 offset:49152
	ds_read_b128 v[206:209], v201 offset:50176
	ds_read_b128 v[210:213], v201 offset:51200
	ds_read_b128 v[214:217], v201 offset:52224
	ds_read_b128 v[218:221], v201 offset:53248
	ds_read_b128 v[222:225], v201 offset:54272
	ds_read_b128 v[226:229], v201 offset:55296
	ds_read_b128 v[230:233], v201 offset:56320
	global_load_lds_dwordx4 v[182:183], off
	v_lshl_add_u64 v[182:183], v[184:185], 0, s[48:49]
	s_mov_b32 m0, s90
	s_addc_u32 s9, s79, 0
	global_load_lds_dwordx4 v[182:183], off
	v_lshl_add_u64 v[182:183], s[8:9], 0, v[164:165]
	s_mov_b32 m0, s93
	s_nop 0
	global_load_lds_dwordx4 v[182:183], off
	v_lshl_add_u64 v[182:183], s[8:9], 0, v[168:169]
	s_mov_b32 m0, s95
	s_nop 0
	global_load_lds_dwordx4 v[182:183], off
	v_lshl_add_u64 v[182:183], v[186:187], 0, s[48:49]
	s_mov_b32 m0, s91
	s_nop 0
	global_load_lds_dwordx4 v[182:183], off
	v_lshl_add_u64 v[182:183], v[188:189], 0, s[48:49]
	s_mov_b32 m0, s92
	s_nop 0
	global_load_lds_dwordx4 v[182:183], off
	s_waitcnt vmcnt(8)
	s_waitcnt lgkmcnt(0)
	s_setprio 1
	s_barrier
	v_mfma_f32_16x16x128_f8f6f4 v[94:97], v[18:25], v[202:209], v[94:97]
	v_mfma_f32_16x16x128_f8f6f4 v[90:93], v[26:33], v[202:209], v[90:93]
	v_mfma_f32_16x16x128_f8f6f4 v[82:85], v[26:33], v[210:217], v[82:85]
	v_mfma_f32_16x16x128_f8f6f4 v[86:89], v[18:25], v[210:217], v[86:89]
	v_mfma_f32_16x16x128_f8f6f4 v[78:81], v[18:25], v[218:225], v[78:81]
	v_mfma_f32_16x16x128_f8f6f4 v[74:77], v[26:33], v[218:225], v[74:77]
	v_mfma_f32_16x16x128_f8f6f4 v[66:69], v[26:33], v[226:233], v[66:69]
	v_mfma_f32_16x16x128_f8f6f4 v[70:73], v[18:25], v[226:233], v[70:73]
	s_setprio 0
	s_setprio 1
	v_mfma_f32_16x16x128_f8f6f4 v[38:41], v[2:9], v[226:233], v[38:41]
	v_mfma_f32_16x16x128_f8f6f4 v[34:37], v[10:17], v[226:233], v[34:37]
	v_mfma_f32_16x16x128_f8f6f4 v[42:45], v[10:17], v[218:225], v[42:45]
	v_mfma_f32_16x16x128_f8f6f4 v[46:49], v[2:9], v[218:225], v[46:49]
	v_mfma_f32_16x16x128_f8f6f4 v[54:57], v[2:9], v[210:217], v[54:57]
	v_mfma_f32_16x16x128_f8f6f4 v[50:53], v[10:17], v[210:217], v[50:53]
	v_mfma_f32_16x16x128_f8f6f4 v[58:61], v[10:17], v[202:209], v[58:61]
	v_mfma_f32_16x16x128_f8f6f4 v[62:65], v[2:9], v[202:209], v[62:65]
	s_barrier
	s_setprio 0
	s_add_u32 s80, s80, 0x20180
	s_addc_u32 s81, s81, 0
	s_add_u32 s8, s78, 0x200
	s_addc_u32 s9, s79, 0
	s_mov_b32 s62, 0
.LBB0_601:
	ds_read_b128 v[2:5], v200
	ds_read_b128 v[6:9], v200 offset:1024
	ds_read_b128 v[18:21], v200 offset:2048
	ds_read_b128 v[22:25], v200 offset:3072
	ds_read_b128 v[26:29], v200 offset:16384
	ds_read_b128 v[30:33], v200 offset:17408
	ds_read_b128 v[182:185], v200 offset:18432
	ds_read_b128 v[186:189], v200 offset:19456
	s_add_u32 s63, s80, 0xfffe0080
	s_addc_u32 s71, s81, -1
	s_cmp_eq_u32 s62, 4
	s_cselect_b32 s83, s4, s71
	s_cselect_b32 s82, s5, s63
	s_cselect_b32 s79, s53, s9
	s_cselect_b32 s78, s55, s8
	s_mov_b32 m0, s96
	v_lshl_add_u64 v[226:227], s[80:81], 0, v[170:171]
	ds_read_b128 v[10:13], v201
	ds_read_b128 v[14:17], v201 offset:1024
	ds_read_b128 v[202:205], v201 offset:2048
	ds_read_b128 v[206:209], v201 offset:3072
	ds_read_b128 v[210:213], v201 offset:4096
	ds_read_b128 v[214:217], v201 offset:5120
	ds_read_b128 v[218:221], v201 offset:6144
	ds_read_b128 v[222:225], v201 offset:7168
	global_load_lds_dwordx4 v[226:227], off
	v_lshl_add_u64 v[226:227], s[80:81], 0, v[172:173]
	s_mov_b32 m0, s61
	s_nop 0
	global_load_lds_dwordx4 v[226:227], off
	s_waitcnt vmcnt(8)
	s_waitcnt lgkmcnt(0)
	s_setprio 1
	s_barrier
	v_mfma_f32_16x16x128_f8f6f4 v[158:161], v[2:9], v[10:17], v[158:161]
	v_mfma_f32_16x16x128_f8f6f4 v[154:157], v[18:25], v[10:17], v[154:157]
	v_mfma_f32_16x16x128_f8f6f4 v[146:149], v[18:25], v[202:209], v[146:149]
	v_mfma_f32_16x16x128_f8f6f4 v[150:153], v[2:9], v[202:209], v[150:153]
	v_mfma_f32_16x16x128_f8f6f4 v[142:145], v[2:9], v[210:217], v[142:145]
	v_mfma_f32_16x16x128_f8f6f4 v[138:141], v[18:25], v[210:217], v[138:141]
	v_mfma_f32_16x16x128_f8f6f4 v[130:133], v[18:25], v[218:225], v[130:133]
	v_mfma_f32_16x16x128_f8f6f4 v[134:137], v[2:9], v[218:225], v[134:137]
	s_setprio 0
	s_setprio 1
	v_mfma_f32_16x16x128_f8f6f4 v[102:105], v[26:33], v[218:225], v[102:105]
	v_mfma_f32_16x16x128_f8f6f4 v[98:101], v[182:189], v[218:225], v[98:101]
	v_mfma_f32_16x16x128_f8f6f4 v[106:109], v[182:189], v[210:217], v[106:109]
	v_mfma_f32_16x16x128_f8f6f4 v[110:113], v[26:33], v[210:217], v[110:113]
	v_mfma_f32_16x16x128_f8f6f4 v[118:121], v[26:33], v[202:209], v[118:121]
	v_mfma_f32_16x16x128_f8f6f4 v[114:117], v[182:189], v[202:209], v[114:117]
	v_mfma_f32_16x16x128_f8f6f4 v[122:125], v[182:189], v[10:17], v[122:125]
	v_mfma_f32_16x16x128_f8f6f4 v[126:129], v[26:33], v[10:17], v[126:129]
	s_barrier
	s_setprio 0
	s_mov_b32 m0, s68
	v_lshl_add_u64 v[10:11], s[78:79], 0, v[164:165]
	s_add_u32 vcc_lo, s78, 0x20000
	ds_read_b128 v[202:205], v201 offset:16384
	ds_read_b128 v[206:209], v201 offset:17408
	ds_read_b128 v[210:213], v201 offset:18432
	ds_read_b128 v[214:217], v201 offset:19456
	ds_read_b128 v[218:221], v201 offset:20480
	ds_read_b128 v[222:225], v201 offset:21504
	ds_read_b128 v[226:229], v201 offset:22528
	ds_read_b128 v[230:233], v201 offset:23552
	global_load_lds_dwordx4 v[10:11], off
	v_lshl_add_u64 v[12:13], s[78:79], 0, v[168:169]
	s_mov_b32 m0, s69
	s_addc_u32 vcc_hi, s79, 0
	global_load_lds_dwordx4 v[12:13], off
	v_lshl_add_u64 v[14:15], vcc, 0, v[164:165]
	s_mov_b32 m0, s77
	v_lshl_add_u64 v[16:17], s[82:83], 0, v[166:167]
	global_load_lds_dwordx4 v[14:15], off
	v_lshl_add_u64 v[14:15], vcc, 0, v[168:169]
	s_mov_b32 m0, s84
	s_nop 0
	global_load_lds_dwordx4 v[14:15], off
	v_lshl_add_u64 v[14:15], s[82:83], 0, v[162:163]
	s_mov_b32 m0, s33
	s_nop 0
	global_load_lds_dwordx4 v[14:15], off
	s_mov_b32 m0, s85
	s_nop 0
	global_load_lds_dwordx4 v[16:17], off
	s_waitcnt vmcnt(8)
	s_waitcnt lgkmcnt(0)
	s_setprio 1
	s_barrier
	v_mfma_f32_16x16x128_f8f6f4 v[94:97], v[2:9], v[202:209], v[94:97]
	v_mfma_f32_16x16x128_f8f6f4 v[90:93], v[18:25], v[202:209], v[90:93]
	v_mfma_f32_16x16x128_f8f6f4 v[82:85], v[18:25], v[210:217], v[82:85]
	v_mfma_f32_16x16x128_f8f6f4 v[86:89], v[2:9], v[210:217], v[86:89]
	v_mfma_f32_16x16x128_f8f6f4 v[78:81], v[2:9], v[218:225], v[78:81]
	v_mfma_f32_16x16x128_f8f6f4 v[74:77], v[18:25], v[218:225], v[74:77]
	v_mfma_f32_16x16x128_f8f6f4 v[66:69], v[18:25], v[226:233], v[66:69]
	v_mfma_f32_16x16x128_f8f6f4 v[70:73], v[2:9], v[226:233], v[70:73]
	s_setprio 0
	s_setprio 1
	v_mfma_f32_16x16x128_f8f6f4 v[38:41], v[26:33], v[226:233], v[38:41]
	v_mfma_f32_16x16x128_f8f6f4 v[34:37], v[182:189], v[226:233], v[34:37]
	v_mfma_f32_16x16x128_f8f6f4 v[42:45], v[182:189], v[218:225], v[42:45]
	v_mfma_f32_16x16x128_f8f6f4 v[46:49], v[26:33], v[218:225], v[46:49]
	v_mfma_f32_16x16x128_f8f6f4 v[54:57], v[26:33], v[210:217], v[54:57]
	v_mfma_f32_16x16x128_f8f6f4 v[50:53], v[182:189], v[210:217], v[50:53]
	v_mfma_f32_16x16x128_f8f6f4 v[58:61], v[182:189], v[202:209], v[58:61]
	v_mfma_f32_16x16x128_f8f6f4 v[62:65], v[26:33], v[202:209], v[62:65]
	s_barrier
	s_setprio 0
	ds_read_b128 v[18:21], v200 offset:32768
	ds_read_b128 v[22:25], v200 offset:33792
	ds_read_b128 v[26:29], v200 offset:34816
	ds_read_b128 v[30:33], v200 offset:35840
	ds_read_b128 v[2:5], v200 offset:49152
	ds_read_b128 v[6:9], v200 offset:50176
	ds_read_b128 v[182:185], v200 offset:51200
	ds_read_b128 v[186:189], v200 offset:52224
	s_add_u32 s82, s82, 0x20000
	s_addc_u32 s83, s83, 0
	s_mov_b32 m0, s86
	v_lshl_add_u64 v[234:235], s[82:83], 0, v[162:163]
	ds_read_b128 v[202:205], v201 offset:32768
	ds_read_b128 v[206:209], v201 offset:33792
	ds_read_b128 v[210:213], v201 offset:34816
	ds_read_b128 v[214:217], v201 offset:35840
	ds_read_b128 v[218:221], v201 offset:36864
	ds_read_b128 v[222:225], v201 offset:37888
	ds_read_b128 v[226:229], v201 offset:38912
	ds_read_b128 v[230:233], v201 offset:39936
	global_load_lds_dwordx4 v[234:235], off
	v_lshl_add_u64 v[234:235], s[82:83], 0, v[166:167]
	s_mov_b32 m0, s87
	s_nop 0
	global_load_lds_dwordx4 v[234:235], off
	s_waitcnt vmcnt(8)
	s_waitcnt lgkmcnt(0)
	s_setprio 1
	s_barrier
	v_mfma_f32_16x16x128_f8f6f4 v[158:161], v[18:25], v[202:209], v[158:161]
	v_mfma_f32_16x16x128_f8f6f4 v[154:157], v[26:33], v[202:209], v[154:157]
	v_mfma_f32_16x16x128_f8f6f4 v[146:149], v[26:33], v[210:217], v[146:149]
	v_mfma_f32_16x16x128_f8f6f4 v[150:153], v[18:25], v[210:217], v[150:153]
	v_mfma_f32_16x16x128_f8f6f4 v[142:145], v[18:25], v[218:225], v[142:145]
	v_mfma_f32_16x16x128_f8f6f4 v[138:141], v[26:33], v[218:225], v[138:141]
	v_mfma_f32_16x16x128_f8f6f4 v[130:133], v[26:33], v[226:233], v[130:133]
	v_mfma_f32_16x16x128_f8f6f4 v[134:137], v[18:25], v[226:233], v[134:137]
	s_setprio 0
	s_setprio 1
	v_mfma_f32_16x16x128_f8f6f4 v[102:105], v[2:9], v[226:233], v[102:105]
	v_mfma_f32_16x16x128_f8f6f4 v[98:101], v[182:189], v[226:233], v[98:101]
	v_mfma_f32_16x16x128_f8f6f4 v[106:109], v[182:189], v[218:225], v[106:109]
	v_mfma_f32_16x16x128_f8f6f4 v[110:113], v[2:9], v[218:225], v[110:113]
	v_mfma_f32_16x16x128_f8f6f4 v[118:121], v[2:9], v[210:217], v[118:121]
	v_mfma_f32_16x16x128_f8f6f4 v[114:117], v[182:189], v[210:217], v[114:117]
	v_mfma_f32_16x16x128_f8f6f4 v[122:125], v[182:189], v[202:209], v[122:125]
	v_mfma_f32_16x16x128_f8f6f4 v[126:129], v[2:9], v[202:209], v[126:129]
	s_barrier
	s_setprio 0
	s_mov_b32 m0, s89
	v_lshl_add_u64 v[10:11], v[10:11], 0, s[42:43]
	s_add_u32 s78, s78, 0x20080
	ds_read_b128 v[202:205], v201 offset:49152
	ds_read_b128 v[206:209], v201 offset:50176
	ds_read_b128 v[210:213], v201 offset:51200
	ds_read_b128 v[214:217], v201 offset:52224
	ds_read_b128 v[218:221], v201 offset:53248
	ds_read_b128 v[222:225], v201 offset:54272
	ds_read_b128 v[226:229], v201 offset:55296
	ds_read_b128 v[230:233], v201 offset:56320
	global_load_lds_dwordx4 v[10:11], off
	v_lshl_add_u64 v[10:11], v[12:13], 0, s[42:43]
	s_mov_b32 m0, s90
	s_addc_u32 s79, s79, 0
	global_load_lds_dwordx4 v[10:11], off
	v_lshl_add_u64 v[10:11], s[78:79], 0, v[164:165]
	s_mov_b32 m0, s93
	s_nop 0
	global_load_lds_dwordx4 v[10:11], off
	v_lshl_add_u64 v[10:11], s[78:79], 0, v[168:169]
	s_mov_b32 m0, s95
	s_nop 0
	global_load_lds_dwordx4 v[10:11], off
	v_lshl_add_u64 v[10:11], v[14:15], 0, s[42:43]
	s_mov_b32 m0, s91
	s_nop 0
	global_load_lds_dwordx4 v[10:11], off
	v_lshl_add_u64 v[10:11], v[16:17], 0, s[42:43]
	s_mov_b32 m0, s92
	s_nop 0
	global_load_lds_dwordx4 v[10:11], off
	s_waitcnt vmcnt(8)
	s_waitcnt lgkmcnt(0)
	s_setprio 1
	s_barrier
	v_mfma_f32_16x16x128_f8f6f4 v[94:97], v[18:25], v[202:209], v[94:97]
	v_mfma_f32_16x16x128_f8f6f4 v[90:93], v[26:33], v[202:209], v[90:93]
	v_mfma_f32_16x16x128_f8f6f4 v[82:85], v[26:33], v[210:217], v[82:85]
	v_mfma_f32_16x16x128_f8f6f4 v[86:89], v[18:25], v[210:217], v[86:89]
	v_mfma_f32_16x16x128_f8f6f4 v[78:81], v[18:25], v[218:225], v[78:81]
	v_mfma_f32_16x16x128_f8f6f4 v[74:77], v[26:33], v[218:225], v[74:77]
	v_mfma_f32_16x16x128_f8f6f4 v[66:69], v[26:33], v[226:233], v[66:69]
	v_mfma_f32_16x16x128_f8f6f4 v[70:73], v[18:25], v[226:233], v[70:73]
	s_setprio 0
	s_setprio 1
	v_mfma_f32_16x16x128_f8f6f4 v[38:41], v[2:9], v[226:233], v[38:41]
	v_mfma_f32_16x16x128_f8f6f4 v[34:37], v[182:189], v[226:233], v[34:37]
	v_mfma_f32_16x16x128_f8f6f4 v[42:45], v[182:189], v[218:225], v[42:45]
	v_mfma_f32_16x16x128_f8f6f4 v[46:49], v[2:9], v[218:225], v[46:49]
	v_mfma_f32_16x16x128_f8f6f4 v[54:57], v[2:9], v[210:217], v[54:57]
	v_mfma_f32_16x16x128_f8f6f4 v[50:53], v[182:189], v[210:217], v[50:53]
	v_mfma_f32_16x16x128_f8f6f4 v[58:61], v[182:189], v[202:209], v[58:61]
	v_mfma_f32_16x16x128_f8f6f4 v[62:65], v[2:9], v[202:209], v[62:65]
	s_barrier
	s_setprio 0
	s_add_i32 s62, s62, 2
	s_add_u32 s80, s80, 0x100
	s_addc_u32 s81, s81, 0
	s_add_u32 s8, s8, 0x100
	s_addc_u32 s9, s9, 0
	s_cmp_gt_u32 s62, 5
	s_cbranch_scc0 .LBB0_601
	s_and_b64 vcc, exec, s[44:45]
	s_cbranch_vccz .LBB0_604
	s_barrier

.LBB0_616:
	ds_read_b128 v[18:21], v188
	ds_read_b128 v[22:25], v188 offset:1024
	ds_read_b128 v[26:29], v188 offset:2048
	ds_read_b128 v[30:33], v188 offset:3072
	ds_read_b128 v[2:5], v188 offset:16384
	ds_read_b128 v[6:9], v188 offset:17408
	ds_read_b128 v[10:13], v188 offset:18432
	ds_read_b128 v[14:17], v188 offset:19456
	s_ashr_i32 s55, s54, 31
	s_lshl_b64 s[62:63], s[54:55], 17
	s_add_u32 s72, s36, s62
	s_addc_u32 s73, s37, s63
	s_and_b64 s[62:63], s[2:3], exec
	s_cselect_b32 s85, s73, s79
	s_cselect_b32 s84, s72, s78
	s_ashr_i32 s53, s52, 31
	s_lshl_b64 s[62:63], s[52:53], 17
	s_add_u32 s74, s94, s62
	v_readlane_b32 s5, v254, 8
	s_addc_u32 s75, s5, s63
	s_and_b64 s[62:63], s[2:3], exec
	s_cselect_b32 s83, s75, s81
	s_cselect_b32 s82, s74, s80
	s_add_u32 s62, s78, 0x10080
	s_addc_u32 s63, s79, 0
	s_mov_b32 m0, s96
	v_lshl_add_u64 v[174:175], s[62:63], 0, v[166:167]
	ds_read_b128 v[196:199], v189
	ds_read_b128 v[200:203], v189 offset:1024
	ds_read_b128 v[204:207], v189 offset:2048
	ds_read_b128 v[208:211], v189 offset:3072
	ds_read_b128 v[212:215], v189 offset:4096
	ds_read_b128 v[216:219], v189 offset:5120
	ds_read_b128 v[220:223], v189 offset:6144
	ds_read_b128 v[224:227], v189 offset:7168
	global_load_lds_dwordx4 v[174:175], off
	v_lshl_add_u64 v[174:175], s[62:63], 0, v[168:169]
	s_mov_b32 m0, s97
	s_nop 0
	global_load_lds_dwordx4 v[174:175], off
	s_waitcnt vmcnt(8)
	s_waitcnt lgkmcnt(0)
	s_setprio 1
	s_barrier
	v_mfma_f32_16x16x128_f8f6f4 v[158:161], v[18:25], v[196:203], 0
	v_mfma_f32_16x16x128_f8f6f4 v[154:157], v[26:33], v[196:203], 0
	v_mfma_f32_16x16x128_f8f6f4 v[146:149], v[26:33], v[204:211], 0
	v_mfma_f32_16x16x128_f8f6f4 v[150:153], v[18:25], v[204:211], 0
	v_mfma_f32_16x16x128_f8f6f4 v[142:145], v[18:25], v[212:219], 0
	v_mfma_f32_16x16x128_f8f6f4 v[138:141], v[26:33], v[212:219], 0
	v_mfma_f32_16x16x128_f8f6f4 v[130:133], v[26:33], v[220:227], 0
	v_mfma_f32_16x16x128_f8f6f4 v[134:137], v[18:25], v[220:227], 0
	s_setprio 0
	s_setprio 1
	v_mfma_f32_16x16x128_f8f6f4 v[102:105], v[2:9], v[220:227], 0
	v_mfma_f32_16x16x128_f8f6f4 v[98:101], v[10:17], v[220:227], 0
	v_mfma_f32_16x16x128_f8f6f4 v[106:109], v[10:17], v[212:219], 0
	v_mfma_f32_16x16x128_f8f6f4 v[110:113], v[2:9], v[212:219], 0
	v_mfma_f32_16x16x128_f8f6f4 v[118:121], v[2:9], v[204:211], 0
	v_mfma_f32_16x16x128_f8f6f4 v[114:117], v[10:17], v[204:211], 0
	v_mfma_f32_16x16x128_f8f6f4 v[122:125], v[10:17], v[196:203], 0
	v_mfma_f32_16x16x128_f8f6f4 v[126:129], v[2:9], v[196:203], 0
	s_barrier
	s_setprio 0
	v_lshl_add_u64 v[174:175], s[80:81], 0, v[162:163]
	s_mov_b32 m0, s61
	v_lshl_add_u64 v[176:177], v[174:175], 0, s[46:47]
	ds_read_b128 v[196:199], v189 offset:16384
	ds_read_b128 v[200:203], v189 offset:17408
	ds_read_b128 v[204:207], v189 offset:18432
	ds_read_b128 v[208:211], v189 offset:19456
	ds_read_b128 v[212:215], v189 offset:20480
	ds_read_b128 v[216:219], v189 offset:21504
	ds_read_b128 v[220:223], v189 offset:22528
	ds_read_b128 v[224:227], v189 offset:23552
	global_load_lds_dwordx4 v[176:177], off
	v_lshl_add_u64 v[176:177], s[80:81], 0, v[164:165]
	s_add_u32 s62, s80, 0x10100
	v_lshl_add_u64 v[182:183], v[176:177], 0, s[46:47]
	s_mov_b32 m0, s68
	s_addc_u32 s63, s81, 0
	global_load_lds_dwordx4 v[182:183], off
	v_lshl_add_u64 v[182:183], s[62:63], 0, v[162:163]
	s_mov_b32 m0, s69
	s_nop 0
	global_load_lds_dwordx4 v[182:183], off
	v_lshl_add_u64 v[182:183], s[62:63], 0, v[164:165]
	s_mov_b32 m0, s77
	s_nop 0
	global_load_lds_dwordx4 v[182:183], off
	v_lshl_add_u64 v[182:183], s[78:79], 0, v[166:167]
	v_lshl_add_u64 v[184:185], v[182:183], 0, s[46:47]
	s_mov_b32 m0, s51
	s_nop 0
	global_load_lds_dwordx4 v[184:185], off
	v_lshl_add_u64 v[184:185], s[78:79], 0, v[168:169]
	v_lshl_add_u64 v[228:229], v[184:185], 0, s[46:47]
	s_mov_b32 m0, s86
	s_nop 0
	global_load_lds_dwordx4 v[228:229], off
	s_waitcnt vmcnt(8)
	s_waitcnt lgkmcnt(0)
	s_setprio 1
	s_barrier
	v_mfma_f32_16x16x128_f8f6f4 v[94:97], v[18:25], v[196:203], 0
	v_mfma_f32_16x16x128_f8f6f4 v[90:93], v[26:33], v[196:203], 0
	v_mfma_f32_16x16x128_f8f6f4 v[82:85], v[26:33], v[204:211], 0
	v_mfma_f32_16x16x128_f8f6f4 v[86:89], v[18:25], v[204:211], 0
	v_mfma_f32_16x16x128_f8f6f4 v[78:81], v[18:25], v[212:219], 0
	v_mfma_f32_16x16x128_f8f6f4 v[74:77], v[26:33], v[212:219], 0
	v_mfma_f32_16x16x128_f8f6f4 v[66:69], v[26:33], v[220:227], 0
	v_mfma_f32_16x16x128_f8f6f4 v[70:73], v[18:25], v[220:227], 0
	s_setprio 0
	s_setprio 1
	v_mfma_f32_16x16x128_f8f6f4 v[38:41], v[2:9], v[220:227], 0
	v_mfma_f32_16x16x128_f8f6f4 v[34:37], v[10:17], v[220:227], 0
	v_mfma_f32_16x16x128_f8f6f4 v[42:45], v[10:17], v[212:219], 0
	v_mfma_f32_16x16x128_f8f6f4 v[46:49], v[2:9], v[212:219], 0
	v_mfma_f32_16x16x128_f8f6f4 v[54:57], v[2:9], v[204:211], 0
	v_mfma_f32_16x16x128_f8f6f4 v[50:53], v[10:17], v[204:211], 0
	v_mfma_f32_16x16x128_f8f6f4 v[58:61], v[10:17], v[196:203], 0
	v_mfma_f32_16x16x128_f8f6f4 v[62:65], v[2:9], v[196:203], 0
	s_barrier
	s_setprio 0
	ds_read_b128 v[2:5], v188 offset:32768
	ds_read_b128 v[6:9], v188 offset:33792
	ds_read_b128 v[10:13], v188 offset:34816
	ds_read_b128 v[14:17], v188 offset:35840
	ds_read_b128 v[18:21], v188 offset:49152
	ds_read_b128 v[22:25], v188 offset:50176
	ds_read_b128 v[26:29], v188 offset:51200
	ds_read_b128 v[30:33], v188 offset:52224
	s_add_u32 s62, s78, 0x10100
	s_addc_u32 s63, s79, 0
	s_mov_b32 m0, s87
	v_lshl_add_u64 v[228:229], s[62:63], 0, v[166:167]
	ds_read_b128 v[196:199], v189 offset:32768
	ds_read_b128 v[200:203], v189 offset:33792
	ds_read_b128 v[204:207], v189 offset:34816
	ds_read_b128 v[208:211], v189 offset:35840
	ds_read_b128 v[212:215], v189 offset:36864
	ds_read_b128 v[216:219], v189 offset:37888
	ds_read_b128 v[220:223], v189 offset:38912
	ds_read_b128 v[224:227], v189 offset:39936
	global_load_lds_dwordx4 v[228:229], off
	v_lshl_add_u64 v[228:229], s[62:63], 0, v[168:169]
	s_mov_b32 m0, s88
	s_nop 0
	global_load_lds_dwordx4 v[228:229], off
	s_waitcnt vmcnt(8)
	s_waitcnt lgkmcnt(0)
	s_setprio 1
	s_barrier
	v_mfma_f32_16x16x128_f8f6f4 v[158:161], v[2:9], v[196:203], v[158:161]
	v_mfma_f32_16x16x128_f8f6f4 v[154:157], v[10:17], v[196:203], v[154:157]
	v_mfma_f32_16x16x128_f8f6f4 v[146:149], v[10:17], v[204:211], v[146:149]
	v_mfma_f32_16x16x128_f8f6f4 v[150:153], v[2:9], v[204:211], v[150:153]
	v_mfma_f32_16x16x128_f8f6f4 v[142:145], v[2:9], v[212:219], v[142:145]
	v_mfma_f32_16x16x128_f8f6f4 v[138:141], v[10:17], v[212:219], v[138:141]
	v_mfma_f32_16x16x128_f8f6f4 v[130:133], v[10:17], v[220:227], v[130:133]
	v_mfma_f32_16x16x128_f8f6f4 v[134:137], v[2:9], v[220:227], v[134:137]
	s_setprio 0
	s_setprio 1
	v_mfma_f32_16x16x128_f8f6f4 v[102:105], v[18:25], v[220:227], v[102:105]
	v_mfma_f32_16x16x128_f8f6f4 v[98:101], v[26:33], v[220:227], v[98:101]
	v_mfma_f32_16x16x128_f8f6f4 v[106:109], v[26:33], v[212:219], v[106:109]
	v_mfma_f32_16x16x128_f8f6f4 v[110:113], v[18:25], v[212:219], v[110:113]
	v_mfma_f32_16x16x128_f8f6f4 v[118:121], v[18:25], v[204:211], v[118:121]
	v_mfma_f32_16x16x128_f8f6f4 v[114:117], v[26:33], v[204:211], v[114:117]
	v_mfma_f32_16x16x128_f8f6f4 v[122:125], v[26:33], v[196:203], v[122:125]
	v_mfma_f32_16x16x128_f8f6f4 v[126:129], v[18:25], v[196:203], v[126:129]
	s_barrier
	s_setprio 0
	s_mov_b32 m0, s89
	v_lshl_add_u64 v[174:175], v[174:175], 0, s[48:49]
	s_add_u32 s62, s80, 0x10180
	ds_read_b128 v[196:199], v189 offset:49152
	ds_read_b128 v[200:203], v189 offset:50176
	ds_read_b128 v[204:207], v189 offset:51200
	ds_read_b128 v[208:211], v189 offset:52224
	ds_read_b128 v[212:215], v189 offset:53248
	ds_read_b128 v[216:219], v189 offset:54272
	ds_read_b128 v[220:223], v189 offset:55296
	ds_read_b128 v[224:227], v189 offset:56320
	global_load_lds_dwordx4 v[174:175], off
	v_lshl_add_u64 v[174:175], v[176:177], 0, s[48:49]
	s_mov_b32 m0, s90
	s_addc_u32 s63, s81, 0
	global_load_lds_dwordx4 v[174:175], off
	v_lshl_add_u64 v[174:175], s[62:63], 0, v[162:163]
	s_mov_b32 m0, s93
	s_nop 0
	global_load_lds_dwordx4 v[174:175], off
	v_lshl_add_u64 v[174:175], s[62:63], 0, v[164:165]
	s_mov_b32 m0, s95
	s_nop 0
	global_load_lds_dwordx4 v[174:175], off
	v_lshl_add_u64 v[174:175], v[182:183], 0, s[48:49]
	s_mov_b32 m0, s91
	s_nop 0
	global_load_lds_dwordx4 v[174:175], off
	v_lshl_add_u64 v[174:175], v[184:185], 0, s[48:49]
	s_mov_b32 m0, s92
	s_nop 0
	global_load_lds_dwordx4 v[174:175], off
	s_waitcnt vmcnt(8)
	s_waitcnt lgkmcnt(0)
	s_setprio 1
	s_barrier
	v_mfma_f32_16x16x128_f8f6f4 v[94:97], v[2:9], v[196:203], v[94:97]
	v_mfma_f32_16x16x128_f8f6f4 v[90:93], v[10:17], v[196:203], v[90:93]
	v_mfma_f32_16x16x128_f8f6f4 v[82:85], v[10:17], v[204:211], v[82:85]
	v_mfma_f32_16x16x128_f8f6f4 v[86:89], v[2:9], v[204:211], v[86:89]
	v_mfma_f32_16x16x128_f8f6f4 v[78:81], v[2:9], v[212:219], v[78:81]
	v_mfma_f32_16x16x128_f8f6f4 v[74:77], v[10:17], v[212:219], v[74:77]
	v_mfma_f32_16x16x128_f8f6f4 v[66:69], v[10:17], v[220:227], v[66:69]
	v_mfma_f32_16x16x128_f8f6f4 v[70:73], v[2:9], v[220:227], v[70:73]
	s_setprio 0
	s_setprio 1
	v_mfma_f32_16x16x128_f8f6f4 v[38:41], v[18:25], v[220:227], v[38:41]
	v_mfma_f32_16x16x128_f8f6f4 v[34:37], v[26:33], v[220:227], v[34:37]
	v_mfma_f32_16x16x128_f8f6f4 v[42:45], v[26:33], v[212:219], v[42:45]
	v_mfma_f32_16x16x128_f8f6f4 v[46:49], v[18:25], v[212:219], v[46:49]
	v_mfma_f32_16x16x128_f8f6f4 v[54:57], v[18:25], v[204:211], v[54:57]
	v_mfma_f32_16x16x128_f8f6f4 v[50:53], v[26:33], v[204:211], v[50:53]
	v_mfma_f32_16x16x128_f8f6f4 v[58:61], v[26:33], v[196:203], v[58:61]
	v_mfma_f32_16x16x128_f8f6f4 v[62:65], v[18:25], v[196:203], v[62:65]
	s_barrier
	s_setprio 0
	ds_read_b128 v[2:5], v188
	ds_read_b128 v[6:9], v188 offset:1024
	ds_read_b128 v[10:13], v188 offset:2048
	ds_read_b128 v[14:17], v188 offset:3072
	ds_read_b128 v[18:21], v188 offset:16384
	ds_read_b128 v[22:25], v188 offset:17408
	ds_read_b128 v[26:29], v188 offset:18432
	ds_read_b128 v[30:33], v188 offset:19456
	s_add_u32 s62, s78, 0x10180
	s_addc_u32 s63, s79, 0
	s_mov_b32 m0, s96
	v_lshl_add_u64 v[174:175], s[62:63], 0, v[166:167]
	ds_read_b128 v[196:199], v189
	ds_read_b128 v[200:203], v189 offset:1024
	ds_read_b128 v[204:207], v189 offset:2048
	ds_read_b128 v[208:211], v189 offset:3072
	ds_read_b128 v[212:215], v189 offset:4096
	ds_read_b128 v[216:219], v189 offset:5120
	ds_read_b128 v[220:223], v189 offset:6144
	ds_read_b128 v[224:227], v189 offset:7168
	global_load_lds_dwordx4 v[174:175], off
	v_lshl_add_u64 v[174:175], s[62:63], 0, v[168:169]
	s_mov_b32 m0, s97
	s_nop 0
	global_load_lds_dwordx4 v[174:175], off
	s_waitcnt vmcnt(8)
	s_waitcnt lgkmcnt(0)
	s_setprio 1
	s_barrier
	v_mfma_f32_16x16x128_f8f6f4 v[158:161], v[2:9], v[196:203], v[158:161]
	v_mfma_f32_16x16x128_f8f6f4 v[154:157], v[10:17], v[196:203], v[154:157]
	v_mfma_f32_16x16x128_f8f6f4 v[146:149], v[10:17], v[204:211], v[146:149]
	v_mfma_f32_16x16x128_f8f6f4 v[150:153], v[2:9], v[204:211], v[150:153]
	v_mfma_f32_16x16x128_f8f6f4 v[142:145], v[2:9], v[212:219], v[142:145]
	v_mfma_f32_16x16x128_f8f6f4 v[138:141], v[10:17], v[212:219], v[138:141]
	v_mfma_f32_16x16x128_f8f6f4 v[130:133], v[10:17], v[220:227], v[130:133]
	v_mfma_f32_16x16x128_f8f6f4 v[134:137], v[2:9], v[220:227], v[134:137]
	s_setprio 0
	s_setprio 1
	v_mfma_f32_16x16x128_f8f6f4 v[102:105], v[18:25], v[220:227], v[102:105]
	v_mfma_f32_16x16x128_f8f6f4 v[98:101], v[26:33], v[220:227], v[98:101]
	v_mfma_f32_16x16x128_f8f6f4 v[106:109], v[26:33], v[212:219], v[106:109]
	v_mfma_f32_16x16x128_f8f6f4 v[110:113], v[18:25], v[212:219], v[110:113]
	v_mfma_f32_16x16x128_f8f6f4 v[118:121], v[18:25], v[204:211], v[118:121]
	v_mfma_f32_16x16x128_f8f6f4 v[114:117], v[26:33], v[204:211], v[114:117]
	v_mfma_f32_16x16x128_f8f6f4 v[122:125], v[26:33], v[196:203], v[122:125]
	v_mfma_f32_16x16x128_f8f6f4 v[126:129], v[18:25], v[196:203], v[126:129]
	s_barrier
	s_setprio 0
	s_mov_b32 m0, s61
	v_lshl_add_u64 v[174:175], s[82:83], 0, v[162:163]
	s_add_u32 s62, s82, 0x10000
	ds_read_b128 v[196:199], v189 offset:16384
	ds_read_b128 v[200:203], v189 offset:17408
	ds_read_b128 v[204:207], v189 offset:18432
	ds_read_b128 v[208:211], v189 offset:19456
	ds_read_b128 v[212:215], v189 offset:20480
	ds_read_b128 v[216:219], v189 offset:21504
	ds_read_b128 v[220:223], v189 offset:22528
	ds_read_b128 v[224:227], v189 offset:23552
	global_load_lds_dwordx4 v[174:175], off
	v_lshl_add_u64 v[176:177], s[82:83], 0, v[164:165]
	s_mov_b32 m0, s68
	s_addc_u32 s63, s83, 0
	global_load_lds_dwordx4 v[176:177], off
	v_lshl_add_u64 v[182:183], s[62:63], 0, v[162:163]
	s_mov_b32 m0, s69
	v_lshl_add_u64 v[184:185], s[84:85], 0, v[168:169]
	global_load_lds_dwordx4 v[182:183], off
	v_lshl_add_u64 v[182:183], s[62:63], 0, v[164:165]
	s_mov_b32 m0, s77
	s_nop 0
	global_load_lds_dwordx4 v[182:183], off
	v_lshl_add_u64 v[182:183], s[84:85], 0, v[166:167]
	s_mov_b32 m0, s51
	s_nop 0
	global_load_lds_dwordx4 v[182:183], off
	s_mov_b32 m0, s86
	s_nop 0
	global_load_lds_dwordx4 v[184:185], off
	s_waitcnt vmcnt(8)
	s_waitcnt lgkmcnt(0)
	s_setprio 1
	s_barrier
	v_mfma_f32_16x16x128_f8f6f4 v[94:97], v[2:9], v[196:203], v[94:97]
	v_mfma_f32_16x16x128_f8f6f4 v[90:93], v[10:17], v[196:203], v[90:93]
	v_mfma_f32_16x16x128_f8f6f4 v[82:85], v[10:17], v[204:211], v[82:85]
	v_mfma_f32_16x16x128_f8f6f4 v[86:89], v[2:9], v[204:211], v[86:89]
	v_mfma_f32_16x16x128_f8f6f4 v[78:81], v[2:9], v[212:219], v[78:81]
	v_mfma_f32_16x16x128_f8f6f4 v[74:77], v[10:17], v[212:219], v[74:77]
	v_mfma_f32_16x16x128_f8f6f4 v[66:69], v[10:17], v[220:227], v[66:69]
	v_mfma_f32_16x16x128_f8f6f4 v[70:73], v[2:9], v[220:227], v[70:73]
	s_setprio 0
	s_setprio 1
	v_mfma_f32_16x16x128_f8f6f4 v[38:41], v[18:25], v[220:227], v[38:41]
	v_mfma_f32_16x16x128_f8f6f4 v[34:37], v[26:33], v[220:227], v[34:37]
	v_mfma_f32_16x16x128_f8f6f4 v[42:45], v[26:33], v[212:219], v[42:45]
	v_mfma_f32_16x16x128_f8f6f4 v[46:49], v[18:25], v[212:219], v[46:49]
	v_mfma_f32_16x16x128_f8f6f4 v[54:57], v[18:25], v[204:211], v[54:57]
	v_mfma_f32_16x16x128_f8f6f4 v[50:53], v[26:33], v[204:211], v[50:53]
	v_mfma_f32_16x16x128_f8f6f4 v[58:61], v[26:33], v[196:203], v[58:61]
	v_mfma_f32_16x16x128_f8f6f4 v[62:65], v[18:25], v[196:203], v[62:65]
	s_barrier
	s_setprio 0
	ds_read_b128 v[2:5], v188 offset:32768
	ds_read_b128 v[6:9], v188 offset:33792
	ds_read_b128 v[10:13], v188 offset:34816
	ds_read_b128 v[14:17], v188 offset:35840
	ds_read_b128 v[18:21], v188 offset:49152
	ds_read_b128 v[22:25], v188 offset:50176
	ds_read_b128 v[26:29], v188 offset:51200
	ds_read_b128 v[30:33], v188 offset:52224
	s_add_u32 s62, s84, 0x10000
	s_addc_u32 s63, s85, 0
	s_mov_b32 m0, s87
	v_lshl_add_u64 v[228:229], s[62:63], 0, v[166:167]
	ds_read_b128 v[196:199], v189 offset:32768
	ds_read_b128 v[200:203], v189 offset:33792
	ds_read_b128 v[204:207], v189 offset:34816
	ds_read_b128 v[208:211], v189 offset:35840
	ds_read_b128 v[212:215], v189 offset:36864
	ds_read_b128 v[216:219], v189 offset:37888
	ds_read_b128 v[220:223], v189 offset:38912
	ds_read_b128 v[224:227], v189 offset:39936
	global_load_lds_dwordx4 v[228:229], off
	v_lshl_add_u64 v[228:229], s[62:63], 0, v[168:169]
	s_mov_b32 m0, s88
	s_nop 0
	global_load_lds_dwordx4 v[228:229], off
	s_waitcnt vmcnt(8)
	s_waitcnt lgkmcnt(0)
	s_setprio 1
	s_barrier
	v_mfma_f32_16x16x128_f8f6f4 v[158:161], v[2:9], v[196:203], v[158:161]
	v_mfma_f32_16x16x128_f8f6f4 v[154:157], v[10:17], v[196:203], v[154:157]
	v_mfma_f32_16x16x128_f8f6f4 v[146:149], v[10:17], v[204:211], v[146:149]
	v_mfma_f32_16x16x128_f8f6f4 v[150:153], v[2:9], v[204:211], v[150:153]
	v_mfma_f32_16x16x128_f8f6f4 v[142:145], v[2:9], v[212:219], v[142:145]
	v_mfma_f32_16x16x128_f8f6f4 v[138:141], v[10:17], v[212:219], v[138:141]
	v_mfma_f32_16x16x128_f8f6f4 v[130:133], v[10:17], v[220:227], v[130:133]
	v_mfma_f32_16x16x128_f8f6f4 v[134:137], v[2:9], v[220:227], v[134:137]
	s_setprio 0
	s_setprio 1
	v_mfma_f32_16x16x128_f8f6f4 v[102:105], v[18:25], v[220:227], v[102:105]
	v_mfma_f32_16x16x128_f8f6f4 v[98:101], v[26:33], v[220:227], v[98:101]
	v_mfma_f32_16x16x128_f8f6f4 v[106:109], v[26:33], v[212:219], v[106:109]
	v_mfma_f32_16x16x128_f8f6f4 v[110:113], v[18:25], v[212:219], v[110:113]
	v_mfma_f32_16x16x128_f8f6f4 v[118:121], v[18:25], v[204:211], v[118:121]
	v_mfma_f32_16x16x128_f8f6f4 v[114:117], v[26:33], v[204:211], v[114:117]
	v_mfma_f32_16x16x128_f8f6f4 v[122:125], v[26:33], v[196:203], v[122:125]
	v_mfma_f32_16x16x128_f8f6f4 v[126:129], v[18:25], v[196:203], v[126:129]
	s_barrier
	s_setprio 0
	s_mov_b32 m0, s89
	v_lshl_add_u64 v[174:175], v[174:175], 0, s[40:41]
	s_add_u32 s62, s82, 0x10080
	ds_read_b128 v[196:199], v189 offset:49152
	ds_read_b128 v[200:203], v189 offset:50176
	ds_read_b128 v[204:207], v189 offset:51200
	ds_read_b128 v[208:211], v189 offset:52224
	ds_read_b128 v[212:215], v189 offset:53248
	ds_read_b128 v[216:219], v189 offset:54272
	ds_read_b128 v[220:223], v189 offset:55296
	ds_read_b128 v[224:227], v189 offset:56320
	global_load_lds_dwordx4 v[174:175], off
	v_lshl_add_u64 v[174:175], v[176:177], 0, s[40:41]
	s_mov_b32 m0, s90
	s_addc_u32 s63, s83, 0
	global_load_lds_dwordx4 v[174:175], off
	v_lshl_add_u64 v[174:175], s[62:63], 0, v[162:163]
	s_mov_b32 m0, s93
	s_nop 0
	global_load_lds_dwordx4 v[174:175], off
	v_lshl_add_u64 v[174:175], s[62:63], 0, v[164:165]
	s_mov_b32 m0, s95
	s_nop 0
	global_load_lds_dwordx4 v[174:175], off
	v_lshl_add_u64 v[174:175], v[182:183], 0, s[40:41]
	s_mov_b32 m0, s91
	s_nop 0
	global_load_lds_dwordx4 v[174:175], off
	v_lshl_add_u64 v[174:175], v[184:185], 0, s[40:41]
	s_mov_b32 m0, s92
	s_nop 0
	global_load_lds_dwordx4 v[174:175], off
	s_waitcnt vmcnt(8)
	s_waitcnt lgkmcnt(0)
	s_setprio 1
	s_barrier
	v_mfma_f32_16x16x128_f8f6f4 v[94:97], v[2:9], v[196:203], v[94:97]
	v_mfma_f32_16x16x128_f8f6f4 v[90:93], v[10:17], v[196:203], v[90:93]
	v_mfma_f32_16x16x128_f8f6f4 v[82:85], v[10:17], v[204:211], v[82:85]
	v_mfma_f32_16x16x128_f8f6f4 v[86:89], v[2:9], v[204:211], v[86:89]
	v_mfma_f32_16x16x128_f8f6f4 v[78:81], v[2:9], v[212:219], v[78:81]
	v_mfma_f32_16x16x128_f8f6f4 v[74:77], v[10:17], v[212:219], v[74:77]
	v_mfma_f32_16x16x128_f8f6f4 v[66:69], v[10:17], v[220:227], v[66:69]
	v_mfma_f32_16x16x128_f8f6f4 v[70:73], v[2:9], v[220:227], v[70:73]
	s_setprio 0
	s_setprio 1
	v_mfma_f32_16x16x128_f8f6f4 v[38:41], v[18:25], v[220:227], v[38:41]
	v_mfma_f32_16x16x128_f8f6f4 v[34:37], v[26:33], v[220:227], v[34:37]
	v_mfma_f32_16x16x128_f8f6f4 v[42:45], v[26:33], v[212:219], v[42:45]
	v_mfma_f32_16x16x128_f8f6f4 v[46:49], v[18:25], v[212:219], v[46:49]
	v_mfma_f32_16x16x128_f8f6f4 v[54:57], v[18:25], v[204:211], v[54:57]
	v_mfma_f32_16x16x128_f8f6f4 v[50:53], v[26:33], v[204:211], v[50:53]
	v_mfma_f32_16x16x128_f8f6f4 v[58:61], v[26:33], v[196:203], v[58:61]
	v_mfma_f32_16x16x128_f8f6f4 v[62:65], v[18:25], v[196:203], v[62:65]
	s_barrier
	s_setprio 0
	s_andn2_b64 vcc, exec, s[42:43]
	s_cbranch_vccnz .LBB0_618
	s_barrier

.LBB0_630:
	s_ashr_i32 s54, s48, 1
	s_ashr_i32 s51, s50, 31
	s_ashr_i32 s55, s54, 31
	s_lshl_b64 s[52:53], s[50:51], 19
	s_lshl_b64 s[54:55], s[54:55], 9
	s_waitcnt vmcnt(0)
	ds_read_b128 v[18:21], v181
	ds_read_b128 v[22:25], v181 offset:1024
	ds_read_b128 v[26:29], v181 offset:2048
	ds_read_b128 v[30:33], v181 offset:3072
	ds_read_b128 v[2:5], v181 offset:16384
	ds_read_b128 v[6:9], v181 offset:17408
	ds_read_b128 v[10:13], v181 offset:18432
	ds_read_b128 v[14:17], v181 offset:19456
	s_add_u32 s5, s26, s52
	s_addc_u32 s33, s27, s53
	s_add_u32 s52, s5, s54
	s_addc_u32 s53, s33, s55
	s_and_b64 s[54:55], s[2:3], exec
	s_cselect_b32 s81, s53, s75
	s_cselect_b32 s80, s52, s74
	s_ashr_i32 s49, s48, 31
	s_lshl_b64 s[54:55], s[48:49], 17
	v_readlane_b32 s5, v254, 9
	s_add_u32 s54, s5, s54
	v_readlane_b32 s5, v254, 10
	s_addc_u32 s55, s5, s55
	s_and_b64 s[62:63], s[2:3], exec
	s_cselect_b32 s79, s55, s77
	s_cselect_b32 s78, s54, s76
	s_add_u32 s62, s74, 0x40080
	s_addc_u32 s63, s75, 0
	s_add_i32 s33, s8, 0xc000
	v_lshl_add_u64 v[174:175], s[62:63], 0, v[166:167]
	s_mov_b32 m0, s33
	s_add_i32 s5, s8, 0xe000
	ds_read_b128 v[190:193], v187
	ds_read_b128 v[194:197], v187 offset:1024
	ds_read_b128 v[198:201], v187 offset:2048
	ds_read_b128 v[202:205], v187 offset:3072
	ds_read_b128 v[206:209], v187 offset:4096
	ds_read_b128 v[210:213], v187 offset:5120
	ds_read_b128 v[214:217], v187 offset:6144
	ds_read_b128 v[218:221], v187 offset:7168
	global_load_lds_dwordx4 v[174:175], off
	v_lshl_add_u64 v[174:175], s[62:63], 0, v[168:169]
	s_mov_b32 m0, s5
	s_nop 0
	global_load_lds_dwordx4 v[174:175], off
	s_waitcnt vmcnt(8)
	s_waitcnt lgkmcnt(0)
	s_setprio 1
	s_barrier
	v_mfma_f32_16x16x128_f8f6f4 v[158:161], v[18:25], v[190:197], 0
	v_mfma_f32_16x16x128_f8f6f4 v[154:157], v[26:33], v[190:197], 0
	v_mfma_f32_16x16x128_f8f6f4 v[146:149], v[26:33], v[198:205], 0
	v_mfma_f32_16x16x128_f8f6f4 v[150:153], v[18:25], v[198:205], 0
	v_mfma_f32_16x16x128_f8f6f4 v[142:145], v[18:25], v[206:213], 0
	v_mfma_f32_16x16x128_f8f6f4 v[138:141], v[26:33], v[206:213], 0
	v_mfma_f32_16x16x128_f8f6f4 v[130:133], v[26:33], v[214:221], 0
	v_mfma_f32_16x16x128_f8f6f4 v[134:137], v[18:25], v[214:221], 0
	s_setprio 0
	s_setprio 1
	v_mfma_f32_16x16x128_f8f6f4 v[102:105], v[2:9], v[214:221], 0
	v_mfma_f32_16x16x128_f8f6f4 v[98:101], v[10:17], v[214:221], 0
	v_mfma_f32_16x16x128_f8f6f4 v[106:109], v[10:17], v[206:213], 0
	v_mfma_f32_16x16x128_f8f6f4 v[110:113], v[2:9], v[206:213], 0
	v_mfma_f32_16x16x128_f8f6f4 v[118:121], v[2:9], v[198:205], 0
	v_mfma_f32_16x16x128_f8f6f4 v[114:117], v[10:17], v[198:205], 0
	v_mfma_f32_16x16x128_f8f6f4 v[122:125], v[10:17], v[190:197], 0
	v_mfma_f32_16x16x128_f8f6f4 v[126:129], v[2:9], v[190:197], 0
	s_barrier
	s_setprio 0
	v_lshl_add_u64 v[174:175], s[76:77], 0, v[162:163]
	s_mov_b32 m0, s9
	v_lshl_add_u64 v[176:177], v[174:175], 0, s[44:45]
	ds_read_b128 v[190:193], v187 offset:16384
	ds_read_b128 v[194:197], v187 offset:17408
	ds_read_b128 v[198:201], v187 offset:18432
	ds_read_b128 v[202:205], v187 offset:19456
	ds_read_b128 v[206:209], v187 offset:20480
	ds_read_b128 v[210:213], v187 offset:21504
	ds_read_b128 v[214:217], v187 offset:22528
	ds_read_b128 v[218:221], v187 offset:23552
	global_load_lds_dwordx4 v[176:177], off
	v_lshl_add_u64 v[176:177], s[76:77], 0, v[164:165]
	s_add_u32 s62, s76, 0x10100
	v_lshl_add_u64 v[182:183], v[176:177], 0, s[44:45]
	s_mov_b32 m0, s61
	s_addc_u32 s63, s77, 0
	global_load_lds_dwordx4 v[182:183], off
	v_lshl_add_u64 v[182:183], s[62:63], 0, v[162:163]
	s_mov_b32 m0, s68
	s_nop 0
	global_load_lds_dwordx4 v[182:183], off
	v_lshl_add_u64 v[182:183], s[62:63], 0, v[164:165]
	s_mov_b32 m0, s69
	s_nop 0
	global_load_lds_dwordx4 v[182:183], off
	v_lshl_add_u64 v[182:183], s[74:75], 0, v[166:167]
	v_lshl_add_u64 v[184:185], v[182:183], 0, s[44:45]
	s_mov_b32 m0, s8
	s_nop 0
	global_load_lds_dwordx4 v[184:185], off
	v_lshl_add_u64 v[184:185], s[74:75], 0, v[168:169]
	v_lshl_add_u64 v[222:223], v[184:185], 0, s[44:45]
	s_mov_b32 m0, s71
	s_nop 0
	global_load_lds_dwordx4 v[222:223], off
	s_waitcnt vmcnt(8)
	s_waitcnt lgkmcnt(0)
	s_setprio 1
	s_barrier
	v_mfma_f32_16x16x128_f8f6f4 v[94:97], v[18:25], v[190:197], 0
	v_mfma_f32_16x16x128_f8f6f4 v[90:93], v[26:33], v[190:197], 0
	v_mfma_f32_16x16x128_f8f6f4 v[82:85], v[26:33], v[198:205], 0
	v_mfma_f32_16x16x128_f8f6f4 v[86:89], v[18:25], v[198:205], 0
	v_mfma_f32_16x16x128_f8f6f4 v[78:81], v[18:25], v[206:213], 0
	v_mfma_f32_16x16x128_f8f6f4 v[74:77], v[26:33], v[206:213], 0
	v_mfma_f32_16x16x128_f8f6f4 v[66:69], v[26:33], v[214:221], 0
	v_mfma_f32_16x16x128_f8f6f4 v[70:73], v[18:25], v[214:221], 0
	s_setprio 0
	s_setprio 1
	v_mfma_f32_16x16x128_f8f6f4 v[38:41], v[2:9], v[214:221], 0
	v_mfma_f32_16x16x128_f8f6f4 v[34:37], v[10:17], v[214:221], 0
	v_mfma_f32_16x16x128_f8f6f4 v[42:45], v[10:17], v[206:213], 0
	v_mfma_f32_16x16x128_f8f6f4 v[46:49], v[2:9], v[206:213], 0
	v_mfma_f32_16x16x128_f8f6f4 v[54:57], v[2:9], v[198:205], 0
	v_mfma_f32_16x16x128_f8f6f4 v[50:53], v[10:17], v[198:205], 0
	v_mfma_f32_16x16x128_f8f6f4 v[58:61], v[10:17], v[190:197], 0
	v_mfma_f32_16x16x128_f8f6f4 v[62:65], v[2:9], v[190:197], 0
	s_barrier
	s_setprio 0
	ds_read_b128 v[2:5], v181 offset:32768
	ds_read_b128 v[6:9], v181 offset:33792
	ds_read_b128 v[10:13], v181 offset:34816
	ds_read_b128 v[14:17], v181 offset:35840
	ds_read_b128 v[18:21], v181 offset:49152
	ds_read_b128 v[22:25], v181 offset:50176
	ds_read_b128 v[26:29], v181 offset:51200
	ds_read_b128 v[30:33], v181 offset:52224
	s_add_u32 s62, s74, 0x40100
	s_addc_u32 s63, s75, 0
	s_mov_b32 m0, s73
	v_lshl_add_u64 v[222:223], s[62:63], 0, v[166:167]
	ds_read_b128 v[190:193], v187 offset:32768
	ds_read_b128 v[194:197], v187 offset:33792
	ds_read_b128 v[198:201], v187 offset:34816
	ds_read_b128 v[202:205], v187 offset:35840
	ds_read_b128 v[206:209], v187 offset:36864
	ds_read_b128 v[210:213], v187 offset:37888
	ds_read_b128 v[214:217], v187 offset:38912
	ds_read_b128 v[218:221], v187 offset:39936
	global_load_lds_dwordx4 v[222:223], off
	v_lshl_add_u64 v[222:223], s[62:63], 0, v[168:169]
	s_mov_b32 m0, s82
	s_nop 0
	global_load_lds_dwordx4 v[222:223], off
	s_waitcnt vmcnt(8)
	s_waitcnt lgkmcnt(0)
	s_setprio 1
	s_barrier
	v_mfma_f32_16x16x128_f8f6f4 v[158:161], v[2:9], v[190:197], v[158:161]
	v_mfma_f32_16x16x128_f8f6f4 v[154:157], v[10:17], v[190:197], v[154:157]
	v_mfma_f32_16x16x128_f8f6f4 v[146:149], v[10:17], v[198:205], v[146:149]
	v_mfma_f32_16x16x128_f8f6f4 v[150:153], v[2:9], v[198:205], v[150:153]
	v_mfma_f32_16x16x128_f8f6f4 v[142:145], v[2:9], v[206:213], v[142:145]
	v_mfma_f32_16x16x128_f8f6f4 v[138:141], v[10:17], v[206:213], v[138:141]
	v_mfma_f32_16x16x128_f8f6f4 v[130:133], v[10:17], v[214:221], v[130:133]
	v_mfma_f32_16x16x128_f8f6f4 v[134:137], v[2:9], v[214:221], v[134:137]
	s_setprio 0
	s_setprio 1
	v_mfma_f32_16x16x128_f8f6f4 v[102:105], v[18:25], v[214:221], v[102:105]
	v_mfma_f32_16x16x128_f8f6f4 v[98:101], v[26:33], v[214:221], v[98:101]
	v_mfma_f32_16x16x128_f8f6f4 v[106:109], v[26:33], v[206:213], v[106:109]
	v_mfma_f32_16x16x128_f8f6f4 v[110:113], v[18:25], v[206:213], v[110:113]
	v_mfma_f32_16x16x128_f8f6f4 v[118:121], v[18:25], v[198:205], v[118:121]
	v_mfma_f32_16x16x128_f8f6f4 v[114:117], v[26:33], v[198:205], v[114:117]
	v_mfma_f32_16x16x128_f8f6f4 v[122:125], v[26:33], v[190:197], v[122:125]
	v_mfma_f32_16x16x128_f8f6f4 v[126:129], v[18:25], v[190:197], v[126:129]
	s_barrier
	s_setprio 0
	s_mov_b32 m0, s83
	v_lshl_add_u64 v[174:175], v[174:175], 0, s[46:47]
	s_add_u32 s62, s76, 0x10180
	ds_read_b128 v[190:193], v187 offset:49152
	ds_read_b128 v[194:197], v187 offset:50176
	ds_read_b128 v[198:201], v187 offset:51200
	ds_read_b128 v[202:205], v187 offset:52224
	ds_read_b128 v[206:209], v187 offset:53248
	ds_read_b128 v[210:213], v187 offset:54272
	ds_read_b128 v[214:217], v187 offset:55296
	ds_read_b128 v[218:221], v187 offset:56320
	global_load_lds_dwordx4 v[174:175], off
	v_lshl_add_u64 v[174:175], v[176:177], 0, s[46:47]
	s_mov_b32 m0, s84
	s_addc_u32 s63, s77, 0
	global_load_lds_dwordx4 v[174:175], off
	v_lshl_add_u64 v[174:175], s[62:63], 0, v[162:163]
	s_mov_b32 m0, s87
	s_nop 0
	global_load_lds_dwordx4 v[174:175], off
	v_lshl_add_u64 v[174:175], s[62:63], 0, v[164:165]
	s_mov_b32 m0, s88
	s_nop 0
	global_load_lds_dwordx4 v[174:175], off
	v_lshl_add_u64 v[174:175], v[182:183], 0, s[46:47]
	s_mov_b32 m0, s85
	s_nop 0
	global_load_lds_dwordx4 v[174:175], off
	v_lshl_add_u64 v[174:175], v[184:185], 0, s[46:47]
	s_mov_b32 m0, s86
	s_nop 0
	global_load_lds_dwordx4 v[174:175], off
	s_waitcnt vmcnt(8)
	s_waitcnt lgkmcnt(0)
	s_setprio 1
	s_barrier
	v_mfma_f32_16x16x128_f8f6f4 v[94:97], v[2:9], v[190:197], v[94:97]
	v_mfma_f32_16x16x128_f8f6f4 v[90:93], v[10:17], v[190:197], v[90:93]
	v_mfma_f32_16x16x128_f8f6f4 v[82:85], v[10:17], v[198:205], v[82:85]
	v_mfma_f32_16x16x128_f8f6f4 v[86:89], v[2:9], v[198:205], v[86:89]
	v_mfma_f32_16x16x128_f8f6f4 v[78:81], v[2:9], v[206:213], v[78:81]
	v_mfma_f32_16x16x128_f8f6f4 v[74:77], v[10:17], v[206:213], v[74:77]
	v_mfma_f32_16x16x128_f8f6f4 v[66:69], v[10:17], v[214:221], v[66:69]
	v_mfma_f32_16x16x128_f8f6f4 v[70:73], v[2:9], v[214:221], v[70:73]
	s_setprio 0
	s_setprio 1
	v_mfma_f32_16x16x128_f8f6f4 v[38:41], v[18:25], v[214:221], v[38:41]
	v_mfma_f32_16x16x128_f8f6f4 v[34:37], v[26:33], v[214:221], v[34:37]
	v_mfma_f32_16x16x128_f8f6f4 v[42:45], v[26:33], v[206:213], v[42:45]
	v_mfma_f32_16x16x128_f8f6f4 v[46:49], v[18:25], v[206:213], v[46:49]
	v_mfma_f32_16x16x128_f8f6f4 v[54:57], v[18:25], v[198:205], v[54:57]
	v_mfma_f32_16x16x128_f8f6f4 v[50:53], v[26:33], v[198:205], v[50:53]
	v_mfma_f32_16x16x128_f8f6f4 v[58:61], v[26:33], v[190:197], v[58:61]
	v_mfma_f32_16x16x128_f8f6f4 v[62:65], v[18:25], v[190:197], v[62:65]
	s_barrier
	s_setprio 0
	ds_read_b128 v[2:5], v181
	ds_read_b128 v[6:9], v181 offset:1024
	ds_read_b128 v[10:13], v181 offset:2048
	ds_read_b128 v[14:17], v181 offset:3072
	ds_read_b128 v[18:21], v181 offset:16384
	ds_read_b128 v[22:25], v181 offset:17408
	ds_read_b128 v[26:29], v181 offset:18432
	ds_read_b128 v[30:33], v181 offset:19456
	s_add_u32 s62, s74, 0x40180
	s_addc_u32 s63, s75, 0
	s_mov_b32 m0, s33
	v_lshl_add_u64 v[174:175], s[62:63], 0, v[166:167]
	ds_read_b128 v[190:193], v187
	ds_read_b128 v[194:197], v187 offset:1024
	ds_read_b128 v[198:201], v187 offset:2048
	ds_read_b128 v[202:205], v187 offset:3072
	ds_read_b128 v[206:209], v187 offset:4096
	ds_read_b128 v[210:213], v187 offset:5120
	ds_read_b128 v[214:217], v187 offset:6144
	ds_read_b128 v[218:221], v187 offset:7168
	global_load_lds_dwordx4 v[174:175], off
	v_lshl_add_u64 v[174:175], s[62:63], 0, v[168:169]
	s_mov_b32 m0, s5
	s_nop 0
	global_load_lds_dwordx4 v[174:175], off
	s_waitcnt vmcnt(8)
	s_waitcnt lgkmcnt(0)
	s_setprio 1
	s_barrier
	v_mfma_f32_16x16x128_f8f6f4 v[158:161], v[2:9], v[190:197], v[158:161]
	v_mfma_f32_16x16x128_f8f6f4 v[154:157], v[10:17], v[190:197], v[154:157]
	v_mfma_f32_16x16x128_f8f6f4 v[146:149], v[10:17], v[198:205], v[146:149]
	v_mfma_f32_16x16x128_f8f6f4 v[150:153], v[2:9], v[198:205], v[150:153]
	v_mfma_f32_16x16x128_f8f6f4 v[142:145], v[2:9], v[206:213], v[142:145]
	v_mfma_f32_16x16x128_f8f6f4 v[138:141], v[10:17], v[206:213], v[138:141]
	v_mfma_f32_16x16x128_f8f6f4 v[130:133], v[10:17], v[214:221], v[130:133]
	v_mfma_f32_16x16x128_f8f6f4 v[134:137], v[2:9], v[214:221], v[134:137]
	s_setprio 0
	s_setprio 1
	v_mfma_f32_16x16x128_f8f6f4 v[102:105], v[18:25], v[214:221], v[102:105]
	v_mfma_f32_16x16x128_f8f6f4 v[98:101], v[26:33], v[214:221], v[98:101]
	v_mfma_f32_16x16x128_f8f6f4 v[106:109], v[26:33], v[206:213], v[106:109]
	v_mfma_f32_16x16x128_f8f6f4 v[110:113], v[18:25], v[206:213], v[110:113]
	v_mfma_f32_16x16x128_f8f6f4 v[118:121], v[18:25], v[198:205], v[118:121]
	v_mfma_f32_16x16x128_f8f6f4 v[114:117], v[26:33], v[198:205], v[114:117]
	v_mfma_f32_16x16x128_f8f6f4 v[122:125], v[26:33], v[190:197], v[122:125]
	v_mfma_f32_16x16x128_f8f6f4 v[126:129], v[18:25], v[190:197], v[126:129]
	s_barrier
	s_setprio 0
	s_mov_b32 m0, s9
	v_lshl_add_u64 v[174:175], s[78:79], 0, v[162:163]
	s_add_u32 s62, s78, 0x10000
	ds_read_b128 v[190:193], v187 offset:16384
	ds_read_b128 v[194:197], v187 offset:17408
	ds_read_b128 v[198:201], v187 offset:18432
	ds_read_b128 v[202:205], v187 offset:19456
	ds_read_b128 v[206:209], v187 offset:20480
	ds_read_b128 v[210:213], v187 offset:21504
	ds_read_b128 v[214:217], v187 offset:22528
	ds_read_b128 v[218:221], v187 offset:23552
	global_load_lds_dwordx4 v[174:175], off
	v_lshl_add_u64 v[176:177], s[78:79], 0, v[164:165]
	s_mov_b32 m0, s61
	s_addc_u32 s63, s79, 0
	global_load_lds_dwordx4 v[176:177], off
	v_lshl_add_u64 v[182:183], s[62:63], 0, v[162:163]
	s_mov_b32 m0, s68
	v_lshl_add_u64 v[184:185], s[80:81], 0, v[168:169]
	global_load_lds_dwordx4 v[182:183], off
	v_lshl_add_u64 v[182:183], s[62:63], 0, v[164:165]
	s_mov_b32 m0, s69
	s_nop 0
	global_load_lds_dwordx4 v[182:183], off
	v_lshl_add_u64 v[182:183], s[80:81], 0, v[166:167]
	s_mov_b32 m0, s8
	s_nop 0
	global_load_lds_dwordx4 v[182:183], off
	s_mov_b32 m0, s71
	s_nop 0
	global_load_lds_dwordx4 v[184:185], off
	s_waitcnt vmcnt(8)
	s_waitcnt lgkmcnt(0)
	s_setprio 1
	s_barrier
	v_mfma_f32_16x16x128_f8f6f4 v[94:97], v[2:9], v[190:197], v[94:97]
	v_mfma_f32_16x16x128_f8f6f4 v[90:93], v[10:17], v[190:197], v[90:93]
	v_mfma_f32_16x16x128_f8f6f4 v[82:85], v[10:17], v[198:205], v[82:85]
	v_mfma_f32_16x16x128_f8f6f4 v[86:89], v[2:9], v[198:205], v[86:89]
	v_mfma_f32_16x16x128_f8f6f4 v[78:81], v[2:9], v[206:213], v[78:81]
	v_mfma_f32_16x16x128_f8f6f4 v[74:77], v[10:17], v[206:213], v[74:77]
	v_mfma_f32_16x16x128_f8f6f4 v[66:69], v[10:17], v[214:221], v[66:69]
	v_mfma_f32_16x16x128_f8f6f4 v[70:73], v[2:9], v[214:221], v[70:73]
	s_setprio 0
	s_setprio 1
	v_mfma_f32_16x16x128_f8f6f4 v[38:41], v[18:25], v[214:221], v[38:41]
	v_mfma_f32_16x16x128_f8f6f4 v[34:37], v[26:33], v[214:221], v[34:37]
	v_mfma_f32_16x16x128_f8f6f4 v[42:45], v[26:33], v[206:213], v[42:45]
	v_mfma_f32_16x16x128_f8f6f4 v[46:49], v[18:25], v[206:213], v[46:49]
	v_mfma_f32_16x16x128_f8f6f4 v[54:57], v[18:25], v[198:205], v[54:57]
	v_mfma_f32_16x16x128_f8f6f4 v[50:53], v[26:33], v[198:205], v[50:53]
	v_mfma_f32_16x16x128_f8f6f4 v[58:61], v[26:33], v[190:197], v[58:61]
	v_mfma_f32_16x16x128_f8f6f4 v[62:65], v[18:25], v[190:197], v[62:65]
	s_barrier
	s_setprio 0
	ds_read_b128 v[2:5], v181 offset:32768
	ds_read_b128 v[6:9], v181 offset:33792
	ds_read_b128 v[10:13], v181 offset:34816
	ds_read_b128 v[14:17], v181 offset:35840
	ds_read_b128 v[18:21], v181 offset:49152
	ds_read_b128 v[22:25], v181 offset:50176
	ds_read_b128 v[26:29], v181 offset:51200
	ds_read_b128 v[30:33], v181 offset:52224
	s_add_u32 s62, s80, 0x40000
	s_addc_u32 s63, s81, 0
	s_mov_b32 m0, s73
	v_lshl_add_u64 v[222:223], s[62:63], 0, v[166:167]
	ds_read_b128 v[190:193], v187 offset:32768
	ds_read_b128 v[194:197], v187 offset:33792
	ds_read_b128 v[198:201], v187 offset:34816
	ds_read_b128 v[202:205], v187 offset:35840
	ds_read_b128 v[206:209], v187 offset:36864
	ds_read_b128 v[210:213], v187 offset:37888
	ds_read_b128 v[214:217], v187 offset:38912
	ds_read_b128 v[218:221], v187 offset:39936
	global_load_lds_dwordx4 v[222:223], off
	v_lshl_add_u64 v[222:223], s[62:63], 0, v[168:169]
	s_mov_b32 m0, s82
	s_nop 0
	global_load_lds_dwordx4 v[222:223], off
	s_waitcnt vmcnt(8)
	s_waitcnt lgkmcnt(0)
	s_setprio 1
	s_barrier
	v_mfma_f32_16x16x128_f8f6f4 v[158:161], v[2:9], v[190:197], v[158:161]
	v_mfma_f32_16x16x128_f8f6f4 v[154:157], v[10:17], v[190:197], v[154:157]
	v_mfma_f32_16x16x128_f8f6f4 v[146:149], v[10:17], v[198:205], v[146:149]
	v_mfma_f32_16x16x128_f8f6f4 v[150:153], v[2:9], v[198:205], v[150:153]
	v_mfma_f32_16x16x128_f8f6f4 v[142:145], v[2:9], v[206:213], v[142:145]
	v_mfma_f32_16x16x128_f8f6f4 v[138:141], v[10:17], v[206:213], v[138:141]
	v_mfma_f32_16x16x128_f8f6f4 v[130:133], v[10:17], v[214:221], v[130:133]
	v_mfma_f32_16x16x128_f8f6f4 v[134:137], v[2:9], v[214:221], v[134:137]
	s_setprio 0
	s_setprio 1
	v_mfma_f32_16x16x128_f8f6f4 v[102:105], v[18:25], v[214:221], v[102:105]
	v_mfma_f32_16x16x128_f8f6f4 v[98:101], v[26:33], v[214:221], v[98:101]
	v_mfma_f32_16x16x128_f8f6f4 v[106:109], v[26:33], v[206:213], v[106:109]
	v_mfma_f32_16x16x128_f8f6f4 v[110:113], v[18:25], v[206:213], v[110:113]
	v_mfma_f32_16x16x128_f8f6f4 v[118:121], v[18:25], v[198:205], v[118:121]
	v_mfma_f32_16x16x128_f8f6f4 v[114:117], v[26:33], v[198:205], v[114:117]
	v_mfma_f32_16x16x128_f8f6f4 v[122:125], v[26:33], v[190:197], v[122:125]
	v_mfma_f32_16x16x128_f8f6f4 v[126:129], v[18:25], v[190:197], v[126:129]
	s_barrier
	s_setprio 0
	s_mov_b32 m0, s83
	v_lshl_add_u64 v[174:175], v[174:175], 0, s[38:39]
	s_add_u32 s62, s78, 0x10080
	ds_read_b128 v[190:193], v187 offset:49152
	ds_read_b128 v[194:197], v187 offset:50176
	ds_read_b128 v[198:201], v187 offset:51200
	ds_read_b128 v[202:205], v187 offset:52224
	ds_read_b128 v[206:209], v187 offset:53248
	ds_read_b128 v[210:213], v187 offset:54272
	ds_read_b128 v[214:217], v187 offset:55296
	ds_read_b128 v[218:221], v187 offset:56320
	global_load_lds_dwordx4 v[174:175], off
	v_lshl_add_u64 v[174:175], v[176:177], 0, s[38:39]
	s_mov_b32 m0, s84
	s_addc_u32 s63, s79, 0
	global_load_lds_dwordx4 v[174:175], off
	v_lshl_add_u64 v[174:175], s[62:63], 0, v[162:163]
	s_mov_b32 m0, s87
	s_nop 0
	global_load_lds_dwordx4 v[174:175], off
	v_lshl_add_u64 v[174:175], s[62:63], 0, v[164:165]
	s_mov_b32 m0, s88
	s_nop 0
	global_load_lds_dwordx4 v[174:175], off
	v_lshl_add_u64 v[174:175], v[182:183], 0, s[38:39]
	s_mov_b32 m0, s85
	s_nop 0
	global_load_lds_dwordx4 v[174:175], off
	v_lshl_add_u64 v[174:175], v[184:185], 0, s[38:39]
	s_mov_b32 m0, s86
	s_nop 0
	global_load_lds_dwordx4 v[174:175], off
	s_waitcnt vmcnt(8)
	s_waitcnt lgkmcnt(0)
	s_setprio 1
	s_barrier
	v_mfma_f32_16x16x128_f8f6f4 v[94:97], v[2:9], v[190:197], v[94:97]
	v_mfma_f32_16x16x128_f8f6f4 v[90:93], v[10:17], v[190:197], v[90:93]
	v_mfma_f32_16x16x128_f8f6f4 v[82:85], v[10:17], v[198:205], v[82:85]
	v_mfma_f32_16x16x128_f8f6f4 v[86:89], v[2:9], v[198:205], v[86:89]
	v_mfma_f32_16x16x128_f8f6f4 v[78:81], v[2:9], v[206:213], v[78:81]
	v_mfma_f32_16x16x128_f8f6f4 v[74:77], v[10:17], v[206:213], v[74:77]
	v_mfma_f32_16x16x128_f8f6f4 v[66:69], v[10:17], v[214:221], v[66:69]
	v_mfma_f32_16x16x128_f8f6f4 v[70:73], v[2:9], v[214:221], v[70:73]
	s_setprio 0
	s_setprio 1
	v_mfma_f32_16x16x128_f8f6f4 v[38:41], v[18:25], v[214:221], v[38:41]
	v_mfma_f32_16x16x128_f8f6f4 v[34:37], v[26:33], v[214:221], v[34:37]
	v_mfma_f32_16x16x128_f8f6f4 v[42:45], v[26:33], v[206:213], v[42:45]
	v_mfma_f32_16x16x128_f8f6f4 v[46:49], v[18:25], v[206:213], v[46:49]
	v_mfma_f32_16x16x128_f8f6f4 v[54:57], v[18:25], v[198:205], v[54:57]
	v_mfma_f32_16x16x128_f8f6f4 v[50:53], v[26:33], v[198:205], v[50:53]
	v_mfma_f32_16x16x128_f8f6f4 v[58:61], v[26:33], v[190:197], v[58:61]
	v_mfma_f32_16x16x128_f8f6f4 v[62:65], v[18:25], v[190:197], v[62:65]
	s_barrier
	s_setprio 0
	s_andn2_b64 vcc, exec, s[40:41]
	s_cbranch_vccnz .LBB0_632
	s_barrier

.LBB0_791:
	ds_read_b128 v[2:5], v189
	ds_read_b128 v[6:9], v189 offset:1024
	ds_read_b128 v[192:195], v189 offset:2048
	ds_read_b128 v[196:199], v189 offset:3072
	ds_read_b128 v[200:203], v189 offset:16384
	ds_read_b128 v[204:207], v189 offset:17408
	ds_read_b128 v[208:211], v189 offset:18432
	ds_read_b128 v[212:215], v189 offset:19456
	s_add_u32 s37, s46, 0x100
	s_addc_u32 s39, s47, 0
	s_and_b64 s[50:51], s[48:49], exec
	s_cselect_b32 s51, s1, s39
	s_cselect_b32 s50, s0, s37
	s_add_u32 s37, s44, 0x100
	s_addc_u32 s39, s45, 0
	s_and_b64 s[48:49], s[48:49], exec
	s_cselect_b32 s49, s5, s39
	s_cselect_b32 s48, s4, s37
	s_add_u32 s88, s46, 0x80080
	s_addc_u32 s89, s47, 0
	s_add_i32 s37, s8, 0xc000
	v_lshl_add_u64 v[174:175], s[88:89], 0, v[154:155]
	s_mov_b32 m0, s37
	s_add_i32 s39, s8, 0xe000
	ds_read_b128 v[216:219], v190
	ds_read_b128 v[220:223], v190 offset:1024
	ds_read_b128 v[224:227], v190 offset:2048
	ds_read_b128 v[228:231], v190 offset:3072
	ds_read_b128 v[242:245], v190 offset:4096
	ds_read_b128 v[246:249], v190 offset:5120
	ds_read_b128 v[232:235], v190 offset:6144
	ds_read_b128 v[236:239], v190 offset:7168
	global_load_lds_dwordx4 v[174:175], off
	v_lshl_add_u64 v[174:175], s[88:89], 0, v[158:159]
	s_mov_b32 m0, s39
	s_nop 0
	global_load_lds_dwordx4 v[174:175], off
	s_waitcnt vmcnt(8)
	s_waitcnt lgkmcnt(0)
	s_setprio 1
	s_barrier
	v_mfma_f32_16x16x128_f8f6f4 v[134:137], v[2:9], v[216:223], 0
	v_mfma_f32_16x16x128_f8f6f4 v[130:133], v[192:199], v[216:223], 0
	v_mfma_f32_16x16x128_f8f6f4 v[122:125], v[192:199], v[224:231], 0
	v_mfma_f32_16x16x128_f8f6f4 v[126:129], v[2:9], v[224:231], 0
	v_mfma_f32_16x16x128_f8f6f4 v[118:121], v[2:9], v[242:249], 0
	v_mfma_f32_16x16x128_f8f6f4 v[114:117], v[192:199], v[242:249], 0
	v_mfma_f32_16x16x128_f8f6f4 v[106:109], v[192:199], v[232:239], 0
	v_mfma_f32_16x16x128_f8f6f4 v[110:113], v[2:9], v[232:239], 0
	s_setprio 0
	s_setprio 1
	v_mfma_f32_16x16x128_f8f6f4 v[78:81], v[200:207], v[232:239], 0
	v_mfma_f32_16x16x128_f8f6f4 v[74:77], v[208:215], v[232:239], 0
	v_mfma_f32_16x16x128_f8f6f4 v[82:85], v[208:215], v[242:249], 0
	v_mfma_f32_16x16x128_f8f6f4 v[86:89], v[200:207], v[242:249], 0
	v_mfma_f32_16x16x128_f8f6f4 v[94:97], v[200:207], v[224:231], 0
	v_mfma_f32_16x16x128_f8f6f4 v[90:93], v[208:215], v[224:231], 0
	v_mfma_f32_16x16x128_f8f6f4 v[98:101], v[208:215], v[216:223], 0
	v_mfma_f32_16x16x128_f8f6f4 v[102:105], v[200:207], v[216:223], 0
	s_barrier
	s_setprio 0
	s_mov_b32 m0, s9
	v_lshl_add_u64 v[174:175], s[48:49], 0, v[156:157]
	s_add_u32 s88, s48, 0x80000
	ds_read_b128 v[216:219], v190 offset:16384
	ds_read_b128 v[220:223], v190 offset:17408
	ds_read_b128 v[224:227], v190 offset:18432
	ds_read_b128 v[228:231], v190 offset:19456
	ds_read_b128 v[232:235], v190 offset:20480
	ds_read_b128 v[236:239], v190 offset:21504
	ds_read_b128 v[242:245], v190 offset:22528
	ds_read_b128 v[246:249], v190 offset:23552
	global_load_lds_dwordx4 v[174:175], off
	v_lshl_add_u64 v[176:177], s[48:49], 0, v[160:161]
	s_mov_b32 m0, s27
	s_addc_u32 s89, s49, 0
	global_load_lds_dwordx4 v[176:177], off
	v_lshl_add_u64 v[182:183], s[88:89], 0, v[156:157]
	s_mov_b32 m0, s33
	v_lshl_add_u64 v[184:185], s[50:51], 0, v[158:159]
	global_load_lds_dwordx4 v[182:183], off
	v_lshl_add_u64 v[182:183], s[88:89], 0, v[160:161]
	s_mov_b32 m0, s35
	s_nop 0
	global_load_lds_dwordx4 v[182:183], off
	v_lshl_add_u64 v[182:183], s[50:51], 0, v[154:155]
	s_mov_b32 m0, s8
	s_nop 0
	global_load_lds_dwordx4 v[182:183], off
	s_mov_b32 m0, s43
	s_nop 0
	global_load_lds_dwordx4 v[184:185], off
	s_waitcnt vmcnt(8)
	s_waitcnt lgkmcnt(0)
	s_setprio 1
	s_barrier
	v_mfma_f32_16x16x128_f8f6f4 v[70:73], v[2:9], v[216:223], 0
	v_mfma_f32_16x16x128_f8f6f4 v[66:69], v[192:199], v[216:223], 0
	v_mfma_f32_16x16x128_f8f6f4 v[58:61], v[192:199], v[224:231], 0
	v_mfma_f32_16x16x128_f8f6f4 v[62:65], v[2:9], v[224:231], 0
	v_mfma_f32_16x16x128_f8f6f4 v[54:57], v[2:9], v[232:239], 0
	v_mfma_f32_16x16x128_f8f6f4 v[50:53], v[192:199], v[232:239], 0
	v_mfma_f32_16x16x128_f8f6f4 v[42:45], v[192:199], v[242:249], 0
	v_mfma_f32_16x16x128_f8f6f4 v[46:49], v[2:9], v[242:249], 0
	s_setprio 0
	s_setprio 1
	v_mfma_f32_16x16x128_f8f6f4 v[14:17], v[200:207], v[242:249], 0
	v_mfma_f32_16x16x128_f8f6f4 v[10:13], v[208:215], v[242:249], 0
	v_mfma_f32_16x16x128_f8f6f4 v[18:21], v[208:215], v[232:239], 0
	v_mfma_f32_16x16x128_f8f6f4 v[22:25], v[200:207], v[232:239], 0
	v_mfma_f32_16x16x128_f8f6f4 v[30:33], v[200:207], v[224:231], 0
	v_mfma_f32_16x16x128_f8f6f4 v[26:29], v[208:215], v[224:231], 0
	v_mfma_f32_16x16x128_f8f6f4 v[34:37], v[208:215], v[216:223], 0
	v_mfma_f32_16x16x128_f8f6f4 v[38:41], v[200:207], v[216:223], 0
	s_barrier
	s_setprio 0
	ds_read_b128 v[2:5], v189 offset:32768
	ds_read_b128 v[6:9], v189 offset:33792
	ds_read_b128 v[192:195], v189 offset:34816
	ds_read_b128 v[196:199], v189 offset:35840
	ds_read_b128 v[200:203], v189 offset:49152
	ds_read_b128 v[204:207], v189 offset:50176
	ds_read_b128 v[208:211], v189 offset:51200
	ds_read_b128 v[212:215], v189 offset:52224
	s_add_u32 s50, s50, 0x80000
	s_addc_u32 s51, s51, 0
	s_mov_b32 m0, s52
	v_lshl_add_u64 v[186:187], s[50:51], 0, v[154:155]
	ds_read_b128 v[216:219], v190 offset:32768
	ds_read_b128 v[220:223], v190 offset:33792
	ds_read_b128 v[224:227], v190 offset:34816
	ds_read_b128 v[228:231], v190 offset:35840
	ds_read_b128 v[232:235], v190 offset:36864
	ds_read_b128 v[236:239], v190 offset:37888
	ds_read_b128 v[242:245], v190 offset:38912
	ds_read_b128 v[246:249], v190 offset:39936
	global_load_lds_dwordx4 v[186:187], off
	v_lshl_add_u64 v[186:187], s[50:51], 0, v[158:159]
	s_mov_b32 m0, s53
	s_nop 0
	global_load_lds_dwordx4 v[186:187], off
	s_waitcnt vmcnt(8)
	s_waitcnt lgkmcnt(0)
	s_setprio 1
	s_barrier
	v_mfma_f32_16x16x128_f8f6f4 v[134:137], v[2:9], v[216:223], v[134:137]
	v_mfma_f32_16x16x128_f8f6f4 v[130:133], v[192:199], v[216:223], v[130:133]
	v_mfma_f32_16x16x128_f8f6f4 v[122:125], v[192:199], v[224:231], v[122:125]
	v_mfma_f32_16x16x128_f8f6f4 v[126:129], v[2:9], v[224:231], v[126:129]
	v_mfma_f32_16x16x128_f8f6f4 v[118:121], v[2:9], v[232:239], v[118:121]
	v_mfma_f32_16x16x128_f8f6f4 v[114:117], v[192:199], v[232:239], v[114:117]
	v_mfma_f32_16x16x128_f8f6f4 v[106:109], v[192:199], v[242:249], v[106:109]
	v_mfma_f32_16x16x128_f8f6f4 v[110:113], v[2:9], v[242:249], v[110:113]
	s_setprio 0
	s_setprio 1
	v_mfma_f32_16x16x128_f8f6f4 v[78:81], v[200:207], v[242:249], v[78:81]
	v_mfma_f32_16x16x128_f8f6f4 v[74:77], v[208:215], v[242:249], v[74:77]
	v_mfma_f32_16x16x128_f8f6f4 v[82:85], v[208:215], v[232:239], v[82:85]
	v_mfma_f32_16x16x128_f8f6f4 v[86:89], v[200:207], v[232:239], v[86:89]
	v_mfma_f32_16x16x128_f8f6f4 v[94:97], v[200:207], v[224:231], v[94:97]
	v_mfma_f32_16x16x128_f8f6f4 v[90:93], v[208:215], v[224:231], v[90:93]
	v_mfma_f32_16x16x128_f8f6f4 v[98:101], v[208:215], v[216:223], v[98:101]
	v_mfma_f32_16x16x128_f8f6f4 v[102:105], v[200:207], v[216:223], v[102:105]
	s_barrier
	s_setprio 0
	s_mov_b32 m0, s70
	v_lshl_add_u64 v[174:175], v[174:175], 0, s[18:19]
	s_add_u32 s48, s48, 0x80080
	ds_read_b128 v[216:219], v190 offset:49152
	ds_read_b128 v[220:223], v190 offset:50176
	ds_read_b128 v[224:227], v190 offset:51200
	ds_read_b128 v[228:231], v190 offset:52224
	ds_read_b128 v[232:235], v190 offset:53248
	ds_read_b128 v[236:239], v190 offset:54272
	ds_read_b128 v[242:245], v190 offset:55296
	ds_read_b128 v[246:249], v190 offset:56320
	global_load_lds_dwordx4 v[174:175], off
	v_lshl_add_u64 v[174:175], v[176:177], 0, s[18:19]
	s_mov_b32 m0, s71
	s_addc_u32 s49, s49, 0
	global_load_lds_dwordx4 v[174:175], off
	v_lshl_add_u64 v[174:175], s[48:49], 0, v[156:157]
	s_mov_b32 m0, s74
	s_nop 0
	global_load_lds_dwordx4 v[174:175], off
	v_lshl_add_u64 v[174:175], s[48:49], 0, v[160:161]
	s_mov_b32 m0, s75
	s_nop 0
	global_load_lds_dwordx4 v[174:175], off
	v_lshl_add_u64 v[174:175], v[182:183], 0, s[18:19]
	s_mov_b32 m0, s72
	s_nop 0
	global_load_lds_dwordx4 v[174:175], off
	v_lshl_add_u64 v[174:175], v[184:185], 0, s[18:19]
	s_mov_b32 m0, s73
	s_nop 0
	global_load_lds_dwordx4 v[174:175], off
	s_waitcnt vmcnt(8)
	s_waitcnt lgkmcnt(0)
	s_setprio 1
	s_barrier
	v_mfma_f32_16x16x128_f8f6f4 v[70:73], v[2:9], v[216:223], v[70:73]
	v_mfma_f32_16x16x128_f8f6f4 v[66:69], v[192:199], v[216:223], v[66:69]
	v_mfma_f32_16x16x128_f8f6f4 v[58:61], v[192:199], v[224:231], v[58:61]
	v_mfma_f32_16x16x128_f8f6f4 v[62:65], v[2:9], v[224:231], v[62:65]
	v_mfma_f32_16x16x128_f8f6f4 v[54:57], v[2:9], v[232:239], v[54:57]
	v_mfma_f32_16x16x128_f8f6f4 v[50:53], v[192:199], v[232:239], v[50:53]
	v_mfma_f32_16x16x128_f8f6f4 v[42:45], v[192:199], v[242:249], v[42:45]
	v_mfma_f32_16x16x128_f8f6f4 v[46:49], v[2:9], v[242:249], v[46:49]
	s_setprio 0
	s_setprio 1
	v_mfma_f32_16x16x128_f8f6f4 v[14:17], v[200:207], v[242:249], v[14:17]
	v_mfma_f32_16x16x128_f8f6f4 v[10:13], v[208:215], v[242:249], v[10:13]
	v_mfma_f32_16x16x128_f8f6f4 v[18:21], v[208:215], v[232:239], v[18:21]
	v_mfma_f32_16x16x128_f8f6f4 v[22:25], v[200:207], v[232:239], v[22:25]
	v_mfma_f32_16x16x128_f8f6f4 v[30:33], v[200:207], v[224:231], v[30:33]
	v_mfma_f32_16x16x128_f8f6f4 v[26:29], v[208:215], v[224:231], v[26:29]
	v_mfma_f32_16x16x128_f8f6f4 v[34:37], v[208:215], v[216:223], v[34:37]
	v_mfma_f32_16x16x128_f8f6f4 v[38:41], v[200:207], v[216:223], v[38:41]
	s_barrier
	s_setprio 0
	s_cmp_lt_u32 s86, 3
	s_cbranch_scc1 .LBB0_796
	s_add_u32 s48, s55, s62
	s_addc_u32 s49, s61, s41
	s_add_u32 s46, s46, 0x80180
	s_addc_u32 s47, s47, 0
	s_add_u32 s41, s44, 0x200
	v_lshl_add_u64 v[174:175], v[172:173], 2, s[48:49]
	s_addc_u32 s50, s45, 0
	s_mov_b32 s51, 4
	s_cmp_eq_u32 s86, s51
	s_cselect_b64 s[44:45], -1, 0
	s_cmp_lg_u32 s86, s51
	s_cbranch_scc1 .LBB0_794

.LBB0_794:
	ds_read_b128 v[2:5], v189
	ds_read_b128 v[6:9], v189 offset:1024
	ds_read_b128 v[192:195], v189 offset:2048
	ds_read_b128 v[196:199], v189 offset:3072
	ds_read_b128 v[200:203], v189 offset:16384
	ds_read_b128 v[204:207], v189 offset:17408
	ds_read_b128 v[208:211], v189 offset:18432
	ds_read_b128 v[212:215], v189 offset:19456
	s_add_u32 s48, s46, 0xfff80080
	s_addc_u32 s49, s47, -1
	s_and_b64 s[44:45], s[44:45], exec
	s_cselect_b32 s44, s4, s41
	s_cselect_b32 s49, s1, s49
	s_cselect_b32 s48, s0, s48
	s_cselect_b32 s45, s5, s50
	s_mov_b32 m0, s37
	v_lshl_add_u64 v[176:177], s[46:47], 0, v[162:163]
	ds_read_b128 v[216:219], v190
	ds_read_b128 v[220:223], v190 offset:1024
	ds_read_b128 v[224:227], v190 offset:2048
	ds_read_b128 v[228:231], v190 offset:3072
	ds_read_b128 v[232:235], v190 offset:4096
	ds_read_b128 v[236:239], v190 offset:5120
	ds_read_b128 v[242:245], v190 offset:6144
	ds_read_b128 v[246:249], v190 offset:7168
	global_load_lds_dwordx4 v[176:177], off
	v_lshl_add_u64 v[176:177], s[46:47], 0, v[164:165]
	s_mov_b32 m0, s39
	s_nop 0
	global_load_lds_dwordx4 v[176:177], off
	s_waitcnt vmcnt(8)
	s_waitcnt lgkmcnt(0)
	s_setprio 1
	s_barrier
	v_mfma_f32_16x16x128_f8f6f4 v[134:137], v[2:9], v[216:223], v[134:137]
	v_mfma_f32_16x16x128_f8f6f4 v[130:133], v[192:199], v[216:223], v[130:133]
	v_mfma_f32_16x16x128_f8f6f4 v[122:125], v[192:199], v[224:231], v[122:125]
	v_mfma_f32_16x16x128_f8f6f4 v[126:129], v[2:9], v[224:231], v[126:129]
	v_mfma_f32_16x16x128_f8f6f4 v[118:121], v[2:9], v[232:239], v[118:121]
	v_mfma_f32_16x16x128_f8f6f4 v[114:117], v[192:199], v[232:239], v[114:117]
	v_mfma_f32_16x16x128_f8f6f4 v[106:109], v[192:199], v[242:249], v[106:109]
	v_mfma_f32_16x16x128_f8f6f4 v[110:113], v[2:9], v[242:249], v[110:113]
	s_setprio 0
	s_setprio 1
	v_mfma_f32_16x16x128_f8f6f4 v[78:81], v[200:207], v[242:249], v[78:81]
	v_mfma_f32_16x16x128_f8f6f4 v[74:77], v[208:215], v[242:249], v[74:77]
	v_mfma_f32_16x16x128_f8f6f4 v[82:85], v[208:215], v[232:239], v[82:85]
	v_mfma_f32_16x16x128_f8f6f4 v[86:89], v[200:207], v[232:239], v[86:89]
	v_mfma_f32_16x16x128_f8f6f4 v[94:97], v[200:207], v[224:231], v[94:97]
	v_mfma_f32_16x16x128_f8f6f4 v[90:93], v[208:215], v[224:231], v[90:93]
	v_mfma_f32_16x16x128_f8f6f4 v[98:101], v[208:215], v[216:223], v[98:101]
	v_mfma_f32_16x16x128_f8f6f4 v[102:105], v[200:207], v[216:223], v[102:105]
	s_barrier
	s_setprio 0
	s_mov_b32 m0, s9
	v_lshl_add_u64 v[176:177], s[44:45], 0, v[156:157]
	s_add_u32 s62, s44, 0x80000
	ds_read_b128 v[216:219], v190 offset:16384
	ds_read_b128 v[220:223], v190 offset:17408
	ds_read_b128 v[224:227], v190 offset:18432
	ds_read_b128 v[228:231], v190 offset:19456
	ds_read_b128 v[232:235], v190 offset:20480
	ds_read_b128 v[236:239], v190 offset:21504
	ds_read_b128 v[242:245], v190 offset:22528
	ds_read_b128 v[246:249], v190 offset:23552
	global_load_lds_dwordx4 v[176:177], off
	v_lshl_add_u64 v[182:183], s[44:45], 0, v[160:161]
	s_mov_b32 m0, s27
	s_addc_u32 s63, s45, 0
	global_load_lds_dwordx4 v[182:183], off
	v_lshl_add_u64 v[184:185], s[62:63], 0, v[156:157]
	s_mov_b32 m0, s33
	v_lshl_add_u64 v[186:187], s[48:49], 0, v[158:159]
	global_load_lds_dwordx4 v[184:185], off
	v_lshl_add_u64 v[184:185], s[62:63], 0, v[160:161]
	s_mov_b32 m0, s35
	s_nop 0
	global_load_lds_dwordx4 v[184:185], off
	v_lshl_add_u64 v[184:185], s[48:49], 0, v[154:155]
	s_mov_b32 m0, s8
	s_nop 0
	global_load_lds_dwordx4 v[184:185], off
	s_mov_b32 m0, s43
	s_nop 0
	global_load_lds_dwordx4 v[186:187], off
	s_waitcnt vmcnt(8)
	s_waitcnt lgkmcnt(0)
	s_setprio 1
	s_barrier
	v_mfma_f32_16x16x128_f8f6f4 v[70:73], v[2:9], v[216:223], v[70:73]
	v_mfma_f32_16x16x128_f8f6f4 v[66:69], v[192:199], v[216:223], v[66:69]
	v_mfma_f32_16x16x128_f8f6f4 v[58:61], v[192:199], v[224:231], v[58:61]
	v_mfma_f32_16x16x128_f8f6f4 v[62:65], v[2:9], v[224:231], v[62:65]
	v_mfma_f32_16x16x128_f8f6f4 v[54:57], v[2:9], v[232:239], v[54:57]
	v_mfma_f32_16x16x128_f8f6f4 v[50:53], v[192:199], v[232:239], v[50:53]
	v_mfma_f32_16x16x128_f8f6f4 v[42:45], v[192:199], v[242:249], v[42:45]
	v_mfma_f32_16x16x128_f8f6f4 v[46:49], v[2:9], v[242:249], v[46:49]
	s_setprio 0
	s_setprio 1
	v_mfma_f32_16x16x128_f8f6f4 v[14:17], v[200:207], v[242:249], v[14:17]
	v_mfma_f32_16x16x128_f8f6f4 v[10:13], v[208:215], v[242:249], v[10:13]
	v_mfma_f32_16x16x128_f8f6f4 v[18:21], v[208:215], v[232:239], v[18:21]
	v_mfma_f32_16x16x128_f8f6f4 v[22:25], v[200:207], v[232:239], v[22:25]
	v_mfma_f32_16x16x128_f8f6f4 v[30:33], v[200:207], v[224:231], v[30:33]
	v_mfma_f32_16x16x128_f8f6f4 v[26:29], v[208:215], v[224:231], v[26:29]
	v_mfma_f32_16x16x128_f8f6f4 v[34:37], v[208:215], v[216:223], v[34:37]
	v_mfma_f32_16x16x128_f8f6f4 v[38:41], v[200:207], v[216:223], v[38:41]
	s_barrier
	s_setprio 0
	ds_read_b128 v[192:195], v189 offset:32768
	ds_read_b128 v[196:199], v189 offset:33792
	ds_read_b128 v[200:203], v189 offset:34816
	ds_read_b128 v[204:207], v189 offset:35840
	ds_read_b128 v[2:5], v189 offset:49152
	ds_read_b128 v[6:9], v189 offset:50176
	ds_read_b128 v[208:211], v189 offset:51200
	ds_read_b128 v[212:215], v189 offset:52224
	s_add_u32 s48, s48, 0x80000
	s_addc_u32 s49, s49, 0
	s_mov_b32 m0, s52
	v_lshl_add_u64 v[252:253], s[48:49], 0, v[154:155]
	ds_read_b128 v[216:219], v190 offset:32768
	ds_read_b128 v[220:223], v190 offset:33792
	ds_read_b128 v[224:227], v190 offset:34816
	ds_read_b128 v[228:231], v190 offset:35840
	ds_read_b128 v[232:235], v190 offset:36864
	ds_read_b128 v[236:239], v190 offset:37888
	ds_read_b128 v[242:245], v190 offset:38912
	ds_read_b128 v[246:249], v190 offset:39936
	global_load_lds_dwordx4 v[252:253], off
	v_lshl_add_u64 v[252:253], s[48:49], 0, v[158:159]
	s_mov_b32 m0, s53
	s_nop 0
	global_load_lds_dwordx4 v[252:253], off
	s_waitcnt vmcnt(8)
	s_waitcnt lgkmcnt(0)
	s_setprio 1
	s_barrier
	v_mfma_f32_16x16x128_f8f6f4 v[134:137], v[192:199], v[216:223], v[134:137]
	v_mfma_f32_16x16x128_f8f6f4 v[130:133], v[200:207], v[216:223], v[130:133]
	v_mfma_f32_16x16x128_f8f6f4 v[122:125], v[200:207], v[224:231], v[122:125]
	v_mfma_f32_16x16x128_f8f6f4 v[126:129], v[192:199], v[224:231], v[126:129]
	v_mfma_f32_16x16x128_f8f6f4 v[118:121], v[192:199], v[232:239], v[118:121]
	v_mfma_f32_16x16x128_f8f6f4 v[114:117], v[200:207], v[232:239], v[114:117]
	v_mfma_f32_16x16x128_f8f6f4 v[106:109], v[200:207], v[242:249], v[106:109]
	v_mfma_f32_16x16x128_f8f6f4 v[110:113], v[192:199], v[242:249], v[110:113]
	s_setprio 0
	s_setprio 1
	v_mfma_f32_16x16x128_f8f6f4 v[78:81], v[2:9], v[242:249], v[78:81]
	v_mfma_f32_16x16x128_f8f6f4 v[74:77], v[208:215], v[242:249], v[74:77]
	v_mfma_f32_16x16x128_f8f6f4 v[82:85], v[208:215], v[232:239], v[82:85]
	v_mfma_f32_16x16x128_f8f6f4 v[86:89], v[2:9], v[232:239], v[86:89]
	v_mfma_f32_16x16x128_f8f6f4 v[94:97], v[2:9], v[224:231], v[94:97]
	v_mfma_f32_16x16x128_f8f6f4 v[90:93], v[208:215], v[224:231], v[90:93]
	v_mfma_f32_16x16x128_f8f6f4 v[98:101], v[208:215], v[216:223], v[98:101]
	v_mfma_f32_16x16x128_f8f6f4 v[102:105], v[2:9], v[216:223], v[102:105]
	s_barrier
	s_setprio 0
	s_mov_b32 m0, s70
	v_lshl_add_u64 v[176:177], v[176:177], 0, s[18:19]
	s_add_u32 s44, s44, 0x80080
	ds_read_b128 v[216:219], v190 offset:49152
	ds_read_b128 v[220:223], v190 offset:50176
	ds_read_b128 v[224:227], v190 offset:51200
	ds_read_b128 v[228:231], v190 offset:52224
	ds_read_b128 v[232:235], v190 offset:53248
	ds_read_b128 v[236:239], v190 offset:54272
	ds_read_b128 v[242:245], v190 offset:55296
	ds_read_b128 v[246:249], v190 offset:56320
	global_load_lds_dwordx4 v[176:177], off
	v_lshl_add_u64 v[176:177], v[182:183], 0, s[18:19]
	s_mov_b32 m0, s71
	s_addc_u32 s45, s45, 0
	global_load_lds_dwordx4 v[176:177], off
	v_lshl_add_u64 v[176:177], s[44:45], 0, v[156:157]
	s_mov_b32 m0, s74
	s_nop 0
	global_load_lds_dwordx4 v[176:177], off
	v_lshl_add_u64 v[176:177], s[44:45], 0, v[160:161]
	s_mov_b32 m0, s75
	s_nop 0
	global_load_lds_dwordx4 v[176:177], off
	v_lshl_add_u64 v[176:177], v[184:185], 0, s[18:19]
	s_mov_b32 m0, s72
	s_nop 0
	global_load_lds_dwordx4 v[176:177], off
	v_lshl_add_u64 v[176:177], v[186:187], 0, s[18:19]
	s_mov_b32 m0, s73
	s_nop 0
	global_load_lds_dwordx4 v[176:177], off
	s_waitcnt vmcnt(8)
	s_waitcnt lgkmcnt(0)
	s_setprio 1
	s_barrier
	v_mfma_f32_16x16x128_f8f6f4 v[70:73], v[192:199], v[216:223], v[70:73]
	v_mfma_f32_16x16x128_f8f6f4 v[66:69], v[200:207], v[216:223], v[66:69]
	v_mfma_f32_16x16x128_f8f6f4 v[58:61], v[200:207], v[224:231], v[58:61]
	v_mfma_f32_16x16x128_f8f6f4 v[62:65], v[192:199], v[224:231], v[62:65]
	v_mfma_f32_16x16x128_f8f6f4 v[54:57], v[192:199], v[232:239], v[54:57]
	v_mfma_f32_16x16x128_f8f6f4 v[50:53], v[200:207], v[232:239], v[50:53]
	v_mfma_f32_16x16x128_f8f6f4 v[42:45], v[200:207], v[242:249], v[42:45]
	v_mfma_f32_16x16x128_f8f6f4 v[46:49], v[192:199], v[242:249], v[46:49]
	s_setprio 0
	s_setprio 1
	v_mfma_f32_16x16x128_f8f6f4 v[14:17], v[2:9], v[242:249], v[14:17]
	v_mfma_f32_16x16x128_f8f6f4 v[10:13], v[208:215], v[242:249], v[10:13]
	v_mfma_f32_16x16x128_f8f6f4 v[18:21], v[208:215], v[232:239], v[18:21]
	v_mfma_f32_16x16x128_f8f6f4 v[22:25], v[2:9], v[232:239], v[22:25]
	v_mfma_f32_16x16x128_f8f6f4 v[30:33], v[2:9], v[224:231], v[30:33]
	v_mfma_f32_16x16x128_f8f6f4 v[26:29], v[208:215], v[224:231], v[26:29]
	v_mfma_f32_16x16x128_f8f6f4 v[34:37], v[208:215], v[216:223], v[34:37]
	v_mfma_f32_16x16x128_f8f6f4 v[38:41], v[2:9], v[216:223], v[38:41]
	s_barrier
	s_setprio 0
	s_add_i32 s44, s51, 2
	s_add_u32 s46, s46, 0x100
	s_addc_u32 s47, s47, 0
	s_add_u32 s41, s41, 0x100
	s_addc_u32 s50, s50, 0
	s_cmp_ge_i32 s51, s86
	s_cbranch_scc1 .LBB0_796
	s_mov_b32 s51, s44
	s_cmp_eq_u32 s86, s51
	s_cselect_b64 s[44:45], -1, 0
	s_cmp_lg_u32 s86, s51
	s_cbranch_scc0 .LBB0_793
	s_branch .LBB0_794

.LBB0_946:
	s_ashr_i32 s37, s36, 31
	ds_read_b128 v[18:21], v192
	ds_read_b128 v[22:25], v192 offset:1024
	ds_read_b128 v[26:29], v192 offset:2048
	ds_read_b128 v[30:33], v192 offset:3072
	ds_read_b128 v[2:5], v192 offset:16384
	ds_read_b128 v[6:9], v192 offset:17408
	ds_read_b128 v[10:13], v192 offset:18432
	ds_read_b128 v[14:17], v192 offset:19456
	s_lshl_b64 s[38:39], s[36:37], 20
	s_add_u32 s38, s22, s38
	s_addc_u32 s39, s23, s39
	s_and_b64 s[40:41], s[2:3], exec
	s_cselect_b32 s37, s39, s47
	s_cselect_b32 s84, s38, s46
	s_ashr_i32 s27, s26, 31
	s_lshl_b64 s[40:41], s[26:27], 20
	s_add_u32 s40, s25, s40
	s_addc_u32 s41, s35, s41
	s_and_b64 s[48:49], s[2:3], exec
	s_cselect_b32 s27, s41, s45
	s_cselect_b32 s85, s40, s44
	s_add_u32 s48, s46, 0x80080
	s_addc_u32 s49, s47, 0
	s_mov_b32 m0, s80
	v_lshl_add_u64 v[218:219], s[48:49], 0, v[164:165]
	ds_read_b128 v[184:187], v193
	ds_read_b128 v[188:191], v193 offset:1024
	ds_read_b128 v[194:197], v193 offset:2048
	ds_read_b128 v[198:201], v193 offset:3072
	ds_read_b128 v[202:205], v193 offset:4096
	ds_read_b128 v[206:209], v193 offset:5120
	ds_read_b128 v[210:213], v193 offset:6144
	ds_read_b128 v[214:217], v193 offset:7168
	global_load_lds_dwordx4 v[218:219], off
	v_lshl_add_u64 v[218:219], s[48:49], 0, v[168:169]
	s_mov_b32 m0, s81
	s_nop 0
	global_load_lds_dwordx4 v[218:219], off
	s_waitcnt vmcnt(8)
	s_waitcnt lgkmcnt(0)
	s_setprio 1
	s_barrier
	v_mfma_f32_16x16x128_f8f6f4 v[158:161], v[18:25], v[184:191], 0
	v_mfma_f32_16x16x128_f8f6f4 v[154:157], v[26:33], v[184:191], 0
	v_mfma_f32_16x16x128_f8f6f4 v[146:149], v[26:33], v[194:201], 0
	v_mfma_f32_16x16x128_f8f6f4 v[150:153], v[18:25], v[194:201], 0
	v_mfma_f32_16x16x128_f8f6f4 v[142:145], v[18:25], v[202:209], 0
	v_mfma_f32_16x16x128_f8f6f4 v[138:141], v[26:33], v[202:209], 0
	v_mfma_f32_16x16x128_f8f6f4 v[130:133], v[26:33], v[210:217], 0
	v_mfma_f32_16x16x128_f8f6f4 v[134:137], v[18:25], v[210:217], 0
	s_setprio 0
	s_setprio 1
	v_mfma_f32_16x16x128_f8f6f4 v[102:105], v[2:9], v[210:217], 0
	v_mfma_f32_16x16x128_f8f6f4 v[98:101], v[10:17], v[210:217], 0
	v_mfma_f32_16x16x128_f8f6f4 v[106:109], v[10:17], v[202:209], 0
	v_mfma_f32_16x16x128_f8f6f4 v[110:113], v[2:9], v[202:209], 0
	v_mfma_f32_16x16x128_f8f6f4 v[118:121], v[2:9], v[194:201], 0
	v_mfma_f32_16x16x128_f8f6f4 v[114:117], v[10:17], v[194:201], 0
	v_mfma_f32_16x16x128_f8f6f4 v[122:125], v[10:17], v[184:191], 0
	v_mfma_f32_16x16x128_f8f6f4 v[126:129], v[2:9], v[184:191], 0
	s_barrier
	s_setprio 0
	v_lshl_add_u64 v[184:185], s[44:45], 0, v[166:167]
	s_mov_b32 m0, s52
	v_lshl_add_u64 v[186:187], v[184:185], 0, s[14:15]
	ds_read_b128 v[194:197], v193 offset:16384
	ds_read_b128 v[198:201], v193 offset:17408
	ds_read_b128 v[202:205], v193 offset:18432
	ds_read_b128 v[206:209], v193 offset:19456
	ds_read_b128 v[210:213], v193 offset:20480
	ds_read_b128 v[214:217], v193 offset:21504
	ds_read_b128 v[218:221], v193 offset:22528
	ds_read_b128 v[222:225], v193 offset:23552
	global_load_lds_dwordx4 v[186:187], off
	v_lshl_add_u64 v[186:187], s[44:45], 0, v[170:171]
	s_add_u32 s48, s44, 0x80100
	v_lshl_add_u64 v[188:189], v[186:187], 0, s[14:15]
	s_mov_b32 m0, s53
	s_addc_u32 s49, s45, 0
	global_load_lds_dwordx4 v[188:189], off
	v_lshl_add_u64 v[188:189], s[48:49], 0, v[166:167]
	s_mov_b32 m0, s54
	s_nop 0
	global_load_lds_dwordx4 v[188:189], off
	v_lshl_add_u64 v[188:189], s[48:49], 0, v[170:171]
	s_mov_b32 m0, s55
	s_nop 0
	global_load_lds_dwordx4 v[188:189], off
	v_lshl_add_u64 v[188:189], s[46:47], 0, v[164:165]
	v_lshl_add_u64 v[190:191], v[188:189], 0, s[14:15]
	s_mov_b32 m0, s43
	s_nop 0
	global_load_lds_dwordx4 v[190:191], off
	v_lshl_add_u64 v[190:191], s[46:47], 0, v[168:169]
	v_lshl_add_u64 v[226:227], v[190:191], 0, s[14:15]
	s_mov_b32 m0, s61
	s_nop 0
	global_load_lds_dwordx4 v[226:227], off
	s_waitcnt vmcnt(8)
	s_waitcnt lgkmcnt(0)
	s_setprio 1
	s_barrier
	v_mfma_f32_16x16x128_f8f6f4 v[94:97], v[18:25], v[194:201], 0
	v_mfma_f32_16x16x128_f8f6f4 v[90:93], v[26:33], v[194:201], 0
	v_mfma_f32_16x16x128_f8f6f4 v[82:85], v[26:33], v[202:209], 0
	v_mfma_f32_16x16x128_f8f6f4 v[86:89], v[18:25], v[202:209], 0
	v_mfma_f32_16x16x128_f8f6f4 v[78:81], v[18:25], v[210:217], 0
	v_mfma_f32_16x16x128_f8f6f4 v[74:77], v[26:33], v[210:217], 0
	v_mfma_f32_16x16x128_f8f6f4 v[66:69], v[26:33], v[218:225], 0
	v_mfma_f32_16x16x128_f8f6f4 v[70:73], v[18:25], v[218:225], 0
	s_setprio 0
	s_setprio 1
	v_mfma_f32_16x16x128_f8f6f4 v[38:41], v[2:9], v[218:225], 0
	v_mfma_f32_16x16x128_f8f6f4 v[34:37], v[10:17], v[218:225], 0
	v_mfma_f32_16x16x128_f8f6f4 v[42:45], v[10:17], v[210:217], 0
	v_mfma_f32_16x16x128_f8f6f4 v[46:49], v[2:9], v[210:217], 0
	v_mfma_f32_16x16x128_f8f6f4 v[54:57], v[2:9], v[202:209], 0
	v_mfma_f32_16x16x128_f8f6f4 v[50:53], v[10:17], v[202:209], 0
	v_mfma_f32_16x16x128_f8f6f4 v[58:61], v[10:17], v[194:201], 0
	v_mfma_f32_16x16x128_f8f6f4 v[62:65], v[2:9], v[194:201], 0
	s_barrier
	s_setprio 0
	ds_read_b128 v[18:21], v192 offset:32768
	ds_read_b128 v[22:25], v192 offset:33792
	ds_read_b128 v[26:29], v192 offset:34816
	ds_read_b128 v[30:33], v192 offset:35840
	ds_read_b128 v[2:5], v192 offset:49152
	ds_read_b128 v[6:9], v192 offset:50176
	ds_read_b128 v[10:13], v192 offset:51200
	ds_read_b128 v[14:17], v192 offset:52224
	s_add_u32 s48, s46, 0x80100
	s_addc_u32 s49, s47, 0
	s_mov_b32 m0, s68
	v_lshl_add_u64 v[226:227], s[48:49], 0, v[164:165]
	ds_read_b128 v[194:197], v193 offset:32768
	ds_read_b128 v[198:201], v193 offset:33792
	ds_read_b128 v[202:205], v193 offset:34816
	ds_read_b128 v[206:209], v193 offset:35840
	ds_read_b128 v[210:213], v193 offset:36864
	ds_read_b128 v[214:217], v193 offset:37888
	ds_read_b128 v[218:221], v193 offset:38912
	ds_read_b128 v[222:225], v193 offset:39936
	global_load_lds_dwordx4 v[226:227], off
	v_lshl_add_u64 v[226:227], s[48:49], 0, v[168:169]
	s_mov_b32 m0, s69
	s_nop 0
	global_load_lds_dwordx4 v[226:227], off
	s_waitcnt vmcnt(8)
	s_waitcnt lgkmcnt(0)
	s_setprio 1
	s_barrier
	v_mfma_f32_16x16x128_f8f6f4 v[158:161], v[18:25], v[194:201], v[158:161]
	v_mfma_f32_16x16x128_f8f6f4 v[154:157], v[26:33], v[194:201], v[154:157]
	v_mfma_f32_16x16x128_f8f6f4 v[146:149], v[26:33], v[202:209], v[146:149]
	v_mfma_f32_16x16x128_f8f6f4 v[150:153], v[18:25], v[202:209], v[150:153]
	v_mfma_f32_16x16x128_f8f6f4 v[142:145], v[18:25], v[210:217], v[142:145]
	v_mfma_f32_16x16x128_f8f6f4 v[138:141], v[26:33], v[210:217], v[138:141]
	v_mfma_f32_16x16x128_f8f6f4 v[130:133], v[26:33], v[218:225], v[130:133]
	v_mfma_f32_16x16x128_f8f6f4 v[134:137], v[18:25], v[218:225], v[134:137]
	s_setprio 0
	s_setprio 1
	v_mfma_f32_16x16x128_f8f6f4 v[102:105], v[2:9], v[218:225], v[102:105]
	v_mfma_f32_16x16x128_f8f6f4 v[98:101], v[10:17], v[218:225], v[98:101]
	v_mfma_f32_16x16x128_f8f6f4 v[106:109], v[10:17], v[210:217], v[106:109]
	v_mfma_f32_16x16x128_f8f6f4 v[110:113], v[2:9], v[210:217], v[110:113]
	v_mfma_f32_16x16x128_f8f6f4 v[118:121], v[2:9], v[202:209], v[118:121]
	v_mfma_f32_16x16x128_f8f6f4 v[114:117], v[10:17], v[202:209], v[114:117]
	v_mfma_f32_16x16x128_f8f6f4 v[122:125], v[10:17], v[194:201], v[122:125]
	v_mfma_f32_16x16x128_f8f6f4 v[126:129], v[2:9], v[194:201], v[126:129]
	s_barrier
	s_setprio 0
	s_mov_b32 m0, s74
	v_lshl_add_u64 v[184:185], v[184:185], 0, s[18:19]
	s_add_u32 s48, s44, 0x80180
	ds_read_b128 v[194:197], v193 offset:49152
	ds_read_b128 v[198:201], v193 offset:50176
	ds_read_b128 v[202:205], v193 offset:51200
	ds_read_b128 v[206:209], v193 offset:52224
	ds_read_b128 v[210:213], v193 offset:53248
	ds_read_b128 v[214:217], v193 offset:54272
	ds_read_b128 v[218:221], v193 offset:55296
	ds_read_b128 v[222:225], v193 offset:56320
	global_load_lds_dwordx4 v[184:185], off
	v_lshl_add_u64 v[184:185], v[186:187], 0, s[18:19]
	s_mov_b32 m0, s75
	s_addc_u32 s49, s45, 0
	global_load_lds_dwordx4 v[184:185], off
	v_lshl_add_u64 v[184:185], s[48:49], 0, v[166:167]
	s_mov_b32 m0, s78
	s_nop 0
	global_load_lds_dwordx4 v[184:185], off
	v_lshl_add_u64 v[184:185], s[48:49], 0, v[170:171]
	s_mov_b32 m0, s79
	s_nop 0
	global_load_lds_dwordx4 v[184:185], off
	v_lshl_add_u64 v[184:185], v[188:189], 0, s[18:19]
	s_mov_b32 m0, s76
	s_nop 0
	global_load_lds_dwordx4 v[184:185], off
	v_lshl_add_u64 v[184:185], v[190:191], 0, s[18:19]
	s_mov_b32 m0, s77
	s_nop 0
	global_load_lds_dwordx4 v[184:185], off
	s_waitcnt vmcnt(8)
	s_waitcnt lgkmcnt(0)
	s_setprio 1
	s_barrier
	v_mfma_f32_16x16x128_f8f6f4 v[94:97], v[18:25], v[194:201], v[94:97]
	v_mfma_f32_16x16x128_f8f6f4 v[90:93], v[26:33], v[194:201], v[90:93]
	v_mfma_f32_16x16x128_f8f6f4 v[82:85], v[26:33], v[202:209], v[82:85]
	v_mfma_f32_16x16x128_f8f6f4 v[86:89], v[18:25], v[202:209], v[86:89]
	v_mfma_f32_16x16x128_f8f6f4 v[78:81], v[18:25], v[210:217], v[78:81]
	v_mfma_f32_16x16x128_f8f6f4 v[74:77], v[26:33], v[210:217], v[74:77]
	v_mfma_f32_16x16x128_f8f6f4 v[66:69], v[26:33], v[218:225], v[66:69]
	v_mfma_f32_16x16x128_f8f6f4 v[70:73], v[18:25], v[218:225], v[70:73]
	s_setprio 0
	s_setprio 1
	v_mfma_f32_16x16x128_f8f6f4 v[38:41], v[2:9], v[218:225], v[38:41]
	v_mfma_f32_16x16x128_f8f6f4 v[34:37], v[10:17], v[218:225], v[34:37]
	v_mfma_f32_16x16x128_f8f6f4 v[42:45], v[10:17], v[210:217], v[42:45]
	v_mfma_f32_16x16x128_f8f6f4 v[46:49], v[2:9], v[210:217], v[46:49]
	v_mfma_f32_16x16x128_f8f6f4 v[54:57], v[2:9], v[202:209], v[54:57]
	v_mfma_f32_16x16x128_f8f6f4 v[50:53], v[10:17], v[202:209], v[50:53]
	v_mfma_f32_16x16x128_f8f6f4 v[58:61], v[10:17], v[194:201], v[58:61]
	v_mfma_f32_16x16x128_f8f6f4 v[62:65], v[2:9], v[194:201], v[62:65]
	s_barrier
	s_setprio 0
	s_add_u32 s46, s46, 0x80180
	s_addc_u32 s47, s47, 0
	s_add_u32 s62, s44, 0x200
	s_addc_u32 s63, s45, 0
	s_mov_b32 s86, 0
.LBB0_947:
	ds_read_b128 v[2:5], v192
	ds_read_b128 v[6:9], v192 offset:1024
	ds_read_b128 v[18:21], v192 offset:2048
	ds_read_b128 v[22:25], v192 offset:3072
	ds_read_b128 v[26:29], v192 offset:16384
	ds_read_b128 v[30:33], v192 offset:17408
	ds_read_b128 v[184:187], v192 offset:18432
	ds_read_b128 v[188:191], v192 offset:19456
	s_add_u32 s44, s46, 0xfff80080
	s_addc_u32 s45, s47, -1
	s_cmp_eq_u32 s86, 28
	s_cselect_b32 s49, s37, s45
	s_cselect_b32 s48, s84, s44
	s_cselect_b32 s45, s27, s63
	s_cselect_b32 s44, s85, s62
	s_mov_b32 m0, s80
	v_lshl_add_u64 v[218:219], s[46:47], 0, v[172:173]
	ds_read_b128 v[10:13], v193
	ds_read_b128 v[14:17], v193 offset:1024
	ds_read_b128 v[194:197], v193 offset:2048
	ds_read_b128 v[198:201], v193 offset:3072
	ds_read_b128 v[202:205], v193 offset:4096
	ds_read_b128 v[206:209], v193 offset:5120
	ds_read_b128 v[210:213], v193 offset:6144
	ds_read_b128 v[214:217], v193 offset:7168
	global_load_lds_dwordx4 v[218:219], off
	v_lshl_add_u64 v[218:219], s[46:47], 0, v[174:175]
	s_mov_b32 m0, s81
	s_nop 0
	global_load_lds_dwordx4 v[218:219], off
	s_waitcnt vmcnt(8)
	s_waitcnt lgkmcnt(0)
	s_setprio 1
	s_barrier
	v_mfma_f32_16x16x128_f8f6f4 v[158:161], v[2:9], v[10:17], v[158:161]
	v_mfma_f32_16x16x128_f8f6f4 v[154:157], v[18:25], v[10:17], v[154:157]
	v_mfma_f32_16x16x128_f8f6f4 v[146:149], v[18:25], v[194:201], v[146:149]
	v_mfma_f32_16x16x128_f8f6f4 v[150:153], v[2:9], v[194:201], v[150:153]
	v_mfma_f32_16x16x128_f8f6f4 v[142:145], v[2:9], v[202:209], v[142:145]
	v_mfma_f32_16x16x128_f8f6f4 v[138:141], v[18:25], v[202:209], v[138:141]
	v_mfma_f32_16x16x128_f8f6f4 v[130:133], v[18:25], v[210:217], v[130:133]
	v_mfma_f32_16x16x128_f8f6f4 v[134:137], v[2:9], v[210:217], v[134:137]
	s_setprio 0
	s_setprio 1
	v_mfma_f32_16x16x128_f8f6f4 v[102:105], v[26:33], v[210:217], v[102:105]
	v_mfma_f32_16x16x128_f8f6f4 v[98:101], v[184:191], v[210:217], v[98:101]
	v_mfma_f32_16x16x128_f8f6f4 v[106:109], v[184:191], v[202:209], v[106:109]
	v_mfma_f32_16x16x128_f8f6f4 v[110:113], v[26:33], v[202:209], v[110:113]
	v_mfma_f32_16x16x128_f8f6f4 v[118:121], v[26:33], v[194:201], v[118:121]
	v_mfma_f32_16x16x128_f8f6f4 v[114:117], v[184:191], v[194:201], v[114:117]
	v_mfma_f32_16x16x128_f8f6f4 v[122:125], v[184:191], v[10:17], v[122:125]
	v_mfma_f32_16x16x128_f8f6f4 v[126:129], v[26:33], v[10:17], v[126:129]
	s_barrier
	s_setprio 0
	s_mov_b32 m0, s52
	v_lshl_add_u64 v[10:11], s[44:45], 0, v[166:167]
	s_add_u32 s88, s44, 0x80000
	ds_read_b128 v[194:197], v193 offset:16384
	ds_read_b128 v[198:201], v193 offset:17408
	ds_read_b128 v[202:205], v193 offset:18432
	ds_read_b128 v[206:209], v193 offset:19456
	ds_read_b128 v[210:213], v193 offset:20480
	ds_read_b128 v[214:217], v193 offset:21504
	ds_read_b128 v[218:221], v193 offset:22528
	ds_read_b128 v[222:225], v193 offset:23552
	global_load_lds_dwordx4 v[10:11], off
	v_lshl_add_u64 v[12:13], s[44:45], 0, v[170:171]
	s_mov_b32 m0, s53
	s_addc_u32 s89, s45, 0
	global_load_lds_dwordx4 v[12:13], off
	v_lshl_add_u64 v[14:15], s[88:89], 0, v[166:167]
	s_mov_b32 m0, s54
	v_lshl_add_u64 v[16:17], s[48:49], 0, v[168:169]
	global_load_lds_dwordx4 v[14:15], off
	v_lshl_add_u64 v[14:15], s[88:89], 0, v[170:171]
	s_mov_b32 m0, s55
	s_nop 0
	global_load_lds_dwordx4 v[14:15], off
	v_lshl_add_u64 v[14:15], s[48:49], 0, v[164:165]
	s_mov_b32 m0, s43
	s_nop 0
	global_load_lds_dwordx4 v[14:15], off
	s_mov_b32 m0, s61
	s_nop 0
	global_load_lds_dwordx4 v[16:17], off
	s_waitcnt vmcnt(8)
	s_waitcnt lgkmcnt(0)
	s_setprio 1
	s_barrier
	v_mfma_f32_16x16x128_f8f6f4 v[94:97], v[2:9], v[194:201], v[94:97]
	v_mfma_f32_16x16x128_f8f6f4 v[90:93], v[18:25], v[194:201], v[90:93]
	v_mfma_f32_16x16x128_f8f6f4 v[82:85], v[18:25], v[202:209], v[82:85]
	v_mfma_f32_16x16x128_f8f6f4 v[86:89], v[2:9], v[202:209], v[86:89]
	v_mfma_f32_16x16x128_f8f6f4 v[78:81], v[2:9], v[210:217], v[78:81]
	v_mfma_f32_16x16x128_f8f6f4 v[74:77], v[18:25], v[210:217], v[74:77]
	v_mfma_f32_16x16x128_f8f6f4 v[66:69], v[18:25], v[218:225], v[66:69]
	v_mfma_f32_16x16x128_f8f6f4 v[70:73], v[2:9], v[218:225], v[70:73]
	s_setprio 0
	s_setprio 1
	v_mfma_f32_16x16x128_f8f6f4 v[38:41], v[26:33], v[218:225], v[38:41]
	v_mfma_f32_16x16x128_f8f6f4 v[34:37], v[184:191], v[218:225], v[34:37]
	v_mfma_f32_16x16x128_f8f6f4 v[42:45], v[184:191], v[210:217], v[42:45]
	v_mfma_f32_16x16x128_f8f6f4 v[46:49], v[26:33], v[210:217], v[46:49]
	v_mfma_f32_16x16x128_f8f6f4 v[54:57], v[26:33], v[202:209], v[54:57]
	v_mfma_f32_16x16x128_f8f6f4 v[50:53], v[184:191], v[202:209], v[50:53]
	v_mfma_f32_16x16x128_f8f6f4 v[58:61], v[184:191], v[194:201], v[58:61]
	v_mfma_f32_16x16x128_f8f6f4 v[62:65], v[26:33], v[194:201], v[62:65]
	s_barrier
	s_setprio 0
	ds_read_b128 v[18:21], v192 offset:32768
	ds_read_b128 v[22:25], v192 offset:33792
	ds_read_b128 v[26:29], v192 offset:34816
	ds_read_b128 v[30:33], v192 offset:35840
	ds_read_b128 v[2:5], v192 offset:49152
	ds_read_b128 v[6:9], v192 offset:50176
	ds_read_b128 v[184:187], v192 offset:51200
	ds_read_b128 v[188:191], v192 offset:52224
	s_add_u32 s48, s48, 0x80000
	s_addc_u32 s49, s49, 0
	s_mov_b32 m0, s68
	v_lshl_add_u64 v[226:227], s[48:49], 0, v[164:165]
	ds_read_b128 v[194:197], v193 offset:32768
	ds_read_b128 v[198:201], v193 offset:33792
	ds_read_b128 v[202:205], v193 offset:34816
	ds_read_b128 v[206:209], v193 offset:35840
	ds_read_b128 v[210:213], v193 offset:36864
	ds_read_b128 v[214:217], v193 offset:37888
	ds_read_b128 v[218:221], v193 offset:38912
	ds_read_b128 v[222:225], v193 offset:39936
	global_load_lds_dwordx4 v[226:227], off
	v_lshl_add_u64 v[226:227], s[48:49], 0, v[168:169]
	s_mov_b32 m0, s69
	s_nop 0
	global_load_lds_dwordx4 v[226:227], off
	s_waitcnt vmcnt(8)
	s_waitcnt lgkmcnt(0)
	s_setprio 1
	s_barrier
	v_mfma_f32_16x16x128_f8f6f4 v[158:161], v[18:25], v[194:201], v[158:161]
	v_mfma_f32_16x16x128_f8f6f4 v[154:157], v[26:33], v[194:201], v[154:157]
	v_mfma_f32_16x16x128_f8f6f4 v[146:149], v[26:33], v[202:209], v[146:149]
	v_mfma_f32_16x16x128_f8f6f4 v[150:153], v[18:25], v[202:209], v[150:153]
	v_mfma_f32_16x16x128_f8f6f4 v[142:145], v[18:25], v[210:217], v[142:145]
	v_mfma_f32_16x16x128_f8f6f4 v[138:141], v[26:33], v[210:217], v[138:141]
	v_mfma_f32_16x16x128_f8f6f4 v[130:133], v[26:33], v[218:225], v[130:133]
	v_mfma_f32_16x16x128_f8f6f4 v[134:137], v[18:25], v[218:225], v[134:137]
	s_setprio 0
	s_setprio 1
	v_mfma_f32_16x16x128_f8f6f4 v[102:105], v[2:9], v[218:225], v[102:105]
	v_mfma_f32_16x16x128_f8f6f4 v[98:101], v[184:191], v[218:225], v[98:101]
	v_mfma_f32_16x16x128_f8f6f4 v[106:109], v[184:191], v[210:217], v[106:109]
	v_mfma_f32_16x16x128_f8f6f4 v[110:113], v[2:9], v[210:217], v[110:113]
	v_mfma_f32_16x16x128_f8f6f4 v[118:121], v[2:9], v[202:209], v[118:121]
	v_mfma_f32_16x16x128_f8f6f4 v[114:117], v[184:191], v[202:209], v[114:117]
	v_mfma_f32_16x16x128_f8f6f4 v[122:125], v[184:191], v[194:201], v[122:125]
	v_mfma_f32_16x16x128_f8f6f4 v[126:129], v[2:9], v[194:201], v[126:129]
	s_barrier
	s_setprio 0
	s_mov_b32 m0, s74
	v_lshl_add_u64 v[10:11], v[10:11], 0, s[4:5]
	s_add_u32 s44, s44, 0x80080
	ds_read_b128 v[194:197], v193 offset:49152
	ds_read_b128 v[198:201], v193 offset:50176
	ds_read_b128 v[202:205], v193 offset:51200
	ds_read_b128 v[206:209], v193 offset:52224
	ds_read_b128 v[210:213], v193 offset:53248
	ds_read_b128 v[214:217], v193 offset:54272
	ds_read_b128 v[218:221], v193 offset:55296
	ds_read_b128 v[222:225], v193 offset:56320
	global_load_lds_dwordx4 v[10:11], off
	v_lshl_add_u64 v[10:11], v[12:13], 0, s[4:5]
	s_mov_b32 m0, s75
	s_addc_u32 s45, s45, 0
	global_load_lds_dwordx4 v[10:11], off
	v_lshl_add_u64 v[10:11], s[44:45], 0, v[166:167]
	s_mov_b32 m0, s78
	s_nop 0
	global_load_lds_dwordx4 v[10:11], off
	v_lshl_add_u64 v[10:11], s[44:45], 0, v[170:171]
	s_mov_b32 m0, s79
	s_nop 0
	global_load_lds_dwordx4 v[10:11], off
	v_lshl_add_u64 v[10:11], v[14:15], 0, s[4:5]
	s_mov_b32 m0, s76
	s_nop 0
	global_load_lds_dwordx4 v[10:11], off
	v_lshl_add_u64 v[10:11], v[16:17], 0, s[4:5]
	s_mov_b32 m0, s77
	s_nop 0
	global_load_lds_dwordx4 v[10:11], off
	s_waitcnt vmcnt(8)
	s_waitcnt lgkmcnt(0)
	s_setprio 1
	s_barrier
	v_mfma_f32_16x16x128_f8f6f4 v[94:97], v[18:25], v[194:201], v[94:97]
	v_mfma_f32_16x16x128_f8f6f4 v[90:93], v[26:33], v[194:201], v[90:93]
	v_mfma_f32_16x16x128_f8f6f4 v[82:85], v[26:33], v[202:209], v[82:85]
	v_mfma_f32_16x16x128_f8f6f4 v[86:89], v[18:25], v[202:209], v[86:89]
	v_mfma_f32_16x16x128_f8f6f4 v[78:81], v[18:25], v[210:217], v[78:81]
	v_mfma_f32_16x16x128_f8f6f4 v[74:77], v[26:33], v[210:217], v[74:77]
	v_mfma_f32_16x16x128_f8f6f4 v[66:69], v[26:33], v[218:225], v[66:69]
	v_mfma_f32_16x16x128_f8f6f4 v[70:73], v[18:25], v[218:225], v[70:73]
	s_setprio 0
	s_setprio 1
	v_mfma_f32_16x16x128_f8f6f4 v[38:41], v[2:9], v[218:225], v[38:41]
	v_mfma_f32_16x16x128_f8f6f4 v[34:37], v[184:191], v[218:225], v[34:37]
	v_mfma_f32_16x16x128_f8f6f4 v[42:45], v[184:191], v[210:217], v[42:45]
	v_mfma_f32_16x16x128_f8f6f4 v[46:49], v[2:9], v[210:217], v[46:49]
	v_mfma_f32_16x16x128_f8f6f4 v[54:57], v[2:9], v[202:209], v[54:57]
	v_mfma_f32_16x16x128_f8f6f4 v[50:53], v[184:191], v[202:209], v[50:53]
	v_mfma_f32_16x16x128_f8f6f4 v[58:61], v[184:191], v[194:201], v[58:61]
	v_mfma_f32_16x16x128_f8f6f4 v[62:65], v[2:9], v[194:201], v[62:65]
	s_barrier
	s_setprio 0
	s_add_i32 s86, s86, 2
	s_add_u32 s46, s46, 0x100
	s_addc_u32 s47, s47, 0
	s_add_u32 s62, s62, 0x100
	s_addc_u32 s63, s63, 0
	s_cmp_gt_u32 s86, 29
	s_cbranch_scc0 .LBB0_947
	s_and_b64 vcc, exec, s[6:7]
	s_cbranch_vccz .LBB0_950
	s_barrier

.LBB0_1031:
	ds_read_b128 v[2:5], v189
	ds_read_b128 v[6:9], v189 offset:1024
	ds_read_b128 v[192:195], v189 offset:2048
	ds_read_b128 v[196:199], v189 offset:3072
	ds_read_b128 v[200:203], v189 offset:16384
	ds_read_b128 v[204:207], v189 offset:17408
	ds_read_b128 v[208:211], v189 offset:18432
	ds_read_b128 v[212:215], v189 offset:19456
	s_add_u32 s25, s36, 0x100
	s_addc_u32 s83, s37, 0
	s_and_b64 s[40:41], s[38:39], exec
	s_cselect_b32 s41, s1, s83
	s_cselect_b32 s40, s0, s25
	s_add_u32 s25, s26, 0x100
	s_addc_u32 s83, s27, 0
	s_and_b64 s[38:39], s[38:39], exec
	s_cselect_b32 s39, s5, s83
	s_cselect_b32 s38, s4, s25
	s_add_u32 s84, s36, 0x158080
	s_addc_u32 s85, s37, 0
	s_add_i32 s25, s23, 0xc000
	v_lshl_add_u64 v[174:175], s[84:85], 0, v[154:155]
	s_mov_b32 m0, s25
	s_add_i32 s83, s23, 0xe000
	ds_read_b128 v[216:219], v190
	ds_read_b128 v[220:223], v190 offset:1024
	ds_read_b128 v[224:227], v190 offset:2048
	ds_read_b128 v[228:231], v190 offset:3072
	ds_read_b128 v[232:235], v190 offset:4096
	ds_read_b128 v[236:239], v190 offset:5120
	ds_read_b128 v[240:243], v190 offset:6144
	ds_read_b128 v[244:247], v190 offset:7168
	global_load_lds_dwordx4 v[174:175], off
	v_lshl_add_u64 v[174:175], s[84:85], 0, v[158:159]
	s_mov_b32 m0, s83
	s_nop 0
	global_load_lds_dwordx4 v[174:175], off
	s_waitcnt vmcnt(8)
	s_waitcnt lgkmcnt(0)
	s_setprio 1
	s_barrier
	v_mfma_f32_16x16x128_f8f6f4 v[134:137], v[2:9], v[216:223], 0
	v_mfma_f32_16x16x128_f8f6f4 v[130:133], v[192:199], v[216:223], 0
	v_mfma_f32_16x16x128_f8f6f4 v[122:125], v[192:199], v[224:231], 0
	v_mfma_f32_16x16x128_f8f6f4 v[126:129], v[2:9], v[224:231], 0
	v_mfma_f32_16x16x128_f8f6f4 v[118:121], v[2:9], v[232:239], 0
	v_mfma_f32_16x16x128_f8f6f4 v[114:117], v[192:199], v[232:239], 0
	v_mfma_f32_16x16x128_f8f6f4 v[106:109], v[192:199], v[240:247], 0
	v_mfma_f32_16x16x128_f8f6f4 v[110:113], v[2:9], v[240:247], 0
	s_setprio 0
	s_setprio 1
	v_mfma_f32_16x16x128_f8f6f4 v[78:81], v[200:207], v[240:247], 0
	v_mfma_f32_16x16x128_f8f6f4 v[74:77], v[208:215], v[240:247], 0
	v_mfma_f32_16x16x128_f8f6f4 v[82:85], v[208:215], v[232:239], 0
	v_mfma_f32_16x16x128_f8f6f4 v[86:89], v[200:207], v[232:239], 0
	v_mfma_f32_16x16x128_f8f6f4 v[94:97], v[200:207], v[224:231], 0
	v_mfma_f32_16x16x128_f8f6f4 v[90:93], v[208:215], v[224:231], 0
	v_mfma_f32_16x16x128_f8f6f4 v[98:101], v[208:215], v[216:223], 0
	v_mfma_f32_16x16x128_f8f6f4 v[102:105], v[200:207], v[216:223], 0
	s_barrier
	s_setprio 0
	s_mov_b32 m0, s33
	v_lshl_add_u64 v[174:175], s[38:39], 0, v[156:157]
	s_add_u32 s84, s38, 0x158000
	ds_read_b128 v[216:219], v190 offset:16384
	ds_read_b128 v[220:223], v190 offset:17408
	ds_read_b128 v[224:227], v190 offset:18432
	ds_read_b128 v[228:231], v190 offset:19456
	ds_read_b128 v[232:235], v190 offset:20480
	ds_read_b128 v[236:239], v190 offset:21504
	ds_read_b128 v[240:243], v190 offset:22528
	ds_read_b128 v[244:247], v190 offset:23552
	global_load_lds_dwordx4 v[174:175], off
	v_lshl_add_u64 v[176:177], s[38:39], 0, v[160:161]
	s_mov_b32 m0, s35
	s_addc_u32 s85, s39, 0
	global_load_lds_dwordx4 v[176:177], off
	v_lshl_add_u64 v[182:183], s[84:85], 0, v[156:157]
	s_mov_b32 m0, s42
	v_lshl_add_u64 v[184:185], s[40:41], 0, v[158:159]
	global_load_lds_dwordx4 v[182:183], off
	v_lshl_add_u64 v[182:183], s[84:85], 0, v[160:161]
	s_mov_b32 m0, s43
	s_nop 0
	global_load_lds_dwordx4 v[182:183], off
	v_lshl_add_u64 v[182:183], s[40:41], 0, v[154:155]
	s_mov_b32 m0, s23
	s_nop 0
	global_load_lds_dwordx4 v[182:183], off
	s_mov_b32 m0, s44
	s_nop 0
	global_load_lds_dwordx4 v[184:185], off
	s_waitcnt vmcnt(8)
	s_waitcnt lgkmcnt(0)
	s_setprio 1
	s_barrier
	v_mfma_f32_16x16x128_f8f6f4 v[70:73], v[2:9], v[216:223], 0
	v_mfma_f32_16x16x128_f8f6f4 v[66:69], v[192:199], v[216:223], 0
	v_mfma_f32_16x16x128_f8f6f4 v[58:61], v[192:199], v[224:231], 0
	v_mfma_f32_16x16x128_f8f6f4 v[62:65], v[2:9], v[224:231], 0
	v_mfma_f32_16x16x128_f8f6f4 v[54:57], v[2:9], v[232:239], 0
	v_mfma_f32_16x16x128_f8f6f4 v[50:53], v[192:199], v[232:239], 0
	v_mfma_f32_16x16x128_f8f6f4 v[42:45], v[192:199], v[240:247], 0
	v_mfma_f32_16x16x128_f8f6f4 v[46:49], v[2:9], v[240:247], 0
	s_setprio 0
	s_setprio 1
	v_mfma_f32_16x16x128_f8f6f4 v[14:17], v[200:207], v[240:247], 0
	v_mfma_f32_16x16x128_f8f6f4 v[10:13], v[208:215], v[240:247], 0
	v_mfma_f32_16x16x128_f8f6f4 v[18:21], v[208:215], v[232:239], 0
	v_mfma_f32_16x16x128_f8f6f4 v[22:25], v[200:207], v[232:239], 0
	v_mfma_f32_16x16x128_f8f6f4 v[30:33], v[200:207], v[224:231], 0
	v_mfma_f32_16x16x128_f8f6f4 v[26:29], v[208:215], v[224:231], 0
	v_mfma_f32_16x16x128_f8f6f4 v[34:37], v[208:215], v[216:223], 0
	v_mfma_f32_16x16x128_f8f6f4 v[38:41], v[200:207], v[216:223], 0
	s_barrier
	s_setprio 0
	ds_read_b128 v[2:5], v189 offset:32768
	ds_read_b128 v[6:9], v189 offset:33792
	ds_read_b128 v[192:195], v189 offset:34816
	ds_read_b128 v[196:199], v189 offset:35840
	ds_read_b128 v[200:203], v189 offset:49152
	ds_read_b128 v[204:207], v189 offset:50176
	ds_read_b128 v[208:211], v189 offset:51200
	ds_read_b128 v[212:215], v189 offset:52224
	s_add_u32 s40, s40, 0x158000
	s_addc_u32 s41, s41, 0
	s_mov_b32 m0, s45
	v_lshl_add_u64 v[186:187], s[40:41], 0, v[154:155]
	ds_read_b128 v[216:219], v190 offset:32768
	ds_read_b128 v[220:223], v190 offset:33792
	ds_read_b128 v[224:227], v190 offset:34816
	ds_read_b128 v[228:231], v190 offset:35840
	ds_read_b128 v[232:235], v190 offset:36864
	ds_read_b128 v[236:239], v190 offset:37888
	ds_read_b128 v[240:243], v190 offset:38912
	ds_read_b128 v[244:247], v190 offset:39936
	global_load_lds_dwordx4 v[186:187], off
	v_lshl_add_u64 v[186:187], s[40:41], 0, v[158:159]
	s_mov_b32 m0, s46
	s_nop 0
	global_load_lds_dwordx4 v[186:187], off
	s_waitcnt vmcnt(8)
	s_waitcnt lgkmcnt(0)
	s_setprio 1
	s_barrier
	v_mfma_f32_16x16x128_f8f6f4 v[134:137], v[2:9], v[216:223], v[134:137]
	v_mfma_f32_16x16x128_f8f6f4 v[130:133], v[192:199], v[216:223], v[130:133]
	v_mfma_f32_16x16x128_f8f6f4 v[122:125], v[192:199], v[224:231], v[122:125]
	v_mfma_f32_16x16x128_f8f6f4 v[126:129], v[2:9], v[224:231], v[126:129]
	v_mfma_f32_16x16x128_f8f6f4 v[118:121], v[2:9], v[232:239], v[118:121]
	v_mfma_f32_16x16x128_f8f6f4 v[114:117], v[192:199], v[232:239], v[114:117]
	v_mfma_f32_16x16x128_f8f6f4 v[106:109], v[192:199], v[240:247], v[106:109]
	v_mfma_f32_16x16x128_f8f6f4 v[110:113], v[2:9], v[240:247], v[110:113]
	s_setprio 0
	s_setprio 1
	v_mfma_f32_16x16x128_f8f6f4 v[78:81], v[200:207], v[240:247], v[78:81]
	v_mfma_f32_16x16x128_f8f6f4 v[74:77], v[208:215], v[240:247], v[74:77]
	v_mfma_f32_16x16x128_f8f6f4 v[82:85], v[208:215], v[232:239], v[82:85]
	v_mfma_f32_16x16x128_f8f6f4 v[86:89], v[200:207], v[232:239], v[86:89]
	v_mfma_f32_16x16x128_f8f6f4 v[94:97], v[200:207], v[224:231], v[94:97]
	v_mfma_f32_16x16x128_f8f6f4 v[90:93], v[208:215], v[224:231], v[90:93]
	v_mfma_f32_16x16x128_f8f6f4 v[98:101], v[208:215], v[216:223], v[98:101]
	v_mfma_f32_16x16x128_f8f6f4 v[102:105], v[200:207], v[216:223], v[102:105]
	s_barrier
	s_setprio 0
	s_mov_b32 m0, s52
	v_lshl_add_u64 v[174:175], v[174:175], 0, s[14:15]
	s_add_u32 s38, s38, 0x158080
	ds_read_b128 v[216:219], v190 offset:49152
	ds_read_b128 v[220:223], v190 offset:50176
	ds_read_b128 v[224:227], v190 offset:51200
	ds_read_b128 v[228:231], v190 offset:52224
	ds_read_b128 v[232:235], v190 offset:53248
	ds_read_b128 v[236:239], v190 offset:54272
	ds_read_b128 v[240:243], v190 offset:55296
	ds_read_b128 v[244:247], v190 offset:56320
	global_load_lds_dwordx4 v[174:175], off
	v_lshl_add_u64 v[174:175], v[176:177], 0, s[14:15]
	s_mov_b32 m0, s53
	s_addc_u32 s39, s39, 0
	global_load_lds_dwordx4 v[174:175], off
	v_lshl_add_u64 v[174:175], s[38:39], 0, v[156:157]
	s_mov_b32 m0, s56
	s_nop 0
	global_load_lds_dwordx4 v[174:175], off
	v_lshl_add_u64 v[174:175], s[38:39], 0, v[160:161]
	s_mov_b32 m0, s57
	s_nop 0
	global_load_lds_dwordx4 v[174:175], off
	v_lshl_add_u64 v[174:175], v[182:183], 0, s[14:15]
	s_mov_b32 m0, s54
	s_nop 0
	global_load_lds_dwordx4 v[174:175], off
	v_lshl_add_u64 v[174:175], v[184:185], 0, s[14:15]
	s_mov_b32 m0, s55
	s_nop 0
	global_load_lds_dwordx4 v[174:175], off
	s_waitcnt vmcnt(8)
	s_waitcnt lgkmcnt(0)
	s_setprio 1
	s_barrier
	v_mfma_f32_16x16x128_f8f6f4 v[70:73], v[2:9], v[216:223], v[70:73]
	v_mfma_f32_16x16x128_f8f6f4 v[66:69], v[192:199], v[216:223], v[66:69]
	v_mfma_f32_16x16x128_f8f6f4 v[58:61], v[192:199], v[224:231], v[58:61]
	v_mfma_f32_16x16x128_f8f6f4 v[62:65], v[2:9], v[224:231], v[62:65]
	v_mfma_f32_16x16x128_f8f6f4 v[54:57], v[2:9], v[232:239], v[54:57]
	v_mfma_f32_16x16x128_f8f6f4 v[50:53], v[192:199], v[232:239], v[50:53]
	v_mfma_f32_16x16x128_f8f6f4 v[42:45], v[192:199], v[240:247], v[42:45]
	v_mfma_f32_16x16x128_f8f6f4 v[46:49], v[2:9], v[240:247], v[46:49]
	s_setprio 0
	s_setprio 1
	v_mfma_f32_16x16x128_f8f6f4 v[14:17], v[200:207], v[240:247], v[14:17]
	v_mfma_f32_16x16x128_f8f6f4 v[10:13], v[208:215], v[240:247], v[10:13]
	v_mfma_f32_16x16x128_f8f6f4 v[18:21], v[208:215], v[232:239], v[18:21]
	v_mfma_f32_16x16x128_f8f6f4 v[22:25], v[200:207], v[232:239], v[22:25]
	v_mfma_f32_16x16x128_f8f6f4 v[30:33], v[200:207], v[224:231], v[30:33]
	v_mfma_f32_16x16x128_f8f6f4 v[26:29], v[208:215], v[224:231], v[26:29]
	v_mfma_f32_16x16x128_f8f6f4 v[34:37], v[208:215], v[216:223], v[34:37]
	v_mfma_f32_16x16x128_f8f6f4 v[38:41], v[200:207], v[216:223], v[38:41]
	s_barrier
	s_setprio 0
	s_cmp_lt_u32 s82, 3
	s_cbranch_scc1 .LBB0_1036
	s_add_u32 s38, s48, s63
	s_addc_u32 s39, s49, s62
	s_add_u32 s36, s36, 0x158180
	s_addc_u32 s37, s37, 0
	s_add_u32 s40, s26, 0x200
	v_lshl_add_u64 v[174:175], v[172:173], 2, s[38:39]
	s_addc_u32 s41, s27, 0
	s_mov_b32 s84, 4
	s_cmp_eq_u32 s82, s84
	s_cselect_b64 s[26:27], -1, 0
	s_cmp_lg_u32 s82, s84
	s_cbranch_scc1 .LBB0_1034

.LBB0_1034:
	ds_read_b128 v[2:5], v189
	ds_read_b128 v[6:9], v189 offset:1024
	ds_read_b128 v[192:195], v189 offset:2048
	ds_read_b128 v[196:199], v189 offset:3072
	ds_read_b128 v[200:203], v189 offset:16384
	ds_read_b128 v[204:207], v189 offset:17408
	ds_read_b128 v[208:211], v189 offset:18432
	ds_read_b128 v[212:215], v189 offset:19456
	s_add_u32 s38, s36, 0xffea8080
	s_addc_u32 s39, s37, -1
	s_and_b64 s[26:27], s[26:27], exec
	s_cselect_b32 s26, s4, s40
	s_cselect_b32 s39, s1, s39
	s_cselect_b32 s38, s0, s38
	s_cselect_b32 s27, s5, s41
	s_mov_b32 m0, s25
	v_lshl_add_u64 v[176:177], s[36:37], 0, v[162:163]
	ds_read_b128 v[216:219], v190
	ds_read_b128 v[220:223], v190 offset:1024
	ds_read_b128 v[224:227], v190 offset:2048
	ds_read_b128 v[228:231], v190 offset:3072
	ds_read_b128 v[232:235], v190 offset:4096
	ds_read_b128 v[236:239], v190 offset:5120
	ds_read_b128 v[240:243], v190 offset:6144
	ds_read_b128 v[244:247], v190 offset:7168
	global_load_lds_dwordx4 v[176:177], off
	v_lshl_add_u64 v[176:177], s[36:37], 0, v[164:165]
	s_mov_b32 m0, s83
	s_nop 0
	global_load_lds_dwordx4 v[176:177], off
	s_waitcnt vmcnt(8)
	s_waitcnt lgkmcnt(0)
	s_setprio 1
	s_barrier
	v_mfma_f32_16x16x128_f8f6f4 v[134:137], v[2:9], v[216:223], v[134:137]
	v_mfma_f32_16x16x128_f8f6f4 v[130:133], v[192:199], v[216:223], v[130:133]
	v_mfma_f32_16x16x128_f8f6f4 v[122:125], v[192:199], v[224:231], v[122:125]
	v_mfma_f32_16x16x128_f8f6f4 v[126:129], v[2:9], v[224:231], v[126:129]
	v_mfma_f32_16x16x128_f8f6f4 v[118:121], v[2:9], v[232:239], v[118:121]
	v_mfma_f32_16x16x128_f8f6f4 v[114:117], v[192:199], v[232:239], v[114:117]
	v_mfma_f32_16x16x128_f8f6f4 v[106:109], v[192:199], v[240:247], v[106:109]
	v_mfma_f32_16x16x128_f8f6f4 v[110:113], v[2:9], v[240:247], v[110:113]
	s_setprio 0
	s_setprio 1
	v_mfma_f32_16x16x128_f8f6f4 v[78:81], v[200:207], v[240:247], v[78:81]
	v_mfma_f32_16x16x128_f8f6f4 v[74:77], v[208:215], v[240:247], v[74:77]
	v_mfma_f32_16x16x128_f8f6f4 v[82:85], v[208:215], v[232:239], v[82:85]
	v_mfma_f32_16x16x128_f8f6f4 v[86:89], v[200:207], v[232:239], v[86:89]
	v_mfma_f32_16x16x128_f8f6f4 v[94:97], v[200:207], v[224:231], v[94:97]
	v_mfma_f32_16x16x128_f8f6f4 v[90:93], v[208:215], v[224:231], v[90:93]
	v_mfma_f32_16x16x128_f8f6f4 v[98:101], v[208:215], v[216:223], v[98:101]
	v_mfma_f32_16x16x128_f8f6f4 v[102:105], v[200:207], v[216:223], v[102:105]
	s_barrier
	s_setprio 0
	s_mov_b32 m0, s33
	v_lshl_add_u64 v[176:177], s[26:27], 0, v[156:157]
	s_add_u32 s62, s26, 0x158000
	ds_read_b128 v[216:219], v190 offset:16384
	ds_read_b128 v[220:223], v190 offset:17408
	ds_read_b128 v[224:227], v190 offset:18432
	ds_read_b128 v[228:231], v190 offset:19456
	ds_read_b128 v[232:235], v190 offset:20480
	ds_read_b128 v[236:239], v190 offset:21504
	ds_read_b128 v[240:243], v190 offset:22528
	ds_read_b128 v[244:247], v190 offset:23552
	global_load_lds_dwordx4 v[176:177], off
	v_lshl_add_u64 v[182:183], s[26:27], 0, v[160:161]
	s_mov_b32 m0, s35
	s_addc_u32 s63, s27, 0
	global_load_lds_dwordx4 v[182:183], off
	v_lshl_add_u64 v[184:185], s[62:63], 0, v[156:157]
	s_mov_b32 m0, s42
	v_lshl_add_u64 v[186:187], s[38:39], 0, v[158:159]
	global_load_lds_dwordx4 v[184:185], off
	v_lshl_add_u64 v[184:185], s[62:63], 0, v[160:161]
	s_mov_b32 m0, s43
	s_nop 0
	global_load_lds_dwordx4 v[184:185], off
	v_lshl_add_u64 v[184:185], s[38:39], 0, v[154:155]
	s_mov_b32 m0, s23
	s_nop 0
	global_load_lds_dwordx4 v[184:185], off
	s_mov_b32 m0, s44
	s_nop 0
	global_load_lds_dwordx4 v[186:187], off
	s_waitcnt vmcnt(8)
	s_waitcnt lgkmcnt(0)
	s_setprio 1
	s_barrier
	v_mfma_f32_16x16x128_f8f6f4 v[70:73], v[2:9], v[216:223], v[70:73]
	v_mfma_f32_16x16x128_f8f6f4 v[66:69], v[192:199], v[216:223], v[66:69]
	v_mfma_f32_16x16x128_f8f6f4 v[58:61], v[192:199], v[224:231], v[58:61]
	v_mfma_f32_16x16x128_f8f6f4 v[62:65], v[2:9], v[224:231], v[62:65]
	v_mfma_f32_16x16x128_f8f6f4 v[54:57], v[2:9], v[232:239], v[54:57]
	v_mfma_f32_16x16x128_f8f6f4 v[50:53], v[192:199], v[232:239], v[50:53]
	v_mfma_f32_16x16x128_f8f6f4 v[42:45], v[192:199], v[240:247], v[42:45]
	v_mfma_f32_16x16x128_f8f6f4 v[46:49], v[2:9], v[240:247], v[46:49]
	s_setprio 0
	s_setprio 1
	v_mfma_f32_16x16x128_f8f6f4 v[14:17], v[200:207], v[240:247], v[14:17]
	v_mfma_f32_16x16x128_f8f6f4 v[10:13], v[208:215], v[240:247], v[10:13]
	v_mfma_f32_16x16x128_f8f6f4 v[18:21], v[208:215], v[232:239], v[18:21]
	v_mfma_f32_16x16x128_f8f6f4 v[22:25], v[200:207], v[232:239], v[22:25]
	v_mfma_f32_16x16x128_f8f6f4 v[30:33], v[200:207], v[224:231], v[30:33]
	v_mfma_f32_16x16x128_f8f6f4 v[26:29], v[208:215], v[224:231], v[26:29]
	v_mfma_f32_16x16x128_f8f6f4 v[34:37], v[208:215], v[216:223], v[34:37]
	v_mfma_f32_16x16x128_f8f6f4 v[38:41], v[200:207], v[216:223], v[38:41]
	s_barrier
	s_setprio 0
	ds_read_b128 v[192:195], v189 offset:32768
	ds_read_b128 v[196:199], v189 offset:33792
	ds_read_b128 v[200:203], v189 offset:34816
	ds_read_b128 v[204:207], v189 offset:35840
	ds_read_b128 v[2:5], v189 offset:49152
	ds_read_b128 v[6:9], v189 offset:50176
	ds_read_b128 v[208:211], v189 offset:51200
	ds_read_b128 v[212:215], v189 offset:52224
	s_add_u32 s38, s38, 0x158000
	s_addc_u32 s39, s39, 0
	s_mov_b32 m0, s45
	v_lshl_add_u64 v[248:249], s[38:39], 0, v[154:155]
	ds_read_b128 v[216:219], v190 offset:32768
	ds_read_b128 v[220:223], v190 offset:33792
	ds_read_b128 v[224:227], v190 offset:34816
	ds_read_b128 v[228:231], v190 offset:35840
	ds_read_b128 v[232:235], v190 offset:36864
	ds_read_b128 v[236:239], v190 offset:37888
	ds_read_b128 v[240:243], v190 offset:38912
	ds_read_b128 v[244:247], v190 offset:39936
	global_load_lds_dwordx4 v[248:249], off
	v_lshl_add_u64 v[248:249], s[38:39], 0, v[158:159]
	s_mov_b32 m0, s46
	s_nop 0
	global_load_lds_dwordx4 v[248:249], off
	s_waitcnt vmcnt(8)
	s_waitcnt lgkmcnt(0)
	s_setprio 1
	s_barrier
	v_mfma_f32_16x16x128_f8f6f4 v[134:137], v[192:199], v[216:223], v[134:137]
	v_mfma_f32_16x16x128_f8f6f4 v[130:133], v[200:207], v[216:223], v[130:133]
	v_mfma_f32_16x16x128_f8f6f4 v[122:125], v[200:207], v[224:231], v[122:125]
	v_mfma_f32_16x16x128_f8f6f4 v[126:129], v[192:199], v[224:231], v[126:129]
	v_mfma_f32_16x16x128_f8f6f4 v[118:121], v[192:199], v[232:239], v[118:121]
	v_mfma_f32_16x16x128_f8f6f4 v[114:117], v[200:207], v[232:239], v[114:117]
	v_mfma_f32_16x16x128_f8f6f4 v[106:109], v[200:207], v[240:247], v[106:109]
	v_mfma_f32_16x16x128_f8f6f4 v[110:113], v[192:199], v[240:247], v[110:113]
	s_setprio 0
	s_setprio 1
	v_mfma_f32_16x16x128_f8f6f4 v[78:81], v[2:9], v[240:247], v[78:81]
	v_mfma_f32_16x16x128_f8f6f4 v[74:77], v[208:215], v[240:247], v[74:77]
	v_mfma_f32_16x16x128_f8f6f4 v[82:85], v[208:215], v[232:239], v[82:85]
	v_mfma_f32_16x16x128_f8f6f4 v[86:89], v[2:9], v[232:239], v[86:89]
	v_mfma_f32_16x16x128_f8f6f4 v[94:97], v[2:9], v[224:231], v[94:97]
	v_mfma_f32_16x16x128_f8f6f4 v[90:93], v[208:215], v[224:231], v[90:93]
	v_mfma_f32_16x16x128_f8f6f4 v[98:101], v[208:215], v[216:223], v[98:101]
	v_mfma_f32_16x16x128_f8f6f4 v[102:105], v[2:9], v[216:223], v[102:105]
	s_barrier
	s_setprio 0
	s_mov_b32 m0, s52
	v_lshl_add_u64 v[176:177], v[176:177], 0, s[14:15]
	s_add_u32 s26, s26, 0x158080
	ds_read_b128 v[216:219], v190 offset:49152
	ds_read_b128 v[220:223], v190 offset:50176
	ds_read_b128 v[224:227], v190 offset:51200
	ds_read_b128 v[228:231], v190 offset:52224
	ds_read_b128 v[232:235], v190 offset:53248
	ds_read_b128 v[236:239], v190 offset:54272
	ds_read_b128 v[240:243], v190 offset:55296
	ds_read_b128 v[244:247], v190 offset:56320
	global_load_lds_dwordx4 v[176:177], off
	v_lshl_add_u64 v[176:177], v[182:183], 0, s[14:15]
	s_mov_b32 m0, s53
	s_addc_u32 s27, s27, 0
	global_load_lds_dwordx4 v[176:177], off
	v_lshl_add_u64 v[176:177], s[26:27], 0, v[156:157]
	s_mov_b32 m0, s56
	s_nop 0
	global_load_lds_dwordx4 v[176:177], off
	v_lshl_add_u64 v[176:177], s[26:27], 0, v[160:161]
	s_mov_b32 m0, s57
	s_nop 0
	global_load_lds_dwordx4 v[176:177], off
	v_lshl_add_u64 v[176:177], v[184:185], 0, s[14:15]
	s_mov_b32 m0, s54
	s_nop 0
	global_load_lds_dwordx4 v[176:177], off
	v_lshl_add_u64 v[176:177], v[186:187], 0, s[14:15]
	s_mov_b32 m0, s55
	s_nop 0
	global_load_lds_dwordx4 v[176:177], off
	s_waitcnt vmcnt(8)
	s_waitcnt lgkmcnt(0)
	s_setprio 1
	s_barrier
	v_mfma_f32_16x16x128_f8f6f4 v[70:73], v[192:199], v[216:223], v[70:73]
	v_mfma_f32_16x16x128_f8f6f4 v[66:69], v[200:207], v[216:223], v[66:69]
	v_mfma_f32_16x16x128_f8f6f4 v[58:61], v[200:207], v[224:231], v[58:61]
	v_mfma_f32_16x16x128_f8f6f4 v[62:65], v[192:199], v[224:231], v[62:65]
	v_mfma_f32_16x16x128_f8f6f4 v[54:57], v[192:199], v[232:239], v[54:57]
	v_mfma_f32_16x16x128_f8f6f4 v[50:53], v[200:207], v[232:239], v[50:53]
	v_mfma_f32_16x16x128_f8f6f4 v[42:45], v[200:207], v[240:247], v[42:45]
	v_mfma_f32_16x16x128_f8f6f4 v[46:49], v[192:199], v[240:247], v[46:49]
	s_setprio 0
	s_setprio 1
	v_mfma_f32_16x16x128_f8f6f4 v[14:17], v[2:9], v[240:247], v[14:17]
	v_mfma_f32_16x16x128_f8f6f4 v[10:13], v[208:215], v[240:247], v[10:13]
	v_mfma_f32_16x16x128_f8f6f4 v[18:21], v[208:215], v[232:239], v[18:21]
	v_mfma_f32_16x16x128_f8f6f4 v[22:25], v[2:9], v[232:239], v[22:25]
	v_mfma_f32_16x16x128_f8f6f4 v[30:33], v[2:9], v[224:231], v[30:33]
	v_mfma_f32_16x16x128_f8f6f4 v[26:29], v[208:215], v[224:231], v[26:29]
	v_mfma_f32_16x16x128_f8f6f4 v[34:37], v[208:215], v[216:223], v[34:37]
	v_mfma_f32_16x16x128_f8f6f4 v[38:41], v[2:9], v[216:223], v[38:41]
	s_barrier
	s_setprio 0
	s_add_i32 s26, s84, 2
	s_add_u32 s36, s36, 0x100
	s_addc_u32 s37, s37, 0
	s_add_u32 s40, s40, 0x100
	s_addc_u32 s41, s41, 0
	s_cmp_ge_i32 s84, s82
	s_cbranch_scc1 .LBB0_1036
	s_mov_b32 s84, s26
	s_cmp_eq_u32 s82, s84
	s_cselect_b64 s[26:27], -1, 0
	s_cmp_lg_u32 s82, s84
	s_cbranch_scc0 .LBB0_1033
	s_branch .LBB0_1034
